# speedup vs baseline: 1.0204x; 1.0072x over previous
; #define PG8_STAGE(bufoff, gbase, voff) do { _Pragma("unroll") for (int _i = 0; _i < 2; ++_i) \
;         __builtin_amdgcn_global_load_lds((const unsigned*)((const char*)(gbase) + (voff)[_i]), (PG8_LAS unsigned*)(lds + (bufoff) + ldsw + _i * 8192), 16, 0, 0); } while (0)
; #define PG8_LDA(dst, b, h) do { _Pragma("unroll") for (int m = 0; m < 4; ++m) _Pragma("unroll") for (int k = 0; k < 2; ++k) dst[m][k] = *(const PG8_LAS bf16x8*)(lds + PG8_SA(b, h) + aoff + m * 2048 + k * 1024); } while (0)
; #define PG8_LDB(dst, b, h) do { _Pragma("unroll") for (int n = 0; n < 2; ++n) _Pragma("unroll") for (int k = 0; k < 2; ++k) dst[n][k] = *(const PG8_LAS bf16x8*)(lds + PG8_SB(b, h) + boff + n * 2048 + k * 1024); } while (0)
; #define PG8_MMA(ai, bj, At, Bt) do { __builtin_amdgcn_s_setprio(3); _Pragma("unroll") for (int m = 0; m < 4; ++m) _Pragma("unroll") for (int n = 0; n < 2; ++n) _Pragma("unroll") for (int k = 0; k < 2; ++k) \
;         acc[ai][bj][m][n] = __builtin_amdgcn_mfma_f32_16x16x32_bf16(Bt[n][k], At[m][k], acc[ai][bj][m][n], 0, 0, 0); __builtin_amdgcn_s_setprio(0); } while (0)
; #define PG8_WAIT_V(n) asm volatile("s_waitcnt vmcnt(" #n ")" ::: "memory")
; #define PG8_BAR __builtin_amdgcn_s_barrier()
; template <class Epi, class Sched, bool ALIGN_EPI = false, bool SP2 = false>
; __device__ __forceinline__ void gemm_phase(PG8_LAS unsigned char* lds, const Gemm g, const Sched& S, const Epi& E) {
;     ...
;         for (int t = 0; t < nt; t += 2) {
;             const bool last = (t == nt - 2);
;             const char* a1 = cA + (size_t)(t + 1) * kstep;
;             const char* a2 = last ? nA : cA + (size_t)(t + 2) * kstep; const char* b2 = last ? nB : cB + (size_t)(t + 2) * kstep;
;             const char* a3 = a2 + kstep; const char* b3 = b2 + kstep;
;             if (last && has_next) S.a_ready(nxt);
;             if constexpr (SP2) {
;             PG8_LDB(B0, 0, 0); PG8_LDB(B1, 0, 1); PG8_SCHED; PG8_LDA(At, 0, 0); PG8_STAGE(PG8_SA(1, 1), a1 + hstep, voffA);
;             PG8_WAIT_V(8); PG8_WAIT_L(0); PG8_BAR; PG8_MMA(0, 0, At, B0); PG8_MMA(0, 1, At, B1); PG8_BAR; PG8_SCHED;
;             PG8_LDA(At, 0, 1); PG8_STAGE(PG8_SB(0, 0), b2, voffB); PG8_STAGE(PG8_SB(0, 1), b2 + hstep, voffB); PG8_STAGE(PG8_SA(0, 0), a2, voffA);
;             PG8_WAIT_V(8); PG8_WAIT_L(0); PG8_BAR; PG8_MMA(1, 0, At, B0); PG8_MMA(1, 1, At, B1); PG8_BAR; PG8_SCHED;
.LBB0_70:
	ds_read_b128 v[148:151], v153
	ds_read_b128 v[156:159], v153 offset:1024
	ds_read_b128 v[160:163], v153 offset:2048
	ds_read_b128 v[168:171], v153 offset:3072
	ds_read_b128 v[172:175], v154
	ds_read_b128 v[176:179], v154 offset:1024
	ds_read_b128 v[180:183], v154 offset:2048
	ds_read_b128 v[184:187], v154 offset:3072
	s_add_u32 s50, s48, 0xfff80080
	s_addc_u32 s51, s49, -1
	s_cmp_eq_u32 s70, 28
	s_cselect_b32 s53, s29, s51
	s_cselect_b32 s52, s65, s50
	s_cselect_b32 s51, s27, s69
	s_cselect_b32 s50, s67, s68
	v_lshl_add_u64 v[164:165], s[48:49], 0, v[138:139]
	s_add_i32 m0, s43, 0xc000
	ds_read_b128 v[188:191], v155
	ds_read_b128 v[192:195], v155 offset:1024
	ds_read_b128 v[196:199], v155 offset:2048
	ds_read_b128 v[200:203], v155 offset:3072
	ds_read_b128 v[204:207], v155 offset:4096
	ds_read_b128 v[208:211], v155 offset:5120
	ds_read_b128 v[212:215], v155 offset:6144
	ds_read_b128 v[216:219], v155 offset:7168
	global_load_lds_dwordx4 v[164:165], off
	v_lshl_add_u64 v[164:165], s[48:49], 0, v[142:143]
	s_add_i32 m0, s43, 0xe000
	s_nop 0
	global_load_lds_dwordx4 v[164:165], off
	s_waitcnt vmcnt(8)
	s_waitcnt lgkmcnt(0)
	s_barrier
	s_setprio 3
	s_waitcnt lgkmcnt(0)
	v_mfma_f32_16x16x32_bf16 v[126:129], v[148:151], v[188:191], v[126:129]
	v_mfma_f32_16x16x32_bf16 v[118:121], v[160:163], v[188:191], v[118:121]
	v_mfma_f32_16x16x32_bf16 v[110:113], v[148:151], v[196:199], v[110:113]
	v_mfma_f32_16x16x32_bf16 v[102:105], v[160:163], v[196:199], v[102:105]
	v_mfma_f32_16x16x32_bf16 v[94:97], v[148:151], v[204:207], v[94:97]
	v_mfma_f32_16x16x32_bf16 v[86:89], v[160:163], v[204:207], v[86:89]
	v_mfma_f32_16x16x32_bf16 v[78:81], v[148:151], v[212:215], v[78:81]
	v_mfma_f32_16x16x32_bf16 v[70:73], v[160:163], v[212:215], v[70:73]
	v_mfma_f32_16x16x32_bf16 v[126:129], v[156:159], v[192:195], v[126:129]
	v_mfma_f32_16x16x32_bf16 v[118:121], v[168:171], v[192:195], v[118:121]
	v_mfma_f32_16x16x32_bf16 v[110:113], v[156:159], v[200:203], v[110:113]
	v_mfma_f32_16x16x32_bf16 v[102:105], v[168:171], v[200:203], v[102:105]
	v_mfma_f32_16x16x32_bf16 v[94:97], v[156:159], v[208:211], v[94:97]
	v_mfma_f32_16x16x32_bf16 v[86:89], v[168:171], v[208:211], v[86:89]
	v_mfma_f32_16x16x32_bf16 v[78:81], v[156:159], v[216:219], v[78:81]
	v_mfma_f32_16x16x32_bf16 v[70:73], v[168:171], v[216:219], v[70:73]
	s_setprio 0
	s_setprio 3
	v_mfma_f32_16x16x32_bf16 v[122:125], v[172:175], v[188:191], v[122:125]
	v_mfma_f32_16x16x32_bf16 v[114:117], v[180:183], v[188:191], v[114:117]
	v_mfma_f32_16x16x32_bf16 v[106:109], v[172:175], v[196:199], v[106:109]
	v_mfma_f32_16x16x32_bf16 v[98:101], v[180:183], v[196:199], v[98:101]
	v_mfma_f32_16x16x32_bf16 v[90:93], v[172:175], v[204:207], v[90:93]
	v_mfma_f32_16x16x32_bf16 v[82:85], v[180:183], v[204:207], v[82:85]
	v_mfma_f32_16x16x32_bf16 v[74:77], v[172:175], v[212:215], v[74:77]
	v_mfma_f32_16x16x32_bf16 v[66:69], v[180:183], v[212:215], v[66:69]
	v_mfma_f32_16x16x32_bf16 v[122:125], v[176:179], v[192:195], v[122:125]
	v_mfma_f32_16x16x32_bf16 v[114:117], v[184:187], v[192:195], v[114:117]
	v_mfma_f32_16x16x32_bf16 v[106:109], v[176:179], v[200:203], v[106:109]
	v_mfma_f32_16x16x32_bf16 v[98:101], v[184:187], v[200:203], v[98:101]
	v_mfma_f32_16x16x32_bf16 v[90:93], v[176:179], v[208:211], v[90:93]
	v_mfma_f32_16x16x32_bf16 v[82:85], v[184:187], v[208:211], v[82:85]
	v_mfma_f32_16x16x32_bf16 v[74:77], v[176:179], v[216:219], v[74:77]
	s_setprio 0
	s_barrier
	v_mfma_f32_16x16x32_bf16 v[66:69], v[184:187], v[216:219], v[66:69]
	s_add_i32 s71, s61, s37
	v_lshl_add_u64 v[164:165], s[50:51], 0, v[132:133]
	s_mov_b32 m0, s71
	ds_read_b128 v[188:191], v155 offset:16384
	ds_read_b128 v[192:195], v155 offset:17408
	ds_read_b128 v[196:199], v155 offset:18432
	ds_read_b128 v[200:203], v155 offset:19456
	ds_read_b128 v[204:207], v155 offset:20480
	ds_read_b128 v[208:211], v155 offset:21504
	ds_read_b128 v[212:215], v155 offset:22528
	ds_read_b128 v[216:219], v155 offset:23552
	global_load_lds_dwordx4 v[164:165], off
	s_add_i32 m0, s71, 0x2000
	s_add_u32 s72, s50, 0x80000
	v_lshl_add_u64 v[220:221], s[50:51], 0, v[136:137]
	s_addc_u32 s73, s51, 0
	s_add_i32 s71, s62, s37
	global_load_lds_dwordx4 v[220:221], off
	v_lshl_add_u64 v[222:223], s[72:73], 0, v[132:133]
	s_mov_b32 m0, s71
	v_lshl_add_u64 v[224:225], s[52:53], 0, v[134:135]
	global_load_lds_dwordx4 v[222:223], off
	v_lshl_add_u64 v[222:223], s[72:73], 0, v[136:137]
	s_add_i32 m0, s71, 0x2000
	s_nop 0
	global_load_lds_dwordx4 v[222:223], off
	v_lshl_add_u64 v[222:223], s[52:53], 0, v[130:131]
	s_mov_b32 m0, s43
	s_nop 0
	global_load_lds_dwordx4 v[222:223], off
	s_mov_b32 m0, s47
	s_nop 0
	global_load_lds_dwordx4 v[224:225], off
	s_waitcnt vmcnt(8)
	s_waitcnt lgkmcnt(0)
	s_barrier
; #define PG8_STAGE(bufoff, gbase, voff) do { _Pragma("unroll") for (int _i = 0; _i < 2; ++_i) \
;         __builtin_amdgcn_global_load_lds((const unsigned*)((const char*)(gbase) + (voff)[_i]), (PG8_LAS unsigned*)(lds + (bufoff) + ldsw + _i * 8192), 16, 0, 0); } while (0)
; #define PG8_LDA(dst, b, h) do { _Pragma("unroll") for (int m = 0; m < 4; ++m) _Pragma("unroll") for (int k = 0; k < 2; ++k) dst[m][k] = *(const PG8_LAS bf16x8*)(lds + PG8_SA(b, h) + aoff + m * 2048 + k * 1024); } while (0)
; #define PG8_LDB(dst, b, h) do { _Pragma("unroll") for (int n = 0; n < 2; ++n) _Pragma("unroll") for (int k = 0; k < 2; ++k) dst[n][k] = *(const PG8_LAS bf16x8*)(lds + PG8_SB(b, h) + boff + n * 2048 + k * 1024); } while (0)
; #define PG8_MMA(ai, bj, At, Bt) do { __builtin_amdgcn_s_setprio(3); _Pragma("unroll") for (int m = 0; m < 4; ++m) _Pragma("unroll") for (int n = 0; n < 2; ++n) _Pragma("unroll") for (int k = 0; k < 2; ++k) \
;         acc[ai][bj][m][n] = __builtin_amdgcn_mfma_f32_16x16x32_bf16(Bt[n][k], At[m][k], acc[ai][bj][m][n], 0, 0, 0); __builtin_amdgcn_s_setprio(0); } while (0)
; #define PG8_WAIT_V(n) asm volatile("s_waitcnt vmcnt(" #n ")" ::: "memory")
; #define PG8_WAIT_L(n) asm volatile("s_waitcnt lgkmcnt(" #n ")" ::: "memory")
; #define PG8_BAR __builtin_amdgcn_s_barrier()
; #define PG8_SCHED __builtin_amdgcn_sched_barrier(0)
; template <class Epi, class Sched, bool ALIGN_EPI = false, bool SP2 = false>
; __device__ __forceinline__ void gemm_phase(PG8_LAS unsigned char* lds, const Gemm g, const Sched& S, const Epi& E) {
;     ...
;             PG8_WAIT_V(8); PG8_WAIT_L(0); PG8_BAR; PG8_MMA(1, 0, At, B0); PG8_MMA(1, 1, At, B1); PG8_BAR; PG8_SCHED;
;             PG8_LDB(B0, 1, 0); PG8_LDB(B1, 1, 1); PG8_SCHED; PG8_LDA(At, 1, 0); PG8_STAGE(PG8_SA(0, 1), a2 + hstep, voffA);
;             PG8_WAIT_V(8); PG8_WAIT_L(0); PG8_BAR; PG8_MMA(0, 0, At, B0); PG8_MMA(0, 1, At, B1); PG8_BAR; PG8_SCHED;
	s_setprio 3
	s_waitcnt lgkmcnt(0)
	v_mfma_f32_16x16x32_bf16 v[62:65], v[148:151], v[188:191], v[62:65]
	v_mfma_f32_16x16x32_bf16 v[54:57], v[160:163], v[188:191], v[54:57]
	v_mfma_f32_16x16x32_bf16 v[46:49], v[148:151], v[196:199], v[46:49]
	v_mfma_f32_16x16x32_bf16 v[38:41], v[160:163], v[196:199], v[38:41]
	v_mfma_f32_16x16x32_bf16 v[30:33], v[148:151], v[204:207], v[30:33]
	v_mfma_f32_16x16x32_bf16 v[22:25], v[160:163], v[204:207], v[22:25]
	v_mfma_f32_16x16x32_bf16 v[14:17], v[148:151], v[212:215], v[14:17]
	v_mfma_f32_16x16x32_bf16 v[6:9], v[160:163], v[212:215], v[6:9]
	v_mfma_f32_16x16x32_bf16 v[62:65], v[156:159], v[192:195], v[62:65]
	v_mfma_f32_16x16x32_bf16 v[54:57], v[168:171], v[192:195], v[54:57]
	v_mfma_f32_16x16x32_bf16 v[46:49], v[156:159], v[200:203], v[46:49]
	v_mfma_f32_16x16x32_bf16 v[38:41], v[168:171], v[200:203], v[38:41]
	v_mfma_f32_16x16x32_bf16 v[30:33], v[156:159], v[208:211], v[30:33]
	v_mfma_f32_16x16x32_bf16 v[22:25], v[168:171], v[208:211], v[22:25]
	v_mfma_f32_16x16x32_bf16 v[14:17], v[156:159], v[216:219], v[14:17]
	v_mfma_f32_16x16x32_bf16 v[6:9], v[168:171], v[216:219], v[6:9]
	s_setprio 0
	s_setprio 3
	v_mfma_f32_16x16x32_bf16 v[58:61], v[172:175], v[188:191], v[58:61]
	v_mfma_f32_16x16x32_bf16 v[50:53], v[180:183], v[188:191], v[50:53]
	v_mfma_f32_16x16x32_bf16 v[42:45], v[172:175], v[196:199], v[42:45]
	v_mfma_f32_16x16x32_bf16 v[34:37], v[180:183], v[196:199], v[34:37]
	v_mfma_f32_16x16x32_bf16 v[26:29], v[172:175], v[204:207], v[26:29]
	v_mfma_f32_16x16x32_bf16 v[18:21], v[180:183], v[204:207], v[18:21]
	v_mfma_f32_16x16x32_bf16 v[10:13], v[172:175], v[212:215], v[10:13]
	v_mfma_f32_16x16x32_bf16 v[2:5], v[180:183], v[212:215], v[2:5]
	v_mfma_f32_16x16x32_bf16 v[58:61], v[176:179], v[192:195], v[58:61]
	v_mfma_f32_16x16x32_bf16 v[50:53], v[184:187], v[192:195], v[50:53]
	v_mfma_f32_16x16x32_bf16 v[42:45], v[176:179], v[200:203], v[42:45]
	v_mfma_f32_16x16x32_bf16 v[34:37], v[184:187], v[200:203], v[34:37]
	v_mfma_f32_16x16x32_bf16 v[26:29], v[176:179], v[208:211], v[26:29]
	v_mfma_f32_16x16x32_bf16 v[18:21], v[184:187], v[208:211], v[18:21]
	v_mfma_f32_16x16x32_bf16 v[10:13], v[176:179], v[216:219], v[10:13]
	s_setprio 0
	s_barrier
	v_mfma_f32_16x16x32_bf16 v[2:5], v[184:187], v[216:219], v[2:5]
	s_add_i32 s71, 0, 0x18000
	v_add_u32_e32 v167, s71, v141
	s_add_i32 s72, 0, 0x1c000
	ds_read_b128 v[148:151], v167
	ds_read_b128 v[156:159], v167 offset:1024
	ds_read_b128 v[160:163], v167 offset:2048
	ds_read_b128 v[168:171], v167 offset:3072
	v_add_u32_e32 v167, s72, v141
	ds_read_b128 v[172:175], v167
	ds_read_b128 v[176:179], v167 offset:1024
	ds_read_b128 v[180:183], v167 offset:2048
	ds_read_b128 v[184:187], v167 offset:3072
	s_add_u32 s52, s52, 0x80000
	s_addc_u32 s53, s53, 0
	s_mov_b32 m0, s54
	v_lshl_add_u64 v[226:227], s[52:53], 0, v[130:131]
	ds_read_b128 v[188:191], v155 offset:32768
	ds_read_b128 v[192:195], v155 offset:33792
	ds_read_b128 v[196:199], v155 offset:34816
	ds_read_b128 v[200:203], v155 offset:35840
	ds_read_b128 v[204:207], v155 offset:36864
	ds_read_b128 v[208:211], v155 offset:37888
	ds_read_b128 v[212:215], v155 offset:38912
	ds_read_b128 v[216:219], v155 offset:39936
	global_load_lds_dwordx4 v[226:227], off
	v_lshl_add_u64 v[226:227], s[52:53], 0, v[134:135]
	s_mov_b32 m0, s55
	s_nop 0
	global_load_lds_dwordx4 v[226:227], off
	s_waitcnt vmcnt(8)
	s_waitcnt lgkmcnt(0)
	s_barrier
	s_setprio 3
	s_waitcnt lgkmcnt(0)
	v_mfma_f32_16x16x32_bf16 v[126:129], v[148:151], v[188:191], v[126:129]
	v_mfma_f32_16x16x32_bf16 v[118:121], v[160:163], v[188:191], v[118:121]
	v_mfma_f32_16x16x32_bf16 v[110:113], v[148:151], v[196:199], v[110:113]
	v_mfma_f32_16x16x32_bf16 v[102:105], v[160:163], v[196:199], v[102:105]
	v_mfma_f32_16x16x32_bf16 v[94:97], v[148:151], v[204:207], v[94:97]
	v_mfma_f32_16x16x32_bf16 v[86:89], v[160:163], v[204:207], v[86:89]
	v_mfma_f32_16x16x32_bf16 v[78:81], v[148:151], v[212:215], v[78:81]
	v_mfma_f32_16x16x32_bf16 v[70:73], v[160:163], v[212:215], v[70:73]
	v_mfma_f32_16x16x32_bf16 v[126:129], v[156:159], v[192:195], v[126:129]
	v_mfma_f32_16x16x32_bf16 v[118:121], v[168:171], v[192:195], v[118:121]
	v_mfma_f32_16x16x32_bf16 v[110:113], v[156:159], v[200:203], v[110:113]
	v_mfma_f32_16x16x32_bf16 v[102:105], v[168:171], v[200:203], v[102:105]
	v_mfma_f32_16x16x32_bf16 v[94:97], v[156:159], v[208:211], v[94:97]
	v_mfma_f32_16x16x32_bf16 v[86:89], v[168:171], v[208:211], v[86:89]
	v_mfma_f32_16x16x32_bf16 v[78:81], v[156:159], v[216:219], v[78:81]
	v_mfma_f32_16x16x32_bf16 v[70:73], v[168:171], v[216:219], v[70:73]
	s_setprio 0
	s_setprio 3
	v_mfma_f32_16x16x32_bf16 v[122:125], v[172:175], v[188:191], v[122:125]
	v_mfma_f32_16x16x32_bf16 v[114:117], v[180:183], v[188:191], v[114:117]
	v_mfma_f32_16x16x32_bf16 v[106:109], v[172:175], v[196:199], v[106:109]
	v_mfma_f32_16x16x32_bf16 v[98:101], v[180:183], v[196:199], v[98:101]
	v_mfma_f32_16x16x32_bf16 v[90:93], v[172:175], v[204:207], v[90:93]
	v_mfma_f32_16x16x32_bf16 v[82:85], v[180:183], v[204:207], v[82:85]
	v_mfma_f32_16x16x32_bf16 v[74:77], v[172:175], v[212:215], v[74:77]
	v_mfma_f32_16x16x32_bf16 v[66:69], v[180:183], v[212:215], v[66:69]
	v_mfma_f32_16x16x32_bf16 v[122:125], v[176:179], v[192:195], v[122:125]
	v_mfma_f32_16x16x32_bf16 v[114:117], v[184:187], v[192:195], v[114:117]
	v_mfma_f32_16x16x32_bf16 v[106:109], v[176:179], v[200:203], v[106:109]
	v_mfma_f32_16x16x32_bf16 v[98:101], v[184:187], v[200:203], v[98:101]
	v_mfma_f32_16x16x32_bf16 v[90:93], v[176:179], v[208:211], v[90:93]
	v_mfma_f32_16x16x32_bf16 v[82:85], v[184:187], v[208:211], v[82:85]
	v_mfma_f32_16x16x32_bf16 v[74:77], v[176:179], v[216:219], v[74:77]
	s_setprio 0
	s_barrier
; #define PG8_STAGE(bufoff, gbase, voff) do { _Pragma("unroll") for (int _i = 0; _i < 2; ++_i) \
;         __builtin_amdgcn_global_load_lds((const unsigned*)((const char*)(gbase) + (voff)[_i]), (PG8_LAS unsigned*)(lds + (bufoff) + ldsw + _i * 8192), 16, 0, 0); } while (0)
; #define PG8_LDA(dst, b, h) do { _Pragma("unroll") for (int m = 0; m < 4; ++m) _Pragma("unroll") for (int k = 0; k < 2; ++k) dst[m][k] = *(const PG8_LAS bf16x8*)(lds + PG8_SA(b, h) + aoff + m * 2048 + k * 1024); } while (0)
; #define PG8_MMA(ai, bj, At, Bt) do { __builtin_amdgcn_s_setprio(3); _Pragma("unroll") for (int m = 0; m < 4; ++m) _Pragma("unroll") for (int n = 0; n < 2; ++n) _Pragma("unroll") for (int k = 0; k < 2; ++k) \
;         acc[ai][bj][m][n] = __builtin_amdgcn_mfma_f32_16x16x32_bf16(Bt[n][k], At[m][k], acc[ai][bj][m][n], 0, 0, 0); __builtin_amdgcn_s_setprio(0); } while (0)
; #define PG8_WAIT_V(n) asm volatile("s_waitcnt vmcnt(" #n ")" ::: "memory")
; #define PG8_WAIT_L(n) asm volatile("s_waitcnt lgkmcnt(" #n ")" ::: "memory")
; #define PG8_BAR __builtin_amdgcn_s_barrier()
; #define PG8_SCHED __builtin_amdgcn_sched_barrier(0)
; template <class Epi, class Sched, bool ALIGN_EPI = false, bool SP2 = false>
; __device__ __forceinline__ void gemm_phase(PG8_LAS unsigned char* lds, const Gemm g, const Sched& S, const Epi& E) {
;     ...
;             PG8_WAIT_V(8); PG8_WAIT_L(0); PG8_BAR; PG8_MMA(0, 0, At, B0); PG8_MMA(0, 1, At, B1); PG8_BAR; PG8_SCHED;
;             PG8_LDA(At, 1, 1); PG8_STAGE(PG8_SB(1, 0), b3, voffB); PG8_STAGE(PG8_SB(1, 1), b3 + hstep, voffB); PG8_STAGE(PG8_SA(1, 0), a3, voffA);
;             PG8_WAIT_V(8); PG8_WAIT_L(0); PG8_BAR; PG8_MMA(1, 0, At, B0); PG8_MMA(1, 1, At, B1); PG8_BAR; PG8_SCHED;
;     ...
;         if constexpr (ALIGN_EPI) { if (wr == 0) PG8_BAR; }
	v_mfma_f32_16x16x32_bf16 v[66:69], v[184:187], v[216:219], v[66:69]
	s_add_i32 s52, s71, s37
	v_lshl_add_u64 v[164:165], v[164:165], 0, s[18:19]
	s_mov_b32 m0, s52
	ds_read_b128 v[188:191], v155 offset:49152
	ds_read_b128 v[192:195], v155 offset:50176
	ds_read_b128 v[196:199], v155 offset:51200
	ds_read_b128 v[200:203], v155 offset:52224
	ds_read_b128 v[204:207], v155 offset:53248
	ds_read_b128 v[208:211], v155 offset:54272
	ds_read_b128 v[212:215], v155 offset:55296
	ds_read_b128 v[216:219], v155 offset:56320
	global_load_lds_dwordx4 v[164:165], off
	s_add_i32 m0, s52, 0x2000
	s_add_u32 s50, s50, 0x80080
	v_lshl_add_u64 v[164:165], v[220:221], 0, s[18:19]
	s_addc_u32 s51, s51, 0
	s_add_i32 s52, s72, s37
	global_load_lds_dwordx4 v[164:165], off
	v_lshl_add_u64 v[164:165], s[50:51], 0, v[132:133]
	s_mov_b32 m0, s52
	s_nop 0
	global_load_lds_dwordx4 v[164:165], off
	v_lshl_add_u64 v[164:165], s[50:51], 0, v[136:137]
	s_add_i32 m0, s52, 0x2000
	s_nop 0
	global_load_lds_dwordx4 v[164:165], off
	v_lshl_add_u64 v[164:165], v[222:223], 0, s[18:19]
	s_mov_b32 m0, s58
	s_nop 0
	global_load_lds_dwordx4 v[164:165], off
	v_lshl_add_u64 v[164:165], v[224:225], 0, s[18:19]
	s_mov_b32 m0, s59
	s_nop 0
	global_load_lds_dwordx4 v[164:165], off
	s_waitcnt vmcnt(8)
	s_waitcnt lgkmcnt(0)
	s_barrier
	s_setprio 3
	s_waitcnt lgkmcnt(0)
	v_mfma_f32_16x16x32_bf16 v[62:65], v[148:151], v[188:191], v[62:65]
	v_mfma_f32_16x16x32_bf16 v[54:57], v[160:163], v[188:191], v[54:57]
	v_mfma_f32_16x16x32_bf16 v[46:49], v[148:151], v[196:199], v[46:49]
	v_mfma_f32_16x16x32_bf16 v[38:41], v[160:163], v[196:199], v[38:41]
	v_mfma_f32_16x16x32_bf16 v[30:33], v[148:151], v[204:207], v[30:33]
	v_mfma_f32_16x16x32_bf16 v[22:25], v[160:163], v[204:207], v[22:25]
	v_mfma_f32_16x16x32_bf16 v[14:17], v[148:151], v[212:215], v[14:17]
	v_mfma_f32_16x16x32_bf16 v[6:9], v[160:163], v[212:215], v[6:9]
	v_mfma_f32_16x16x32_bf16 v[62:65], v[156:159], v[192:195], v[62:65]
	v_mfma_f32_16x16x32_bf16 v[54:57], v[168:171], v[192:195], v[54:57]
	v_mfma_f32_16x16x32_bf16 v[46:49], v[156:159], v[200:203], v[46:49]
	v_mfma_f32_16x16x32_bf16 v[38:41], v[168:171], v[200:203], v[38:41]
	v_mfma_f32_16x16x32_bf16 v[30:33], v[156:159], v[208:211], v[30:33]
	v_mfma_f32_16x16x32_bf16 v[22:25], v[168:171], v[208:211], v[22:25]
	v_mfma_f32_16x16x32_bf16 v[14:17], v[156:159], v[216:219], v[14:17]
	v_mfma_f32_16x16x32_bf16 v[6:9], v[168:171], v[216:219], v[6:9]
	s_setprio 0
	s_setprio 3
	v_mfma_f32_16x16x32_bf16 v[58:61], v[172:175], v[188:191], v[58:61]
	v_mfma_f32_16x16x32_bf16 v[50:53], v[180:183], v[188:191], v[50:53]
	v_mfma_f32_16x16x32_bf16 v[42:45], v[172:175], v[196:199], v[42:45]
	v_mfma_f32_16x16x32_bf16 v[34:37], v[180:183], v[196:199], v[34:37]
	v_mfma_f32_16x16x32_bf16 v[26:29], v[172:175], v[204:207], v[26:29]
	v_mfma_f32_16x16x32_bf16 v[18:21], v[180:183], v[204:207], v[18:21]
	v_mfma_f32_16x16x32_bf16 v[10:13], v[172:175], v[212:215], v[10:13]
	v_mfma_f32_16x16x32_bf16 v[2:5], v[180:183], v[212:215], v[2:5]
	v_mfma_f32_16x16x32_bf16 v[58:61], v[176:179], v[192:195], v[58:61]
	v_mfma_f32_16x16x32_bf16 v[50:53], v[184:187], v[192:195], v[50:53]
	v_mfma_f32_16x16x32_bf16 v[42:45], v[176:179], v[200:203], v[42:45]
	v_mfma_f32_16x16x32_bf16 v[34:37], v[184:187], v[200:203], v[34:37]
	v_mfma_f32_16x16x32_bf16 v[26:29], v[176:179], v[208:211], v[26:29]
	v_mfma_f32_16x16x32_bf16 v[18:21], v[184:187], v[208:211], v[18:21]
	v_mfma_f32_16x16x32_bf16 v[10:13], v[176:179], v[216:219], v[10:13]
	s_setprio 0
	s_barrier
	v_mfma_f32_16x16x32_bf16 v[2:5], v[184:187], v[216:219], v[2:5]
	s_add_i32 s70, s70, 2
	s_add_u32 s48, s48, 0x100
	s_addc_u32 s49, s49, 0
	s_add_u32 s68, s68, 0x100
	s_addc_u32 s69, s69, 0
	s_cmp_gt_u32 s70, 29
	s_cbranch_scc0 .LBB0_70
	s_and_b64 vcc, exec, s[24:25]
	s_cbranch_vccz .LBB0_73
	s_barrier

; #define PG8_STAGE(bufoff, gbase, voff) do { _Pragma("unroll") for (int _i = 0; _i < 2; ++_i) \
;         __builtin_amdgcn_global_load_lds((const unsigned*)((const char*)(gbase) + (voff)[_i]), (PG8_LAS unsigned*)(lds + (bufoff) + ldsw + _i * 8192), 16, 0, 0); } while (0)
; #define PG8_LDA(dst, b, h) do { _Pragma("unroll") for (int m = 0; m < 4; ++m) _Pragma("unroll") for (int k = 0; k < 2; ++k) dst[m][k] = *(const PG8_LAS bf16x8*)(lds + PG8_SA(b, h) + aoff + m * 2048 + k * 1024); } while (0)
; #define PG8_LDB(dst, b, h) do { _Pragma("unroll") for (int n = 0; n < 2; ++n) _Pragma("unroll") for (int k = 0; k < 2; ++k) dst[n][k] = *(const PG8_LAS bf16x8*)(lds + PG8_SB(b, h) + boff + n * 2048 + k * 1024); } while (0)
; #define PG8_MMA(ai, bj, At, Bt) do { __builtin_amdgcn_s_setprio(3); _Pragma("unroll") for (int m = 0; m < 4; ++m) _Pragma("unroll") for (int n = 0; n < 2; ++n) _Pragma("unroll") for (int k = 0; k < 2; ++k) \
;         acc[ai][bj][m][n] = __builtin_amdgcn_mfma_f32_16x16x32_bf16(Bt[n][k], At[m][k], acc[ai][bj][m][n], 0, 0, 0); __builtin_amdgcn_s_setprio(0); } while (0)
; #define PG8_WAIT_V(n) asm volatile("s_waitcnt vmcnt(" #n ")" ::: "memory")
; #define PG8_BAR __builtin_amdgcn_s_barrier()
; template <class Epi, class Sched, bool ALIGN_EPI = false, bool SP2 = false>
; __device__ __forceinline__ void gemm_phase(PG8_LAS unsigned char* lds, const Gemm g, const Sched& S, const Epi& E) {
;     ...
;         for (int t = 0; t < nt; t += 2) {
;             const bool last = (t == nt - 2);
;             const char* a1 = cA + (size_t)(t + 1) * kstep;
;             const char* a2 = last ? nA : cA + (size_t)(t + 2) * kstep; const char* b2 = last ? nB : cB + (size_t)(t + 2) * kstep;
;             const char* a3 = a2 + kstep; const char* b3 = b2 + kstep;
;             if (last && has_next) S.a_ready(nxt);
;             if constexpr (SP2) {
;             PG8_LDB(B0, 0, 0); PG8_LDB(B1, 0, 1); PG8_SCHED; PG8_LDA(At, 0, 0); PG8_STAGE(PG8_SA(1, 1), a1 + hstep, voffA);
;             PG8_WAIT_V(8); PG8_WAIT_L(0); PG8_BAR; PG8_MMA(0, 0, At, B0); PG8_MMA(0, 1, At, B1); PG8_BAR; PG8_SCHED;
;             PG8_LDA(At, 0, 1); PG8_STAGE(PG8_SB(0, 0), b2, voffB); PG8_STAGE(PG8_SB(0, 1), b2 + hstep, voffB); PG8_STAGE(PG8_SA(0, 0), a2, voffA);
;             PG8_WAIT_V(8); PG8_WAIT_L(0); PG8_BAR; PG8_MMA(1, 0, At, B0); PG8_MMA(1, 1, At, B1); PG8_BAR; PG8_SCHED;
.LBB0_179:
	ds_read_b128 v[148:151], v157
	ds_read_b128 v[152:155], v157 offset:1024
	ds_read_b128 v[160:163], v157 offset:2048
	ds_read_b128 v[168:171], v157 offset:3072
	ds_read_b128 v[172:175], v158
	ds_read_b128 v[176:179], v158 offset:1024
	ds_read_b128 v[180:183], v158 offset:2048
	ds_read_b128 v[184:187], v158 offset:3072
	s_add_i32 s79, s50, 2
	s_add_u32 s51, s8, 0xffea8080
	s_addc_u32 s52, s9, -1
	s_cmp_eq_u32 s76, s50
	s_cselect_b32 s50, s48, s77
	s_cselect_b32 s53, s47, s52
	s_cselect_b32 s52, s46, s51
	s_cselect_b32 s51, s49, s78
	v_lshl_add_u64 v[164:165], s[8:9], 0, v[138:139]
	s_add_i32 m0, s54, 0xc000
	ds_read_b128 v[188:191], v159
	ds_read_b128 v[192:195], v159 offset:1024
	ds_read_b128 v[196:199], v159 offset:2048
	ds_read_b128 v[200:203], v159 offset:3072
	ds_read_b128 v[204:207], v159 offset:4096
	ds_read_b128 v[208:211], v159 offset:5120
	ds_read_b128 v[212:215], v159 offset:6144
	ds_read_b128 v[216:219], v159 offset:7168
	global_load_lds_dwordx4 v[164:165], off
	v_lshl_add_u64 v[164:165], s[8:9], 0, v[142:143]
	s_add_i32 m0, s54, 0xe000
	s_nop 0
	global_load_lds_dwordx4 v[164:165], off
	s_waitcnt vmcnt(8)
	s_waitcnt lgkmcnt(0)
	s_barrier
	s_setprio 3
	s_waitcnt lgkmcnt(0)
	v_mfma_f32_16x16x32_bf16 v[126:129], v[148:151], v[188:191], v[126:129]
	v_mfma_f32_16x16x32_bf16 v[122:125], v[160:163], v[188:191], v[122:125]
	v_mfma_f32_16x16x32_bf16 v[114:117], v[148:151], v[196:199], v[114:117]
	v_mfma_f32_16x16x32_bf16 v[106:109], v[160:163], v[196:199], v[106:109]
	v_mfma_f32_16x16x32_bf16 v[98:101], v[148:151], v[204:207], v[98:101]
	v_mfma_f32_16x16x32_bf16 v[90:93], v[160:163], v[204:207], v[90:93]
	v_mfma_f32_16x16x32_bf16 v[82:85], v[148:151], v[212:215], v[82:85]
	v_mfma_f32_16x16x32_bf16 v[74:77], v[160:163], v[212:215], v[74:77]
	v_mfma_f32_16x16x32_bf16 v[126:129], v[152:155], v[192:195], v[126:129]
	v_mfma_f32_16x16x32_bf16 v[122:125], v[168:171], v[192:195], v[122:125]
	v_mfma_f32_16x16x32_bf16 v[114:117], v[152:155], v[200:203], v[114:117]
	v_mfma_f32_16x16x32_bf16 v[106:109], v[168:171], v[200:203], v[106:109]
	v_mfma_f32_16x16x32_bf16 v[98:101], v[152:155], v[208:211], v[98:101]
	v_mfma_f32_16x16x32_bf16 v[90:93], v[168:171], v[208:211], v[90:93]
	v_mfma_f32_16x16x32_bf16 v[82:85], v[152:155], v[216:219], v[82:85]
	v_mfma_f32_16x16x32_bf16 v[74:77], v[168:171], v[216:219], v[74:77]
	s_setprio 0
	s_setprio 3
	v_mfma_f32_16x16x32_bf16 v[118:121], v[172:175], v[188:191], v[118:121]
	v_mfma_f32_16x16x32_bf16 v[110:113], v[180:183], v[188:191], v[110:113]
	v_mfma_f32_16x16x32_bf16 v[102:105], v[172:175], v[196:199], v[102:105]
	v_mfma_f32_16x16x32_bf16 v[94:97], v[180:183], v[196:199], v[94:97]
	v_mfma_f32_16x16x32_bf16 v[86:89], v[172:175], v[204:207], v[86:89]
	v_mfma_f32_16x16x32_bf16 v[78:81], v[180:183], v[204:207], v[78:81]
	v_mfma_f32_16x16x32_bf16 v[70:73], v[172:175], v[212:215], v[70:73]
	v_mfma_f32_16x16x32_bf16 v[66:69], v[180:183], v[212:215], v[66:69]
	v_mfma_f32_16x16x32_bf16 v[118:121], v[176:179], v[192:195], v[118:121]
	v_mfma_f32_16x16x32_bf16 v[110:113], v[184:187], v[192:195], v[110:113]
	v_mfma_f32_16x16x32_bf16 v[102:105], v[176:179], v[200:203], v[102:105]
	v_mfma_f32_16x16x32_bf16 v[94:97], v[184:187], v[200:203], v[94:97]
	v_mfma_f32_16x16x32_bf16 v[86:89], v[176:179], v[208:211], v[86:89]
	v_mfma_f32_16x16x32_bf16 v[78:81], v[184:187], v[208:211], v[78:81]
	v_mfma_f32_16x16x32_bf16 v[70:73], v[176:179], v[216:219], v[70:73]
	s_setprio 0
	s_barrier
	v_mfma_f32_16x16x32_bf16 v[66:69], v[184:187], v[216:219], v[66:69]
	s_add_i32 s81, s65, s43
	v_lshl_add_u64 v[164:165], s[50:51], 0, v[132:133]
	s_mov_b32 m0, s81
	ds_read_b128 v[188:191], v159 offset:16384
	ds_read_b128 v[192:195], v159 offset:17408
	ds_read_b128 v[196:199], v159 offset:18432
	ds_read_b128 v[200:203], v159 offset:19456
	ds_read_b128 v[204:207], v159 offset:20480
	ds_read_b128 v[208:211], v159 offset:21504
	ds_read_b128 v[212:215], v159 offset:22528
	ds_read_b128 v[216:219], v159 offset:23552
	global_load_lds_dwordx4 v[164:165], off
	s_add_i32 m0, s81, 0x2000
	s_add_u32 s82, s50, 0x158000
	v_lshl_add_u64 v[220:221], s[50:51], 0, v[136:137]
	s_addc_u32 s83, s51, 0
	s_add_i32 s81, s67, s43
	global_load_lds_dwordx4 v[220:221], off
	v_lshl_add_u64 v[222:223], s[82:83], 0, v[132:133]
	s_mov_b32 m0, s81
	v_lshl_add_u64 v[224:225], s[52:53], 0, v[134:135]
	global_load_lds_dwordx4 v[222:223], off
	v_lshl_add_u64 v[222:223], s[82:83], 0, v[136:137]
	s_add_i32 m0, s81, 0x2000
	s_nop 0
	global_load_lds_dwordx4 v[222:223], off
	v_lshl_add_u64 v[222:223], s[52:53], 0, v[130:131]
	s_mov_b32 m0, s54
	s_nop 0
	global_load_lds_dwordx4 v[222:223], off
	s_mov_b32 m0, s55
	s_nop 0
	global_load_lds_dwordx4 v[224:225], off
	s_waitcnt vmcnt(8)
	s_waitcnt lgkmcnt(0)
	s_barrier
; #define PG8_STAGE(bufoff, gbase, voff) do { _Pragma("unroll") for (int _i = 0; _i < 2; ++_i) \
;         __builtin_amdgcn_global_load_lds((const unsigned*)((const char*)(gbase) + (voff)[_i]), (PG8_LAS unsigned*)(lds + (bufoff) + ldsw + _i * 8192), 16, 0, 0); } while (0)
; #define PG8_LDA(dst, b, h) do { _Pragma("unroll") for (int m = 0; m < 4; ++m) _Pragma("unroll") for (int k = 0; k < 2; ++k) dst[m][k] = *(const PG8_LAS bf16x8*)(lds + PG8_SA(b, h) + aoff + m * 2048 + k * 1024); } while (0)
; #define PG8_LDB(dst, b, h) do { _Pragma("unroll") for (int n = 0; n < 2; ++n) _Pragma("unroll") for (int k = 0; k < 2; ++k) dst[n][k] = *(const PG8_LAS bf16x8*)(lds + PG8_SB(b, h) + boff + n * 2048 + k * 1024); } while (0)
; #define PG8_MMA(ai, bj, At, Bt) do { __builtin_amdgcn_s_setprio(3); _Pragma("unroll") for (int m = 0; m < 4; ++m) _Pragma("unroll") for (int n = 0; n < 2; ++n) _Pragma("unroll") for (int k = 0; k < 2; ++k) \
;         acc[ai][bj][m][n] = __builtin_amdgcn_mfma_f32_16x16x32_bf16(Bt[n][k], At[m][k], acc[ai][bj][m][n], 0, 0, 0); __builtin_amdgcn_s_setprio(0); } while (0)
; #define PG8_WAIT_V(n) asm volatile("s_waitcnt vmcnt(" #n ")" ::: "memory")
; #define PG8_WAIT_L(n) asm volatile("s_waitcnt lgkmcnt(" #n ")" ::: "memory")
; #define PG8_BAR __builtin_amdgcn_s_barrier()
; #define PG8_SCHED __builtin_amdgcn_sched_barrier(0)
; template <class Epi, class Sched, bool ALIGN_EPI = false, bool SP2 = false>
; __device__ __forceinline__ void gemm_phase(PG8_LAS unsigned char* lds, const Gemm g, const Sched& S, const Epi& E) {
;     ...
;             PG8_WAIT_V(8); PG8_WAIT_L(0); PG8_BAR; PG8_MMA(1, 0, At, B0); PG8_MMA(1, 1, At, B1); PG8_BAR; PG8_SCHED;
;             PG8_LDB(B0, 1, 0); PG8_LDB(B1, 1, 1); PG8_SCHED; PG8_LDA(At, 1, 0); PG8_STAGE(PG8_SA(0, 1), a2 + hstep, voffA);
;             PG8_WAIT_V(8); PG8_WAIT_L(0); PG8_BAR; PG8_MMA(0, 0, At, B0); PG8_MMA(0, 1, At, B1); PG8_BAR; PG8_SCHED;
	s_setprio 3
	s_waitcnt lgkmcnt(0)
	v_mfma_f32_16x16x32_bf16 v[62:65], v[148:151], v[188:191], v[62:65]
	v_mfma_f32_16x16x32_bf16 v[58:61], v[160:163], v[188:191], v[58:61]
	v_mfma_f32_16x16x32_bf16 v[50:53], v[148:151], v[196:199], v[50:53]
	v_mfma_f32_16x16x32_bf16 v[42:45], v[160:163], v[196:199], v[42:45]
	v_mfma_f32_16x16x32_bf16 v[34:37], v[148:151], v[204:207], v[34:37]
	v_mfma_f32_16x16x32_bf16 v[26:29], v[160:163], v[204:207], v[26:29]
	v_mfma_f32_16x16x32_bf16 v[18:21], v[148:151], v[212:215], v[18:21]
	v_mfma_f32_16x16x32_bf16 v[10:13], v[160:163], v[212:215], v[10:13]
	v_mfma_f32_16x16x32_bf16 v[62:65], v[152:155], v[192:195], v[62:65]
	v_mfma_f32_16x16x32_bf16 v[58:61], v[168:171], v[192:195], v[58:61]
	v_mfma_f32_16x16x32_bf16 v[50:53], v[152:155], v[200:203], v[50:53]
	v_mfma_f32_16x16x32_bf16 v[42:45], v[168:171], v[200:203], v[42:45]
	v_mfma_f32_16x16x32_bf16 v[34:37], v[152:155], v[208:211], v[34:37]
	v_mfma_f32_16x16x32_bf16 v[26:29], v[168:171], v[208:211], v[26:29]
	v_mfma_f32_16x16x32_bf16 v[18:21], v[152:155], v[216:219], v[18:21]
	v_mfma_f32_16x16x32_bf16 v[10:13], v[168:171], v[216:219], v[10:13]
	s_setprio 0
	s_setprio 3
	v_mfma_f32_16x16x32_bf16 v[54:57], v[172:175], v[188:191], v[54:57]
	v_mfma_f32_16x16x32_bf16 v[46:49], v[180:183], v[188:191], v[46:49]
	v_mfma_f32_16x16x32_bf16 v[38:41], v[172:175], v[196:199], v[38:41]
	v_mfma_f32_16x16x32_bf16 v[30:33], v[180:183], v[196:199], v[30:33]
	v_mfma_f32_16x16x32_bf16 v[22:25], v[172:175], v[204:207], v[22:25]
	v_mfma_f32_16x16x32_bf16 v[14:17], v[180:183], v[204:207], v[14:17]
	v_mfma_f32_16x16x32_bf16 v[6:9], v[172:175], v[212:215], v[6:9]
	v_mfma_f32_16x16x32_bf16 v[2:5], v[180:183], v[212:215], v[2:5]
	v_mfma_f32_16x16x32_bf16 v[54:57], v[176:179], v[192:195], v[54:57]
	v_mfma_f32_16x16x32_bf16 v[46:49], v[184:187], v[192:195], v[46:49]
	v_mfma_f32_16x16x32_bf16 v[38:41], v[176:179], v[200:203], v[38:41]
	v_mfma_f32_16x16x32_bf16 v[30:33], v[184:187], v[200:203], v[30:33]
	v_mfma_f32_16x16x32_bf16 v[22:25], v[176:179], v[208:211], v[22:25]
	v_mfma_f32_16x16x32_bf16 v[14:17], v[184:187], v[208:211], v[14:17]
	v_mfma_f32_16x16x32_bf16 v[6:9], v[176:179], v[216:219], v[6:9]
	s_setprio 0
	s_barrier
	v_mfma_f32_16x16x32_bf16 v[2:5], v[184:187], v[216:219], v[2:5]
	s_add_i32 s81, 0, 0x18000
	v_add_u32_e32 v167, s81, v141
	s_add_i32 s82, 0, 0x1c000
	ds_read_b128 v[148:151], v167
	ds_read_b128 v[152:155], v167 offset:1024
	ds_read_b128 v[160:163], v167 offset:2048
	ds_read_b128 v[168:171], v167 offset:3072
	v_add_u32_e32 v167, s82, v141
	ds_read_b128 v[172:175], v167
	ds_read_b128 v[176:179], v167 offset:1024
	ds_read_b128 v[180:183], v167 offset:2048
	ds_read_b128 v[184:187], v167 offset:3072
	s_add_u32 s52, s52, 0x158000
	s_addc_u32 s53, s53, 0
	s_mov_b32 m0, s56
	v_lshl_add_u64 v[226:227], s[52:53], 0, v[130:131]
	ds_read_b128 v[188:191], v159 offset:32768
	ds_read_b128 v[192:195], v159 offset:33792
	ds_read_b128 v[196:199], v159 offset:34816
	ds_read_b128 v[200:203], v159 offset:35840
	ds_read_b128 v[204:207], v159 offset:36864
	ds_read_b128 v[208:211], v159 offset:37888
	ds_read_b128 v[212:215], v159 offset:38912
	ds_read_b128 v[216:219], v159 offset:39936
	global_load_lds_dwordx4 v[226:227], off
	v_lshl_add_u64 v[226:227], s[52:53], 0, v[134:135]
	s_mov_b32 m0, s57
	s_nop 0
	global_load_lds_dwordx4 v[226:227], off
	s_waitcnt vmcnt(8)
	s_waitcnt lgkmcnt(0)
	s_barrier
	s_setprio 3
	s_waitcnt lgkmcnt(0)
	v_mfma_f32_16x16x32_bf16 v[126:129], v[148:151], v[188:191], v[126:129]
	v_mfma_f32_16x16x32_bf16 v[122:125], v[160:163], v[188:191], v[122:125]
	v_mfma_f32_16x16x32_bf16 v[114:117], v[148:151], v[196:199], v[114:117]
	v_mfma_f32_16x16x32_bf16 v[106:109], v[160:163], v[196:199], v[106:109]
	v_mfma_f32_16x16x32_bf16 v[98:101], v[148:151], v[204:207], v[98:101]
	v_mfma_f32_16x16x32_bf16 v[90:93], v[160:163], v[204:207], v[90:93]
	v_mfma_f32_16x16x32_bf16 v[82:85], v[148:151], v[212:215], v[82:85]
	v_mfma_f32_16x16x32_bf16 v[74:77], v[160:163], v[212:215], v[74:77]
	v_mfma_f32_16x16x32_bf16 v[126:129], v[152:155], v[192:195], v[126:129]
	v_mfma_f32_16x16x32_bf16 v[122:125], v[168:171], v[192:195], v[122:125]
	v_mfma_f32_16x16x32_bf16 v[114:117], v[152:155], v[200:203], v[114:117]
	v_mfma_f32_16x16x32_bf16 v[106:109], v[168:171], v[200:203], v[106:109]
	v_mfma_f32_16x16x32_bf16 v[98:101], v[152:155], v[208:211], v[98:101]
	v_mfma_f32_16x16x32_bf16 v[90:93], v[168:171], v[208:211], v[90:93]
	v_mfma_f32_16x16x32_bf16 v[82:85], v[152:155], v[216:219], v[82:85]
	v_mfma_f32_16x16x32_bf16 v[74:77], v[168:171], v[216:219], v[74:77]
	s_setprio 0
	s_setprio 3
	v_mfma_f32_16x16x32_bf16 v[118:121], v[172:175], v[188:191], v[118:121]
	v_mfma_f32_16x16x32_bf16 v[110:113], v[180:183], v[188:191], v[110:113]
	v_mfma_f32_16x16x32_bf16 v[102:105], v[172:175], v[196:199], v[102:105]
	v_mfma_f32_16x16x32_bf16 v[94:97], v[180:183], v[196:199], v[94:97]
	v_mfma_f32_16x16x32_bf16 v[86:89], v[172:175], v[204:207], v[86:89]
	v_mfma_f32_16x16x32_bf16 v[78:81], v[180:183], v[204:207], v[78:81]
	v_mfma_f32_16x16x32_bf16 v[70:73], v[172:175], v[212:215], v[70:73]
	v_mfma_f32_16x16x32_bf16 v[66:69], v[180:183], v[212:215], v[66:69]
	v_mfma_f32_16x16x32_bf16 v[118:121], v[176:179], v[192:195], v[118:121]
	v_mfma_f32_16x16x32_bf16 v[110:113], v[184:187], v[192:195], v[110:113]
	v_mfma_f32_16x16x32_bf16 v[102:105], v[176:179], v[200:203], v[102:105]
	v_mfma_f32_16x16x32_bf16 v[94:97], v[184:187], v[200:203], v[94:97]
	v_mfma_f32_16x16x32_bf16 v[86:89], v[176:179], v[208:211], v[86:89]
	v_mfma_f32_16x16x32_bf16 v[78:81], v[184:187], v[208:211], v[78:81]
	v_mfma_f32_16x16x32_bf16 v[70:73], v[176:179], v[216:219], v[70:73]
	s_setprio 0
	s_barrier
; #define PG8_STAGE(bufoff, gbase, voff) do { _Pragma("unroll") for (int _i = 0; _i < 2; ++_i) \
;         __builtin_amdgcn_global_load_lds((const unsigned*)((const char*)(gbase) + (voff)[_i]), (PG8_LAS unsigned*)(lds + (bufoff) + ldsw + _i * 8192), 16, 0, 0); } while (0)
; #define PG8_LDA(dst, b, h) do { _Pragma("unroll") for (int m = 0; m < 4; ++m) _Pragma("unroll") for (int k = 0; k < 2; ++k) dst[m][k] = *(const PG8_LAS bf16x8*)(lds + PG8_SA(b, h) + aoff + m * 2048 + k * 1024); } while (0)
; #define PG8_MMA(ai, bj, At, Bt) do { __builtin_amdgcn_s_setprio(3); _Pragma("unroll") for (int m = 0; m < 4; ++m) _Pragma("unroll") for (int n = 0; n < 2; ++n) _Pragma("unroll") for (int k = 0; k < 2; ++k) \
;         acc[ai][bj][m][n] = __builtin_amdgcn_mfma_f32_16x16x32_bf16(Bt[n][k], At[m][k], acc[ai][bj][m][n], 0, 0, 0); __builtin_amdgcn_s_setprio(0); } while (0)
; #define PG8_WAIT_V(n) asm volatile("s_waitcnt vmcnt(" #n ")" ::: "memory")
; #define PG8_WAIT_L(n) asm volatile("s_waitcnt lgkmcnt(" #n ")" ::: "memory")
; #define PG8_BAR __builtin_amdgcn_s_barrier()
; #define PG8_SCHED __builtin_amdgcn_sched_barrier(0)
; template <class Epi, class Sched, bool ALIGN_EPI = false, bool SP2 = false>
; __device__ __forceinline__ void gemm_phase(PG8_LAS unsigned char* lds, const Gemm g, const Sched& S, const Epi& E) {
;     ...
;             PG8_WAIT_V(8); PG8_WAIT_L(0); PG8_BAR; PG8_MMA(0, 0, At, B0); PG8_MMA(0, 1, At, B1); PG8_BAR; PG8_SCHED;
;             PG8_LDA(At, 1, 1); PG8_STAGE(PG8_SB(1, 0), b3, voffB); PG8_STAGE(PG8_SB(1, 1), b3 + hstep, voffB); PG8_STAGE(PG8_SA(1, 0), a3, voffA);
;             PG8_WAIT_V(8); PG8_WAIT_L(0); PG8_BAR; PG8_MMA(1, 0, At, B0); PG8_MMA(1, 1, At, B1); PG8_BAR; PG8_SCHED;
;     ...
;         if constexpr (ALIGN_EPI) { if (wr == 0) PG8_BAR; }
	v_mfma_f32_16x16x32_bf16 v[66:69], v[184:187], v[216:219], v[66:69]
	s_add_i32 s52, s81, s43
	v_lshl_add_u64 v[164:165], v[164:165], 0, s[18:19]
	s_mov_b32 m0, s52
	ds_read_b128 v[188:191], v159 offset:49152
	ds_read_b128 v[192:195], v159 offset:50176
	ds_read_b128 v[196:199], v159 offset:51200
	ds_read_b128 v[200:203], v159 offset:52224
	ds_read_b128 v[204:207], v159 offset:53248
	ds_read_b128 v[208:211], v159 offset:54272
	ds_read_b128 v[212:215], v159 offset:55296
	ds_read_b128 v[216:219], v159 offset:56320
	global_load_lds_dwordx4 v[164:165], off
	s_add_i32 m0, s52, 0x2000
	s_add_u32 s50, s50, 0x158080
	v_lshl_add_u64 v[164:165], v[220:221], 0, s[18:19]
	s_addc_u32 s51, s51, 0
	s_add_i32 s52, s82, s43
	global_load_lds_dwordx4 v[164:165], off
	v_lshl_add_u64 v[164:165], s[50:51], 0, v[132:133]
	s_mov_b32 m0, s52
	s_nop 0
	global_load_lds_dwordx4 v[164:165], off
	v_lshl_add_u64 v[164:165], s[50:51], 0, v[136:137]
	s_add_i32 m0, s52, 0x2000
	s_nop 0
	global_load_lds_dwordx4 v[164:165], off
	v_lshl_add_u64 v[164:165], v[222:223], 0, s[18:19]
	s_mov_b32 m0, s62
	s_nop 0
	global_load_lds_dwordx4 v[164:165], off
	v_lshl_add_u64 v[164:165], v[224:225], 0, s[18:19]
	s_mov_b32 m0, s63
	s_nop 0
	global_load_lds_dwordx4 v[164:165], off
	s_waitcnt vmcnt(8)
	s_waitcnt lgkmcnt(0)
	s_barrier
	s_setprio 3
	s_waitcnt lgkmcnt(0)
	v_mfma_f32_16x16x32_bf16 v[62:65], v[148:151], v[188:191], v[62:65]
	v_mfma_f32_16x16x32_bf16 v[58:61], v[160:163], v[188:191], v[58:61]
	v_mfma_f32_16x16x32_bf16 v[50:53], v[148:151], v[196:199], v[50:53]
	v_mfma_f32_16x16x32_bf16 v[42:45], v[160:163], v[196:199], v[42:45]
	v_mfma_f32_16x16x32_bf16 v[34:37], v[148:151], v[204:207], v[34:37]
	v_mfma_f32_16x16x32_bf16 v[26:29], v[160:163], v[204:207], v[26:29]
	v_mfma_f32_16x16x32_bf16 v[18:21], v[148:151], v[212:215], v[18:21]
	v_mfma_f32_16x16x32_bf16 v[10:13], v[160:163], v[212:215], v[10:13]
	v_mfma_f32_16x16x32_bf16 v[62:65], v[152:155], v[192:195], v[62:65]
	v_mfma_f32_16x16x32_bf16 v[58:61], v[168:171], v[192:195], v[58:61]
	v_mfma_f32_16x16x32_bf16 v[50:53], v[152:155], v[200:203], v[50:53]
	v_mfma_f32_16x16x32_bf16 v[42:45], v[168:171], v[200:203], v[42:45]
	v_mfma_f32_16x16x32_bf16 v[34:37], v[152:155], v[208:211], v[34:37]
	v_mfma_f32_16x16x32_bf16 v[26:29], v[168:171], v[208:211], v[26:29]
	v_mfma_f32_16x16x32_bf16 v[18:21], v[152:155], v[216:219], v[18:21]
	v_mfma_f32_16x16x32_bf16 v[10:13], v[168:171], v[216:219], v[10:13]
	s_setprio 0
	s_setprio 3
	v_mfma_f32_16x16x32_bf16 v[54:57], v[172:175], v[188:191], v[54:57]
	v_mfma_f32_16x16x32_bf16 v[46:49], v[180:183], v[188:191], v[46:49]
	v_mfma_f32_16x16x32_bf16 v[38:41], v[172:175], v[196:199], v[38:41]
	v_mfma_f32_16x16x32_bf16 v[30:33], v[180:183], v[196:199], v[30:33]
	v_mfma_f32_16x16x32_bf16 v[22:25], v[172:175], v[204:207], v[22:25]
	v_mfma_f32_16x16x32_bf16 v[14:17], v[180:183], v[204:207], v[14:17]
	v_mfma_f32_16x16x32_bf16 v[6:9], v[172:175], v[212:215], v[6:9]
	v_mfma_f32_16x16x32_bf16 v[2:5], v[180:183], v[212:215], v[2:5]
	v_mfma_f32_16x16x32_bf16 v[54:57], v[176:179], v[192:195], v[54:57]
	v_mfma_f32_16x16x32_bf16 v[46:49], v[184:187], v[192:195], v[46:49]
	v_mfma_f32_16x16x32_bf16 v[38:41], v[176:179], v[200:203], v[38:41]
	v_mfma_f32_16x16x32_bf16 v[30:33], v[184:187], v[200:203], v[30:33]
	v_mfma_f32_16x16x32_bf16 v[22:25], v[176:179], v[208:211], v[22:25]
	v_mfma_f32_16x16x32_bf16 v[14:17], v[184:187], v[208:211], v[14:17]
	v_mfma_f32_16x16x32_bf16 v[6:9], v[176:179], v[216:219], v[6:9]
	s_setprio 0
	s_barrier
	v_mfma_f32_16x16x32_bf16 v[2:5], v[184:187], v[216:219], v[2:5]
	s_add_u32 s8, s8, 0x100
	s_addc_u32 s9, s9, 0
	s_add_u32 s77, s77, 0x100
	s_addc_u32 s78, s78, 0
	s_cmp_ge_u32 s79, s75
	s_mov_b32 s50, s79
	s_cbranch_scc0 .LBB0_179
	s_and_b64 vcc, exec, s[24:25]
	s_cbranch_vccz .LBB0_182
	s_barrier

; #define PG8_STAGE(bufoff, gbase, voff) do { _Pragma("unroll") for (int _i = 0; _i < 2; ++_i) \
;         __builtin_amdgcn_global_load_lds((const unsigned*)((const char*)(gbase) + (voff)[_i]), (PG8_LAS unsigned*)(lds + (bufoff) + ldsw + _i * 8192), 16, 0, 0); } while (0)
; #define PG8_LDA(dst, b, h) do { _Pragma("unroll") for (int m = 0; m < 4; ++m) _Pragma("unroll") for (int k = 0; k < 2; ++k) dst[m][k] = *(const PG8_LAS bf16x8*)(lds + PG8_SA(b, h) + aoff + m * 2048 + k * 1024); } while (0)
; #define PG8_LDB(dst, b, h) do { _Pragma("unroll") for (int n = 0; n < 2; ++n) _Pragma("unroll") for (int k = 0; k < 2; ++k) dst[n][k] = *(const PG8_LAS bf16x8*)(lds + PG8_SB(b, h) + boff + n * 2048 + k * 1024); } while (0)
; #define PG8_MMA(ai, bj, At, Bt) do { __builtin_amdgcn_s_setprio(3); _Pragma("unroll") for (int m = 0; m < 4; ++m) _Pragma("unroll") for (int n = 0; n < 2; ++n) _Pragma("unroll") for (int k = 0; k < 2; ++k) \
;         acc[ai][bj][m][n] = __builtin_amdgcn_mfma_f32_16x16x32_bf16(Bt[n][k], At[m][k], acc[ai][bj][m][n], 0, 0, 0); __builtin_amdgcn_s_setprio(0); } while (0)
; #define PG8_WAIT_V(n) asm volatile("s_waitcnt vmcnt(" #n ")" ::: "memory")
; #define PG8_BAR __builtin_amdgcn_s_barrier()
; template <class Epi, class Sched, bool ALIGN_EPI = false, bool SP2 = false>
; __device__ __forceinline__ void gemm_phase(PG8_LAS unsigned char* lds, const Gemm g, const Sched& S, const Epi& E) {
;     ...
;         for (int t = 0; t < nt; t += 2) {
;             const bool last = (t == nt - 2);
;             const char* a1 = cA + (size_t)(t + 1) * kstep;
;             const char* a2 = last ? nA : cA + (size_t)(t + 2) * kstep; const char* b2 = last ? nB : cB + (size_t)(t + 2) * kstep;
;             const char* a3 = a2 + kstep; const char* b3 = b2 + kstep;
;             if (last && has_next) S.a_ready(nxt);
;             if constexpr (SP2) {
;             PG8_LDB(B0, 0, 0); PG8_LDB(B1, 0, 1); PG8_SCHED; PG8_LDA(At, 0, 0); PG8_STAGE(PG8_SA(1, 1), a1 + hstep, voffA);
;             PG8_WAIT_V(8); PG8_WAIT_L(0); PG8_BAR; PG8_MMA(0, 0, At, B0); PG8_MMA(0, 1, At, B1); PG8_BAR; PG8_SCHED;
;             PG8_LDA(At, 0, 1); PG8_STAGE(PG8_SB(0, 0), b2, voffB); PG8_STAGE(PG8_SB(0, 1), b2 + hstep, voffB); PG8_STAGE(PG8_SA(0, 0), a2, voffA);
;             PG8_WAIT_V(8); PG8_WAIT_L(0); PG8_BAR; PG8_MMA(1, 0, At, B0); PG8_MMA(1, 1, At, B1); PG8_BAR; PG8_SCHED;
.LBB0_394:
	ds_read_b128 v[148:151], v155
	ds_read_b128 v[158:161], v155 offset:1024
	ds_read_b128 v[162:165], v155 offset:2048
	ds_read_b128 v[168:171], v155 offset:3072
	ds_read_b128 v[172:175], v156
	ds_read_b128 v[176:179], v156 offset:1024
	ds_read_b128 v[180:183], v156 offset:2048
	ds_read_b128 v[184:187], v156 offset:3072
	s_add_u32 s48, s46, 0xfff80080
	s_addc_u32 s49, s47, -1
	s_cmp_eq_u32 s70, 28
	s_cselect_b32 s51, s7, s49
	s_cselect_b32 s50, s27, s48
	s_cselect_b32 s49, s25, s69
	s_cselect_b32 s48, s45, s68
	v_lshl_add_u64 v[152:153], s[46:47], 0, v[138:139]
	s_add_i32 m0, s52, 0xc000
	ds_read_b128 v[188:191], v157
	ds_read_b128 v[192:195], v157 offset:1024
	ds_read_b128 v[196:199], v157 offset:2048
	ds_read_b128 v[200:203], v157 offset:3072
	ds_read_b128 v[204:207], v157 offset:4096
	ds_read_b128 v[208:211], v157 offset:5120
	ds_read_b128 v[212:215], v157 offset:6144
	ds_read_b128 v[216:219], v157 offset:7168
	global_load_lds_dwordx4 v[152:153], off
	v_lshl_add_u64 v[152:153], s[46:47], 0, v[142:143]
	s_add_i32 m0, s52, 0xe000
	s_nop 0
	global_load_lds_dwordx4 v[152:153], off
	s_waitcnt vmcnt(8)
	s_waitcnt lgkmcnt(0)
	s_barrier
	s_setprio 3
	s_waitcnt lgkmcnt(0)
	v_mfma_f32_16x16x32_bf16 v[126:129], v[148:151], v[188:191], v[126:129]
	v_mfma_f32_16x16x32_bf16 v[122:125], v[162:165], v[188:191], v[122:125]
	v_mfma_f32_16x16x32_bf16 v[114:117], v[148:151], v[196:199], v[114:117]
	v_mfma_f32_16x16x32_bf16 v[106:109], v[162:165], v[196:199], v[106:109]
	v_mfma_f32_16x16x32_bf16 v[98:101], v[148:151], v[204:207], v[98:101]
	v_mfma_f32_16x16x32_bf16 v[90:93], v[162:165], v[204:207], v[90:93]
	v_mfma_f32_16x16x32_bf16 v[82:85], v[148:151], v[212:215], v[82:85]
	v_mfma_f32_16x16x32_bf16 v[74:77], v[162:165], v[212:215], v[74:77]
	v_mfma_f32_16x16x32_bf16 v[126:129], v[158:161], v[192:195], v[126:129]
	v_mfma_f32_16x16x32_bf16 v[122:125], v[168:171], v[192:195], v[122:125]
	v_mfma_f32_16x16x32_bf16 v[114:117], v[158:161], v[200:203], v[114:117]
	v_mfma_f32_16x16x32_bf16 v[106:109], v[168:171], v[200:203], v[106:109]
	v_mfma_f32_16x16x32_bf16 v[98:101], v[158:161], v[208:211], v[98:101]
	v_mfma_f32_16x16x32_bf16 v[90:93], v[168:171], v[208:211], v[90:93]
	v_mfma_f32_16x16x32_bf16 v[82:85], v[158:161], v[216:219], v[82:85]
	v_mfma_f32_16x16x32_bf16 v[74:77], v[168:171], v[216:219], v[74:77]
	s_setprio 0
	s_setprio 3
	v_mfma_f32_16x16x32_bf16 v[118:121], v[172:175], v[188:191], v[118:121]
	v_mfma_f32_16x16x32_bf16 v[110:113], v[180:183], v[188:191], v[110:113]
	v_mfma_f32_16x16x32_bf16 v[102:105], v[172:175], v[196:199], v[102:105]
	v_mfma_f32_16x16x32_bf16 v[94:97], v[180:183], v[196:199], v[94:97]
	v_mfma_f32_16x16x32_bf16 v[86:89], v[172:175], v[204:207], v[86:89]
	v_mfma_f32_16x16x32_bf16 v[78:81], v[180:183], v[204:207], v[78:81]
	v_mfma_f32_16x16x32_bf16 v[70:73], v[172:175], v[212:215], v[70:73]
	v_mfma_f32_16x16x32_bf16 v[66:69], v[180:183], v[212:215], v[66:69]
	v_mfma_f32_16x16x32_bf16 v[118:121], v[176:179], v[192:195], v[118:121]
	v_mfma_f32_16x16x32_bf16 v[110:113], v[184:187], v[192:195], v[110:113]
	v_mfma_f32_16x16x32_bf16 v[102:105], v[176:179], v[200:203], v[102:105]
	v_mfma_f32_16x16x32_bf16 v[94:97], v[184:187], v[200:203], v[94:97]
	v_mfma_f32_16x16x32_bf16 v[86:89], v[176:179], v[208:211], v[86:89]
	v_mfma_f32_16x16x32_bf16 v[78:81], v[184:187], v[208:211], v[78:81]
	v_mfma_f32_16x16x32_bf16 v[70:73], v[176:179], v[216:219], v[70:73]
	s_setprio 0
	s_barrier
	v_mfma_f32_16x16x32_bf16 v[66:69], v[184:187], v[216:219], v[66:69]
	s_add_i32 s71, s63, s43
	v_lshl_add_u64 v[152:153], s[48:49], 0, v[132:133]
	s_mov_b32 m0, s71
	ds_read_b128 v[188:191], v157 offset:16384
	ds_read_b128 v[192:195], v157 offset:17408
	ds_read_b128 v[196:199], v157 offset:18432
	ds_read_b128 v[200:203], v157 offset:19456
	ds_read_b128 v[204:207], v157 offset:20480
	ds_read_b128 v[208:211], v157 offset:21504
	ds_read_b128 v[212:215], v157 offset:22528
	ds_read_b128 v[216:219], v157 offset:23552
	global_load_lds_dwordx4 v[152:153], off
	s_add_i32 m0, s71, 0x2000
	s_add_u32 s72, s48, 0x80000
	v_lshl_add_u64 v[220:221], s[48:49], 0, v[136:137]
	s_addc_u32 s73, s49, 0
	s_add_i32 s71, s64, s43
	global_load_lds_dwordx4 v[220:221], off
	v_lshl_add_u64 v[222:223], s[72:73], 0, v[132:133]
	s_mov_b32 m0, s71
	v_lshl_add_u64 v[224:225], s[50:51], 0, v[134:135]
	global_load_lds_dwordx4 v[222:223], off
	v_lshl_add_u64 v[222:223], s[72:73], 0, v[136:137]
	s_add_i32 m0, s71, 0x2000
	s_nop 0
	global_load_lds_dwordx4 v[222:223], off
	v_lshl_add_u64 v[222:223], s[50:51], 0, v[130:131]
	s_mov_b32 m0, s52
	s_nop 0
	global_load_lds_dwordx4 v[222:223], off
	s_mov_b32 m0, s53
	s_nop 0
	global_load_lds_dwordx4 v[224:225], off
	s_waitcnt vmcnt(8)
	s_waitcnt lgkmcnt(0)
	s_barrier
; #define PG8_STAGE(bufoff, gbase, voff) do { _Pragma("unroll") for (int _i = 0; _i < 2; ++_i) \
;         __builtin_amdgcn_global_load_lds((const unsigned*)((const char*)(gbase) + (voff)[_i]), (PG8_LAS unsigned*)(lds + (bufoff) + ldsw + _i * 8192), 16, 0, 0); } while (0)
; #define PG8_LDA(dst, b, h) do { _Pragma("unroll") for (int m = 0; m < 4; ++m) _Pragma("unroll") for (int k = 0; k < 2; ++k) dst[m][k] = *(const PG8_LAS bf16x8*)(lds + PG8_SA(b, h) + aoff + m * 2048 + k * 1024); } while (0)
; #define PG8_LDB(dst, b, h) do { _Pragma("unroll") for (int n = 0; n < 2; ++n) _Pragma("unroll") for (int k = 0; k < 2; ++k) dst[n][k] = *(const PG8_LAS bf16x8*)(lds + PG8_SB(b, h) + boff + n * 2048 + k * 1024); } while (0)
; #define PG8_MMA(ai, bj, At, Bt) do { __builtin_amdgcn_s_setprio(3); _Pragma("unroll") for (int m = 0; m < 4; ++m) _Pragma("unroll") for (int n = 0; n < 2; ++n) _Pragma("unroll") for (int k = 0; k < 2; ++k) \
;         acc[ai][bj][m][n] = __builtin_amdgcn_mfma_f32_16x16x32_bf16(Bt[n][k], At[m][k], acc[ai][bj][m][n], 0, 0, 0); __builtin_amdgcn_s_setprio(0); } while (0)
; #define PG8_WAIT_V(n) asm volatile("s_waitcnt vmcnt(" #n ")" ::: "memory")
; #define PG8_WAIT_L(n) asm volatile("s_waitcnt lgkmcnt(" #n ")" ::: "memory")
; #define PG8_BAR __builtin_amdgcn_s_barrier()
; #define PG8_SCHED __builtin_amdgcn_sched_barrier(0)
; template <class Epi, class Sched, bool ALIGN_EPI = false, bool SP2 = false>
; __device__ __forceinline__ void gemm_phase(PG8_LAS unsigned char* lds, const Gemm g, const Sched& S, const Epi& E) {
;     ...
;             PG8_WAIT_V(8); PG8_WAIT_L(0); PG8_BAR; PG8_MMA(1, 0, At, B0); PG8_MMA(1, 1, At, B1); PG8_BAR; PG8_SCHED;
;             PG8_LDB(B0, 1, 0); PG8_LDB(B1, 1, 1); PG8_SCHED; PG8_LDA(At, 1, 0); PG8_STAGE(PG8_SA(0, 1), a2 + hstep, voffA);
;             PG8_WAIT_V(8); PG8_WAIT_L(0); PG8_BAR; PG8_MMA(0, 0, At, B0); PG8_MMA(0, 1, At, B1); PG8_BAR; PG8_SCHED;
	s_setprio 3
	s_waitcnt lgkmcnt(0)
	v_mfma_f32_16x16x32_bf16 v[62:65], v[148:151], v[188:191], v[62:65]
	v_mfma_f32_16x16x32_bf16 v[58:61], v[162:165], v[188:191], v[58:61]
	v_mfma_f32_16x16x32_bf16 v[50:53], v[148:151], v[196:199], v[50:53]
	v_mfma_f32_16x16x32_bf16 v[42:45], v[162:165], v[196:199], v[42:45]
	v_mfma_f32_16x16x32_bf16 v[34:37], v[148:151], v[204:207], v[34:37]
	v_mfma_f32_16x16x32_bf16 v[26:29], v[162:165], v[204:207], v[26:29]
	v_mfma_f32_16x16x32_bf16 v[18:21], v[148:151], v[212:215], v[18:21]
	v_mfma_f32_16x16x32_bf16 v[10:13], v[162:165], v[212:215], v[10:13]
	v_mfma_f32_16x16x32_bf16 v[62:65], v[158:161], v[192:195], v[62:65]
	v_mfma_f32_16x16x32_bf16 v[58:61], v[168:171], v[192:195], v[58:61]
	v_mfma_f32_16x16x32_bf16 v[50:53], v[158:161], v[200:203], v[50:53]
	v_mfma_f32_16x16x32_bf16 v[42:45], v[168:171], v[200:203], v[42:45]
	v_mfma_f32_16x16x32_bf16 v[34:37], v[158:161], v[208:211], v[34:37]
	v_mfma_f32_16x16x32_bf16 v[26:29], v[168:171], v[208:211], v[26:29]
	v_mfma_f32_16x16x32_bf16 v[18:21], v[158:161], v[216:219], v[18:21]
	v_mfma_f32_16x16x32_bf16 v[10:13], v[168:171], v[216:219], v[10:13]
	s_setprio 0
	s_setprio 3
	v_mfma_f32_16x16x32_bf16 v[54:57], v[172:175], v[188:191], v[54:57]
	v_mfma_f32_16x16x32_bf16 v[46:49], v[180:183], v[188:191], v[46:49]
	v_mfma_f32_16x16x32_bf16 v[38:41], v[172:175], v[196:199], v[38:41]
	v_mfma_f32_16x16x32_bf16 v[30:33], v[180:183], v[196:199], v[30:33]
	v_mfma_f32_16x16x32_bf16 v[22:25], v[172:175], v[204:207], v[22:25]
	v_mfma_f32_16x16x32_bf16 v[14:17], v[180:183], v[204:207], v[14:17]
	v_mfma_f32_16x16x32_bf16 v[6:9], v[172:175], v[212:215], v[6:9]
	v_mfma_f32_16x16x32_bf16 v[2:5], v[180:183], v[212:215], v[2:5]
	v_mfma_f32_16x16x32_bf16 v[54:57], v[176:179], v[192:195], v[54:57]
	v_mfma_f32_16x16x32_bf16 v[46:49], v[184:187], v[192:195], v[46:49]
	v_mfma_f32_16x16x32_bf16 v[38:41], v[176:179], v[200:203], v[38:41]
	v_mfma_f32_16x16x32_bf16 v[30:33], v[184:187], v[200:203], v[30:33]
	v_mfma_f32_16x16x32_bf16 v[22:25], v[176:179], v[208:211], v[22:25]
	v_mfma_f32_16x16x32_bf16 v[14:17], v[184:187], v[208:211], v[14:17]
	v_mfma_f32_16x16x32_bf16 v[6:9], v[176:179], v[216:219], v[6:9]
	s_setprio 0
	s_barrier
	v_mfma_f32_16x16x32_bf16 v[2:5], v[184:187], v[216:219], v[2:5]
	s_add_i32 s71, 0, 0x18000
	v_add_u32_e32 v167, s71, v141
	s_add_i32 s72, 0, 0x1c000
	ds_read_b128 v[148:151], v167
	ds_read_b128 v[158:161], v167 offset:1024
	ds_read_b128 v[162:165], v167 offset:2048
	ds_read_b128 v[168:171], v167 offset:3072
	v_add_u32_e32 v167, s72, v141
	ds_read_b128 v[172:175], v167
	ds_read_b128 v[176:179], v167 offset:1024
	ds_read_b128 v[180:183], v167 offset:2048
	ds_read_b128 v[184:187], v167 offset:3072
	s_add_u32 s50, s50, 0x80000
	s_addc_u32 s51, s51, 0
	s_mov_b32 m0, s54
	v_lshl_add_u64 v[226:227], s[50:51], 0, v[130:131]
	ds_read_b128 v[188:191], v157 offset:32768
	ds_read_b128 v[192:195], v157 offset:33792
	ds_read_b128 v[196:199], v157 offset:34816
	ds_read_b128 v[200:203], v157 offset:35840
	ds_read_b128 v[204:207], v157 offset:36864
	ds_read_b128 v[208:211], v157 offset:37888
	ds_read_b128 v[212:215], v157 offset:38912
	ds_read_b128 v[216:219], v157 offset:39936
	global_load_lds_dwordx4 v[226:227], off
	v_lshl_add_u64 v[226:227], s[50:51], 0, v[134:135]
	s_mov_b32 m0, s55
	s_nop 0
	global_load_lds_dwordx4 v[226:227], off
	s_waitcnt vmcnt(8)
	s_waitcnt lgkmcnt(0)
	s_barrier
	s_setprio 3
	s_waitcnt lgkmcnt(0)
	v_mfma_f32_16x16x32_bf16 v[126:129], v[148:151], v[188:191], v[126:129]
	v_mfma_f32_16x16x32_bf16 v[122:125], v[162:165], v[188:191], v[122:125]
	v_mfma_f32_16x16x32_bf16 v[114:117], v[148:151], v[196:199], v[114:117]
	v_mfma_f32_16x16x32_bf16 v[106:109], v[162:165], v[196:199], v[106:109]
	v_mfma_f32_16x16x32_bf16 v[98:101], v[148:151], v[204:207], v[98:101]
	v_mfma_f32_16x16x32_bf16 v[90:93], v[162:165], v[204:207], v[90:93]
	v_mfma_f32_16x16x32_bf16 v[82:85], v[148:151], v[212:215], v[82:85]
	v_mfma_f32_16x16x32_bf16 v[74:77], v[162:165], v[212:215], v[74:77]
	v_mfma_f32_16x16x32_bf16 v[126:129], v[158:161], v[192:195], v[126:129]
	v_mfma_f32_16x16x32_bf16 v[122:125], v[168:171], v[192:195], v[122:125]
	v_mfma_f32_16x16x32_bf16 v[114:117], v[158:161], v[200:203], v[114:117]
	v_mfma_f32_16x16x32_bf16 v[106:109], v[168:171], v[200:203], v[106:109]
	v_mfma_f32_16x16x32_bf16 v[98:101], v[158:161], v[208:211], v[98:101]
	v_mfma_f32_16x16x32_bf16 v[90:93], v[168:171], v[208:211], v[90:93]
	v_mfma_f32_16x16x32_bf16 v[82:85], v[158:161], v[216:219], v[82:85]
	v_mfma_f32_16x16x32_bf16 v[74:77], v[168:171], v[216:219], v[74:77]
	s_setprio 0
	s_setprio 3
	v_mfma_f32_16x16x32_bf16 v[118:121], v[172:175], v[188:191], v[118:121]
	v_mfma_f32_16x16x32_bf16 v[110:113], v[180:183], v[188:191], v[110:113]
	v_mfma_f32_16x16x32_bf16 v[102:105], v[172:175], v[196:199], v[102:105]
	v_mfma_f32_16x16x32_bf16 v[94:97], v[180:183], v[196:199], v[94:97]
	v_mfma_f32_16x16x32_bf16 v[86:89], v[172:175], v[204:207], v[86:89]
	v_mfma_f32_16x16x32_bf16 v[78:81], v[180:183], v[204:207], v[78:81]
	v_mfma_f32_16x16x32_bf16 v[70:73], v[172:175], v[212:215], v[70:73]
	v_mfma_f32_16x16x32_bf16 v[66:69], v[180:183], v[212:215], v[66:69]
	v_mfma_f32_16x16x32_bf16 v[118:121], v[176:179], v[192:195], v[118:121]
	v_mfma_f32_16x16x32_bf16 v[110:113], v[184:187], v[192:195], v[110:113]
	v_mfma_f32_16x16x32_bf16 v[102:105], v[176:179], v[200:203], v[102:105]
	v_mfma_f32_16x16x32_bf16 v[94:97], v[184:187], v[200:203], v[94:97]
	v_mfma_f32_16x16x32_bf16 v[86:89], v[176:179], v[208:211], v[86:89]
	v_mfma_f32_16x16x32_bf16 v[78:81], v[184:187], v[208:211], v[78:81]
	v_mfma_f32_16x16x32_bf16 v[70:73], v[176:179], v[216:219], v[70:73]
	s_setprio 0
	s_barrier
; #define PG8_STAGE(bufoff, gbase, voff) do { _Pragma("unroll") for (int _i = 0; _i < 2; ++_i) \
;         __builtin_amdgcn_global_load_lds((const unsigned*)((const char*)(gbase) + (voff)[_i]), (PG8_LAS unsigned*)(lds + (bufoff) + ldsw + _i * 8192), 16, 0, 0); } while (0)
; #define PG8_LDA(dst, b, h) do { _Pragma("unroll") for (int m = 0; m < 4; ++m) _Pragma("unroll") for (int k = 0; k < 2; ++k) dst[m][k] = *(const PG8_LAS bf16x8*)(lds + PG8_SA(b, h) + aoff + m * 2048 + k * 1024); } while (0)
; #define PG8_MMA(ai, bj, At, Bt) do { __builtin_amdgcn_s_setprio(3); _Pragma("unroll") for (int m = 0; m < 4; ++m) _Pragma("unroll") for (int n = 0; n < 2; ++n) _Pragma("unroll") for (int k = 0; k < 2; ++k) \
;         acc[ai][bj][m][n] = __builtin_amdgcn_mfma_f32_16x16x32_bf16(Bt[n][k], At[m][k], acc[ai][bj][m][n], 0, 0, 0); __builtin_amdgcn_s_setprio(0); } while (0)
; #define PG8_WAIT_V(n) asm volatile("s_waitcnt vmcnt(" #n ")" ::: "memory")
; #define PG8_WAIT_L(n) asm volatile("s_waitcnt lgkmcnt(" #n ")" ::: "memory")
; #define PG8_BAR __builtin_amdgcn_s_barrier()
; #define PG8_SCHED __builtin_amdgcn_sched_barrier(0)
; template <class Epi, class Sched, bool ALIGN_EPI = false, bool SP2 = false>
; __device__ __forceinline__ void gemm_phase(PG8_LAS unsigned char* lds, const Gemm g, const Sched& S, const Epi& E) {
;     ...
;             PG8_WAIT_V(8); PG8_WAIT_L(0); PG8_BAR; PG8_MMA(0, 0, At, B0); PG8_MMA(0, 1, At, B1); PG8_BAR; PG8_SCHED;
;             PG8_LDA(At, 1, 1); PG8_STAGE(PG8_SB(1, 0), b3, voffB); PG8_STAGE(PG8_SB(1, 1), b3 + hstep, voffB); PG8_STAGE(PG8_SA(1, 0), a3, voffA);
;             PG8_WAIT_V(8); PG8_WAIT_L(0); PG8_BAR; PG8_MMA(1, 0, At, B0); PG8_MMA(1, 1, At, B1); PG8_BAR; PG8_SCHED;
;     ...
;         if constexpr (ALIGN_EPI) { if (wr == 0) PG8_BAR; }
	v_mfma_f32_16x16x32_bf16 v[66:69], v[184:187], v[216:219], v[66:69]
	s_add_i32 s50, s71, s43
	v_lshl_add_u64 v[152:153], v[152:153], 0, s[16:17]
	s_mov_b32 m0, s50
	ds_read_b128 v[188:191], v157 offset:49152
	ds_read_b128 v[192:195], v157 offset:50176
	ds_read_b128 v[196:199], v157 offset:51200
	ds_read_b128 v[200:203], v157 offset:52224
	ds_read_b128 v[204:207], v157 offset:53248
	ds_read_b128 v[208:211], v157 offset:54272
	ds_read_b128 v[212:215], v157 offset:55296
	ds_read_b128 v[216:219], v157 offset:56320
	global_load_lds_dwordx4 v[152:153], off
	s_add_i32 m0, s50, 0x2000
	s_add_u32 s48, s48, 0x80080
	v_lshl_add_u64 v[152:153], v[220:221], 0, s[16:17]
	s_addc_u32 s49, s49, 0
	s_add_i32 s50, s72, s43
	global_load_lds_dwordx4 v[152:153], off
	v_lshl_add_u64 v[152:153], s[48:49], 0, v[132:133]
	s_mov_b32 m0, s50
	s_nop 0
	global_load_lds_dwordx4 v[152:153], off
	v_lshl_add_u64 v[152:153], s[48:49], 0, v[136:137]
	s_add_i32 m0, s50, 0x2000
	s_nop 0
	global_load_lds_dwordx4 v[152:153], off
	v_lshl_add_u64 v[152:153], v[222:223], 0, s[16:17]
	s_mov_b32 m0, s59
	s_nop 0
	global_load_lds_dwordx4 v[152:153], off
	v_lshl_add_u64 v[152:153], v[224:225], 0, s[16:17]
	s_mov_b32 m0, s60
	s_nop 0
	global_load_lds_dwordx4 v[152:153], off
	s_waitcnt vmcnt(8)
	s_waitcnt lgkmcnt(0)
	s_barrier
	s_setprio 3
	s_waitcnt lgkmcnt(0)
	v_mfma_f32_16x16x32_bf16 v[62:65], v[148:151], v[188:191], v[62:65]
	v_mfma_f32_16x16x32_bf16 v[58:61], v[162:165], v[188:191], v[58:61]
	v_mfma_f32_16x16x32_bf16 v[50:53], v[148:151], v[196:199], v[50:53]
	v_mfma_f32_16x16x32_bf16 v[42:45], v[162:165], v[196:199], v[42:45]
	v_mfma_f32_16x16x32_bf16 v[34:37], v[148:151], v[204:207], v[34:37]
	v_mfma_f32_16x16x32_bf16 v[26:29], v[162:165], v[204:207], v[26:29]
	v_mfma_f32_16x16x32_bf16 v[18:21], v[148:151], v[212:215], v[18:21]
	v_mfma_f32_16x16x32_bf16 v[10:13], v[162:165], v[212:215], v[10:13]
	v_mfma_f32_16x16x32_bf16 v[62:65], v[158:161], v[192:195], v[62:65]
	v_mfma_f32_16x16x32_bf16 v[58:61], v[168:171], v[192:195], v[58:61]
	v_mfma_f32_16x16x32_bf16 v[50:53], v[158:161], v[200:203], v[50:53]
	v_mfma_f32_16x16x32_bf16 v[42:45], v[168:171], v[200:203], v[42:45]
	v_mfma_f32_16x16x32_bf16 v[34:37], v[158:161], v[208:211], v[34:37]
	v_mfma_f32_16x16x32_bf16 v[26:29], v[168:171], v[208:211], v[26:29]
	v_mfma_f32_16x16x32_bf16 v[18:21], v[158:161], v[216:219], v[18:21]
	v_mfma_f32_16x16x32_bf16 v[10:13], v[168:171], v[216:219], v[10:13]
	s_setprio 0
	s_setprio 3
	v_mfma_f32_16x16x32_bf16 v[54:57], v[172:175], v[188:191], v[54:57]
	v_mfma_f32_16x16x32_bf16 v[46:49], v[180:183], v[188:191], v[46:49]
	v_mfma_f32_16x16x32_bf16 v[38:41], v[172:175], v[196:199], v[38:41]
	v_mfma_f32_16x16x32_bf16 v[30:33], v[180:183], v[196:199], v[30:33]
	v_mfma_f32_16x16x32_bf16 v[22:25], v[172:175], v[204:207], v[22:25]
	v_mfma_f32_16x16x32_bf16 v[14:17], v[180:183], v[204:207], v[14:17]
	v_mfma_f32_16x16x32_bf16 v[6:9], v[172:175], v[212:215], v[6:9]
	v_mfma_f32_16x16x32_bf16 v[2:5], v[180:183], v[212:215], v[2:5]
	v_mfma_f32_16x16x32_bf16 v[54:57], v[176:179], v[192:195], v[54:57]
	v_mfma_f32_16x16x32_bf16 v[46:49], v[184:187], v[192:195], v[46:49]
	v_mfma_f32_16x16x32_bf16 v[38:41], v[176:179], v[200:203], v[38:41]
	v_mfma_f32_16x16x32_bf16 v[30:33], v[184:187], v[200:203], v[30:33]
	v_mfma_f32_16x16x32_bf16 v[22:25], v[176:179], v[208:211], v[22:25]
	v_mfma_f32_16x16x32_bf16 v[14:17], v[184:187], v[208:211], v[14:17]
	v_mfma_f32_16x16x32_bf16 v[6:9], v[176:179], v[216:219], v[6:9]
	s_setprio 0
	s_barrier
	v_mfma_f32_16x16x32_bf16 v[2:5], v[184:187], v[216:219], v[2:5]
	s_add_i32 s70, s70, 2
	s_add_u32 s46, s46, 0x100
	s_addc_u32 s47, s47, 0
	s_add_u32 s68, s68, 0x100
	s_addc_u32 s69, s69, 0
	s_cmp_gt_u32 s70, 29
	s_cbranch_scc0 .LBB0_394
	s_and_b64 vcc, exec, s[18:19]
	s_cbranch_vccz .LBB0_397
	s_barrier

; #define PG8_STAGE(bufoff, gbase, voff) do { _Pragma("unroll") for (int _i = 0; _i < 2; ++_i) \
;         __builtin_amdgcn_global_load_lds((const unsigned*)((const char*)(gbase) + (voff)[_i]), (PG8_LAS unsigned*)(lds + (bufoff) + ldsw + _i * 8192), 16, 0, 0); } while (0)
; #define PG8_LDA(dst, b, h) do { _Pragma("unroll") for (int m = 0; m < 4; ++m) _Pragma("unroll") for (int k = 0; k < 2; ++k) dst[m][k] = *(const PG8_LAS bf16x8*)(lds + PG8_SA(b, h) + aoff + m * 2048 + k * 1024); } while (0)
; #define PG8_LDB(dst, b, h) do { _Pragma("unroll") for (int n = 0; n < 2; ++n) _Pragma("unroll") for (int k = 0; k < 2; ++k) dst[n][k] = *(const PG8_LAS bf16x8*)(lds + PG8_SB(b, h) + boff + n * 2048 + k * 1024); } while (0)
; #define PG8_MMA(ai, bj, At, Bt) do { __builtin_amdgcn_s_setprio(3); _Pragma("unroll") for (int m = 0; m < 4; ++m) _Pragma("unroll") for (int n = 0; n < 2; ++n) _Pragma("unroll") for (int k = 0; k < 2; ++k) \
;         acc[ai][bj][m][n] = __builtin_amdgcn_mfma_f32_16x16x32_bf16(Bt[n][k], At[m][k], acc[ai][bj][m][n], 0, 0, 0); __builtin_amdgcn_s_setprio(0); } while (0)
; #define PG8_WAIT_V(n) asm volatile("s_waitcnt vmcnt(" #n ")" ::: "memory")
; #define PG8_BAR __builtin_amdgcn_s_barrier()
; template <class Epi, class Sched, bool ALIGN_EPI = false, bool SP2 = false>
; __device__ __forceinline__ void gemm_phase(PG8_LAS unsigned char* lds, const Gemm g, const Sched& S, const Epi& E) {
;     ...
;         for (int t = 0; t < nt; t += 2) {
;             const bool last = (t == nt - 2);
;             const char* a1 = cA + (size_t)(t + 1) * kstep;
;             const char* a2 = last ? nA : cA + (size_t)(t + 2) * kstep; const char* b2 = last ? nB : cB + (size_t)(t + 2) * kstep;
;             const char* a3 = a2 + kstep; const char* b3 = b2 + kstep;
;             if (last && has_next) S.a_ready(nxt);
;             if constexpr (SP2) {
;             PG8_LDB(B0, 0, 0); PG8_LDB(B1, 0, 1); PG8_SCHED; PG8_LDA(At, 0, 0); PG8_STAGE(PG8_SA(1, 1), a1 + hstep, voffA);
;             PG8_WAIT_V(8); PG8_WAIT_L(0); PG8_BAR; PG8_MMA(0, 0, At, B0); PG8_MMA(0, 1, At, B1); PG8_BAR; PG8_SCHED;
;             PG8_LDA(At, 0, 1); PG8_STAGE(PG8_SB(0, 0), b2, voffB); PG8_STAGE(PG8_SB(0, 1), b2 + hstep, voffB); PG8_STAGE(PG8_SA(0, 0), a2, voffA);
;             PG8_WAIT_V(8); PG8_WAIT_L(0); PG8_BAR; PG8_MMA(1, 0, At, B0); PG8_MMA(1, 1, At, B1); PG8_BAR; PG8_SCHED;
.LBB0_677:
	ds_read_b128 v[132:135], v168
	ds_read_b128 v[136:139], v168 offset:1024
	ds_read_b128 v[158:161], v168 offset:2048
	ds_read_b128 v[162:165], v168 offset:3072
	ds_read_b128 v[172:175], v169
	ds_read_b128 v[176:179], v169 offset:1024
	ds_read_b128 v[180:183], v169 offset:2048
	ds_read_b128 v[184:187], v169 offset:3072
	s_add_i32 s74, s48, 2
	s_add_u32 s75, s6, 0x80
	s_addc_u32 s49, s7, 0
	s_cmp_eq_u32 s73, s48
	s_cselect_b32 s48, s44, s75
	s_cselect_b32 s49, s45, s49
	s_cselect_b32 s77, s47, s51
	s_cselect_b32 s76, s46, s50
	v_lshl_add_u64 v[74:75], s[6:7], 0, v[150:151]
	s_add_i32 m0, s54, 0xc000
	ds_read_b128 v[188:191], v170
	ds_read_b128 v[192:195], v170 offset:1024
	ds_read_b128 v[196:199], v170 offset:2048
	ds_read_b128 v[200:203], v170 offset:3072
	ds_read_b128 v[204:207], v170 offset:4096
	ds_read_b128 v[208:211], v170 offset:5120
	ds_read_b128 v[212:215], v170 offset:6144
	ds_read_b128 v[216:219], v170 offset:7168
	global_load_lds_dwordx4 v[74:75], off
	v_lshl_add_u64 v[74:75], s[6:7], 0, v[152:153]
	s_add_i32 m0, s54, 0xe000
	s_nop 0
	global_load_lds_dwordx4 v[74:75], off
	s_waitcnt vmcnt(8)
	s_waitcnt lgkmcnt(0)
	s_barrier
	s_setprio 3
	s_waitcnt lgkmcnt(0)
	v_mfma_f32_16x16x32_bf16 v[128:131], v[132:135], v[188:191], v[128:131]
	v_mfma_f32_16x16x32_bf16 v[124:127], v[158:161], v[188:191], v[124:127]
	v_mfma_f32_16x16x32_bf16 v[120:123], v[132:135], v[196:199], v[120:123]
	v_mfma_f32_16x16x32_bf16 v[116:119], v[158:161], v[196:199], v[116:119]
	v_mfma_f32_16x16x32_bf16 v[112:115], v[132:135], v[204:207], v[112:115]
	v_mfma_f32_16x16x32_bf16 v[108:111], v[158:161], v[204:207], v[108:111]
	v_mfma_f32_16x16x32_bf16 v[104:107], v[132:135], v[212:215], v[104:107]
	v_mfma_f32_16x16x32_bf16 v[100:103], v[158:161], v[212:215], v[100:103]
	v_mfma_f32_16x16x32_bf16 v[128:131], v[136:139], v[192:195], v[128:131]
	v_mfma_f32_16x16x32_bf16 v[124:127], v[162:165], v[192:195], v[124:127]
	v_mfma_f32_16x16x32_bf16 v[120:123], v[136:139], v[200:203], v[120:123]
	v_mfma_f32_16x16x32_bf16 v[116:119], v[162:165], v[200:203], v[116:119]
	v_mfma_f32_16x16x32_bf16 v[112:115], v[136:139], v[208:211], v[112:115]
	v_mfma_f32_16x16x32_bf16 v[108:111], v[162:165], v[208:211], v[108:111]
	v_mfma_f32_16x16x32_bf16 v[104:107], v[136:139], v[216:219], v[104:107]
	v_mfma_f32_16x16x32_bf16 v[100:103], v[162:165], v[216:219], v[100:103]
	s_setprio 0
	s_setprio 3
	v_mfma_f32_16x16x32_bf16 v[62:65], v[172:175], v[188:191], v[62:65]
	v_mfma_f32_16x16x32_bf16 v[58:61], v[180:183], v[188:191], v[58:61]
	v_mfma_f32_16x16x32_bf16 v[54:57], v[172:175], v[196:199], v[54:57]
	v_mfma_f32_16x16x32_bf16 v[50:53], v[180:183], v[196:199], v[50:53]
	v_mfma_f32_16x16x32_bf16 v[46:49], v[172:175], v[204:207], v[46:49]
	v_mfma_f32_16x16x32_bf16 v[42:45], v[180:183], v[204:207], v[42:45]
	v_mfma_f32_16x16x32_bf16 v[38:41], v[172:175], v[212:215], v[38:41]
	v_mfma_f32_16x16x32_bf16 v[34:37], v[180:183], v[212:215], v[34:37]
	v_mfma_f32_16x16x32_bf16 v[62:65], v[176:179], v[192:195], v[62:65]
	v_mfma_f32_16x16x32_bf16 v[58:61], v[184:187], v[192:195], v[58:61]
	v_mfma_f32_16x16x32_bf16 v[54:57], v[176:179], v[200:203], v[54:57]
	v_mfma_f32_16x16x32_bf16 v[50:53], v[184:187], v[200:203], v[50:53]
	v_mfma_f32_16x16x32_bf16 v[46:49], v[176:179], v[208:211], v[46:49]
	v_mfma_f32_16x16x32_bf16 v[42:45], v[184:187], v[208:211], v[42:45]
	v_mfma_f32_16x16x32_bf16 v[38:41], v[176:179], v[216:219], v[38:41]
	s_setprio 0
	s_barrier
	v_mfma_f32_16x16x32_bf16 v[34:37], v[184:187], v[216:219], v[34:37]
	s_add_i32 s75, s63, s43
	v_lshl_add_u64 v[220:221], s[76:77], 0, v[146:147]
	s_mov_b32 m0, s75
	ds_read_b128 v[188:191], v170 offset:16384
	ds_read_b128 v[192:195], v170 offset:17408
	ds_read_b128 v[196:199], v170 offset:18432
	ds_read_b128 v[200:203], v170 offset:19456
	ds_read_b128 v[204:207], v170 offset:20480
	ds_read_b128 v[208:211], v170 offset:21504
	ds_read_b128 v[212:215], v170 offset:22528
	ds_read_b128 v[216:219], v170 offset:23552
	global_load_lds_dwordx4 v[220:221], off
	s_add_i32 m0, s75, 0x2000
	v_lshl_add_u64 v[222:223], s[76:77], 0, v[142:143]
	s_add_u32 s76, s76, s14
	s_addc_u32 s77, s77, s15
	s_add_i32 s75, s64, s43
	global_load_lds_dwordx4 v[222:223], off
	v_lshl_add_u64 v[224:225], s[76:77], 0, v[146:147]
	s_mov_b32 m0, s75
	v_lshl_add_u64 v[226:227], s[76:77], 0, v[142:143]
	global_load_lds_dwordx4 v[224:225], off
	s_add_i32 m0, s75, 0x2000
	v_lshl_add_u64 v[228:229], s[48:49], 0, v[148:149]
	global_load_lds_dwordx4 v[226:227], off
	s_mov_b32 m0, s54
	v_lshl_add_u64 v[230:231], s[48:49], 0, v[144:145]
	global_load_lds_dwordx4 v[228:229], off
	s_mov_b32 m0, s55
	s_nop 0
	global_load_lds_dwordx4 v[230:231], off
	s_waitcnt vmcnt(8)
	s_waitcnt lgkmcnt(0)
	s_barrier
; #define PG8_STAGE(bufoff, gbase, voff) do { _Pragma("unroll") for (int _i = 0; _i < 2; ++_i) \
;         __builtin_amdgcn_global_load_lds((const unsigned*)((const char*)(gbase) + (voff)[_i]), (PG8_LAS unsigned*)(lds + (bufoff) + ldsw + _i * 8192), 16, 0, 0); } while (0)
; #define PG8_LDA(dst, b, h) do { _Pragma("unroll") for (int m = 0; m < 4; ++m) _Pragma("unroll") for (int k = 0; k < 2; ++k) dst[m][k] = *(const PG8_LAS bf16x8*)(lds + PG8_SA(b, h) + aoff + m * 2048 + k * 1024); } while (0)
; #define PG8_LDB(dst, b, h) do { _Pragma("unroll") for (int n = 0; n < 2; ++n) _Pragma("unroll") for (int k = 0; k < 2; ++k) dst[n][k] = *(const PG8_LAS bf16x8*)(lds + PG8_SB(b, h) + boff + n * 2048 + k * 1024); } while (0)
; #define PG8_MMA(ai, bj, At, Bt) do { __builtin_amdgcn_s_setprio(3); _Pragma("unroll") for (int m = 0; m < 4; ++m) _Pragma("unroll") for (int n = 0; n < 2; ++n) _Pragma("unroll") for (int k = 0; k < 2; ++k) \
;         acc[ai][bj][m][n] = __builtin_amdgcn_mfma_f32_16x16x32_bf16(Bt[n][k], At[m][k], acc[ai][bj][m][n], 0, 0, 0); __builtin_amdgcn_s_setprio(0); } while (0)
; #define PG8_WAIT_V(n) asm volatile("s_waitcnt vmcnt(" #n ")" ::: "memory")
; #define PG8_WAIT_L(n) asm volatile("s_waitcnt lgkmcnt(" #n ")" ::: "memory")
; #define PG8_BAR __builtin_amdgcn_s_barrier()
; #define PG8_SCHED __builtin_amdgcn_sched_barrier(0)
; template <class Epi, class Sched, bool ALIGN_EPI = false, bool SP2 = false>
; __device__ __forceinline__ void gemm_phase(PG8_LAS unsigned char* lds, const Gemm g, const Sched& S, const Epi& E) {
;     ...
;             PG8_WAIT_V(8); PG8_WAIT_L(0); PG8_BAR; PG8_MMA(1, 0, At, B0); PG8_MMA(1, 1, At, B1); PG8_BAR; PG8_SCHED;
;             PG8_LDB(B0, 1, 0); PG8_LDB(B1, 1, 1); PG8_SCHED; PG8_LDA(At, 1, 0); PG8_STAGE(PG8_SA(0, 1), a2 + hstep, voffA);
;             PG8_WAIT_V(8); PG8_WAIT_L(0); PG8_BAR; PG8_MMA(0, 0, At, B0); PG8_MMA(0, 1, At, B1); PG8_BAR; PG8_SCHED;
	s_setprio 3
	s_waitcnt lgkmcnt(0)
	v_mfma_f32_16x16x32_bf16 v[96:99], v[132:135], v[188:191], v[96:99]
	v_mfma_f32_16x16x32_bf16 v[92:95], v[158:161], v[188:191], v[92:95]
	v_mfma_f32_16x16x32_bf16 v[88:91], v[132:135], v[196:199], v[88:91]
	v_mfma_f32_16x16x32_bf16 v[84:87], v[158:161], v[196:199], v[84:87]
	v_mfma_f32_16x16x32_bf16 v[80:83], v[132:135], v[204:207], v[80:83]
	v_mfma_f32_16x16x32_bf16 v[74:77], v[158:161], v[204:207], v[76:79]
	v_mfma_f32_16x16x32_bf16 v[70:73], v[132:135], v[212:215], v[70:73]
	v_mfma_f32_16x16x32_bf16 v[66:69], v[158:161], v[212:215], v[66:69]
	v_mfma_f32_16x16x32_bf16 v[96:99], v[136:139], v[192:195], v[96:99]
	v_mfma_f32_16x16x32_bf16 v[92:95], v[162:165], v[192:195], v[92:95]
	v_mfma_f32_16x16x32_bf16 v[88:91], v[136:139], v[200:203], v[88:91]
	v_mfma_f32_16x16x32_bf16 v[84:87], v[162:165], v[200:203], v[84:87]
	v_mfma_f32_16x16x32_bf16 v[80:83], v[136:139], v[208:211], v[80:83]
	v_mfma_f32_16x16x32_bf16 v[74:77], v[162:165], v[208:211], v[74:77]
	v_mfma_f32_16x16x32_bf16 v[70:73], v[136:139], v[216:219], v[70:73]
	v_mfma_f32_16x16x32_bf16 v[66:69], v[162:165], v[216:219], v[66:69]
	s_setprio 0
	s_setprio 3
	v_mfma_f32_16x16x32_bf16 v[30:33], v[172:175], v[188:191], v[30:33]
	v_mfma_f32_16x16x32_bf16 v[26:29], v[180:183], v[188:191], v[26:29]
	v_mfma_f32_16x16x32_bf16 v[22:25], v[172:175], v[196:199], v[22:25]
	v_mfma_f32_16x16x32_bf16 v[18:21], v[180:183], v[196:199], v[18:21]
	v_mfma_f32_16x16x32_bf16 v[14:17], v[172:175], v[204:207], v[14:17]
	v_mfma_f32_16x16x32_bf16 v[10:13], v[180:183], v[204:207], v[10:13]
	v_mfma_f32_16x16x32_bf16 v[6:9], v[172:175], v[212:215], v[6:9]
	v_mfma_f32_16x16x32_bf16 v[2:5], v[180:183], v[212:215], v[2:5]
	v_mfma_f32_16x16x32_bf16 v[30:33], v[176:179], v[192:195], v[30:33]
	v_mfma_f32_16x16x32_bf16 v[26:29], v[184:187], v[192:195], v[26:29]
	v_mfma_f32_16x16x32_bf16 v[22:25], v[176:179], v[200:203], v[22:25]
	v_mfma_f32_16x16x32_bf16 v[18:21], v[184:187], v[200:203], v[18:21]
	v_mfma_f32_16x16x32_bf16 v[14:17], v[176:179], v[208:211], v[14:17]
	v_mfma_f32_16x16x32_bf16 v[10:13], v[184:187], v[208:211], v[10:13]
	v_mfma_f32_16x16x32_bf16 v[6:9], v[176:179], v[216:219], v[6:9]
	s_setprio 0
	s_barrier
	v_mfma_f32_16x16x32_bf16 v[2:5], v[184:187], v[216:219], v[2:5]
	s_add_i32 s75, 0, 0x18000
	v_add_u32_e32 v78, s75, v141
	s_add_i32 s76, 0, 0x1c000
	ds_read_b128 v[132:135], v78
	ds_read_b128 v[136:139], v78 offset:1024
	ds_read_b128 v[158:161], v78 offset:2048
	ds_read_b128 v[162:165], v78 offset:3072
	v_add_u32_e32 v78, s76, v141
	ds_read_b128 v[172:175], v78
	ds_read_b128 v[176:179], v78 offset:1024
	ds_read_b128 v[180:183], v78 offset:2048
	ds_read_b128 v[184:187], v78 offset:3072
	s_add_u32 s48, s48, s14
	s_addc_u32 s49, s49, s15
	s_mov_b32 m0, s56
	v_lshl_add_u64 v[78:79], s[48:49], 0, v[148:149]
	ds_read_b128 v[188:191], v170 offset:32768
	ds_read_b128 v[192:195], v170 offset:33792
	ds_read_b128 v[196:199], v170 offset:34816
	ds_read_b128 v[200:203], v170 offset:35840
	ds_read_b128 v[204:207], v170 offset:36864
	ds_read_b128 v[208:211], v170 offset:37888
	ds_read_b128 v[212:215], v170 offset:38912
	ds_read_b128 v[216:219], v170 offset:39936
	global_load_lds_dwordx4 v[78:79], off
	v_lshl_add_u64 v[78:79], s[48:49], 0, v[144:145]
	s_mov_b32 m0, s57
	s_nop 0
	global_load_lds_dwordx4 v[78:79], off
	s_waitcnt vmcnt(8)
	s_waitcnt lgkmcnt(0)
	s_barrier
	s_setprio 3
	s_waitcnt lgkmcnt(0)
	v_mfma_f32_16x16x32_bf16 v[128:131], v[132:135], v[188:191], v[128:131]
	v_mfma_f32_16x16x32_bf16 v[124:127], v[158:161], v[188:191], v[124:127]
	v_mfma_f32_16x16x32_bf16 v[120:123], v[132:135], v[196:199], v[120:123]
	v_mfma_f32_16x16x32_bf16 v[116:119], v[158:161], v[196:199], v[116:119]
	v_mfma_f32_16x16x32_bf16 v[112:115], v[132:135], v[204:207], v[112:115]
	v_mfma_f32_16x16x32_bf16 v[108:111], v[158:161], v[204:207], v[108:111]
	v_mfma_f32_16x16x32_bf16 v[104:107], v[132:135], v[212:215], v[104:107]
	v_mfma_f32_16x16x32_bf16 v[100:103], v[158:161], v[212:215], v[100:103]
	v_mfma_f32_16x16x32_bf16 v[128:131], v[136:139], v[192:195], v[128:131]
	v_mfma_f32_16x16x32_bf16 v[124:127], v[162:165], v[192:195], v[124:127]
	v_mfma_f32_16x16x32_bf16 v[120:123], v[136:139], v[200:203], v[120:123]
	v_mfma_f32_16x16x32_bf16 v[116:119], v[162:165], v[200:203], v[116:119]
	v_mfma_f32_16x16x32_bf16 v[112:115], v[136:139], v[208:211], v[112:115]
	v_mfma_f32_16x16x32_bf16 v[108:111], v[162:165], v[208:211], v[108:111]
	v_mfma_f32_16x16x32_bf16 v[104:107], v[136:139], v[216:219], v[104:107]
	v_mfma_f32_16x16x32_bf16 v[100:103], v[162:165], v[216:219], v[100:103]
	s_setprio 0
	s_setprio 3
	v_mfma_f32_16x16x32_bf16 v[62:65], v[172:175], v[188:191], v[62:65]
	v_mfma_f32_16x16x32_bf16 v[58:61], v[180:183], v[188:191], v[58:61]
	v_mfma_f32_16x16x32_bf16 v[54:57], v[172:175], v[196:199], v[54:57]
	v_mfma_f32_16x16x32_bf16 v[50:53], v[180:183], v[196:199], v[50:53]
	v_mfma_f32_16x16x32_bf16 v[46:49], v[172:175], v[204:207], v[46:49]
	v_mfma_f32_16x16x32_bf16 v[42:45], v[180:183], v[204:207], v[42:45]
	v_mfma_f32_16x16x32_bf16 v[38:41], v[172:175], v[212:215], v[38:41]
	v_mfma_f32_16x16x32_bf16 v[34:37], v[180:183], v[212:215], v[34:37]
	v_mfma_f32_16x16x32_bf16 v[62:65], v[176:179], v[192:195], v[62:65]
	v_mfma_f32_16x16x32_bf16 v[58:61], v[184:187], v[192:195], v[58:61]
	v_mfma_f32_16x16x32_bf16 v[54:57], v[176:179], v[200:203], v[54:57]
	v_mfma_f32_16x16x32_bf16 v[50:53], v[184:187], v[200:203], v[50:53]
	v_mfma_f32_16x16x32_bf16 v[46:49], v[176:179], v[208:211], v[46:49]
	v_mfma_f32_16x16x32_bf16 v[42:45], v[184:187], v[208:211], v[42:45]
	v_mfma_f32_16x16x32_bf16 v[38:41], v[176:179], v[216:219], v[38:41]
	s_setprio 0
	s_barrier
; #define PG8_STAGE(bufoff, gbase, voff) do { _Pragma("unroll") for (int _i = 0; _i < 2; ++_i) \
;         __builtin_amdgcn_global_load_lds((const unsigned*)((const char*)(gbase) + (voff)[_i]), (PG8_LAS unsigned*)(lds + (bufoff) + ldsw + _i * 8192), 16, 0, 0); } while (0)
; #define PG8_LDA(dst, b, h) do { _Pragma("unroll") for (int m = 0; m < 4; ++m) _Pragma("unroll") for (int k = 0; k < 2; ++k) dst[m][k] = *(const PG8_LAS bf16x8*)(lds + PG8_SA(b, h) + aoff + m * 2048 + k * 1024); } while (0)
; #define PG8_MMA(ai, bj, At, Bt) do { __builtin_amdgcn_s_setprio(3); _Pragma("unroll") for (int m = 0; m < 4; ++m) _Pragma("unroll") for (int n = 0; n < 2; ++n) _Pragma("unroll") for (int k = 0; k < 2; ++k) \
;         acc[ai][bj][m][n] = __builtin_amdgcn_mfma_f32_16x16x32_bf16(Bt[n][k], At[m][k], acc[ai][bj][m][n], 0, 0, 0); __builtin_amdgcn_s_setprio(0); } while (0)
; #define PG8_WAIT_V(n) asm volatile("s_waitcnt vmcnt(" #n ")" ::: "memory")
; #define PG8_WAIT_L(n) asm volatile("s_waitcnt lgkmcnt(" #n ")" ::: "memory")
; #define PG8_BAR __builtin_amdgcn_s_barrier()
; #define PG8_SCHED __builtin_amdgcn_sched_barrier(0)
; template <class Epi, class Sched, bool ALIGN_EPI = false, bool SP2 = false>
; __device__ __forceinline__ void gemm_phase(PG8_LAS unsigned char* lds, const Gemm g, const Sched& S, const Epi& E) {
;     ...
;             PG8_WAIT_V(8); PG8_WAIT_L(0); PG8_BAR; PG8_MMA(0, 0, At, B0); PG8_MMA(0, 1, At, B1); PG8_BAR; PG8_SCHED;
;             PG8_LDA(At, 1, 1); PG8_STAGE(PG8_SB(1, 0), b3, voffB); PG8_STAGE(PG8_SB(1, 1), b3 + hstep, voffB); PG8_STAGE(PG8_SA(1, 0), a3, voffA);
;             PG8_WAIT_V(8); PG8_WAIT_L(0); PG8_BAR; PG8_MMA(1, 0, At, B0); PG8_MMA(1, 1, At, B1); PG8_BAR; PG8_SCHED;
;     ...
;         if constexpr (ALIGN_EPI) { if (wr == 0) PG8_BAR; }
	v_mfma_f32_16x16x32_bf16 v[34:37], v[184:187], v[216:219], v[34:37]
	s_add_i32 s48, s75, s43
	v_lshl_add_u64 v[78:79], v[220:221], 0, s[28:29]
	s_mov_b32 m0, s48
	ds_read_b128 v[188:191], v170 offset:49152
	ds_read_b128 v[192:195], v170 offset:50176
	ds_read_b128 v[196:199], v170 offset:51200
	ds_read_b128 v[200:203], v170 offset:52224
	ds_read_b128 v[204:207], v170 offset:53248
	ds_read_b128 v[208:211], v170 offset:54272
	ds_read_b128 v[212:215], v170 offset:55296
	ds_read_b128 v[216:219], v170 offset:56320
	global_load_lds_dwordx4 v[78:79], off
	v_lshl_add_u64 v[78:79], v[222:223], 0, s[28:29]
	s_add_i32 m0, s48, 0x2000
	s_add_i32 s48, s76, s43
	global_load_lds_dwordx4 v[78:79], off
	v_lshl_add_u64 v[78:79], v[224:225], 0, s[28:29]
	s_mov_b32 m0, s48
	s_nop 0
	global_load_lds_dwordx4 v[78:79], off
	v_lshl_add_u64 v[78:79], v[226:227], 0, s[28:29]
	s_add_i32 m0, s48, 0x2000
	s_nop 0
	global_load_lds_dwordx4 v[78:79], off
	v_lshl_add_u64 v[78:79], v[228:229], 0, s[28:29]
	s_mov_b32 m0, s60
	s_nop 0
	global_load_lds_dwordx4 v[78:79], off
	v_lshl_add_u64 v[78:79], v[230:231], 0, s[28:29]
	s_mov_b32 m0, s61
	s_nop 0
	global_load_lds_dwordx4 v[78:79], off
	s_waitcnt vmcnt(8)
	s_waitcnt lgkmcnt(0)
	s_barrier
	s_setprio 3
	s_waitcnt lgkmcnt(0)
	v_mfma_f32_16x16x32_bf16 v[96:99], v[132:135], v[188:191], v[96:99]
	v_mfma_f32_16x16x32_bf16 v[92:95], v[158:161], v[188:191], v[92:95]
	v_mfma_f32_16x16x32_bf16 v[88:91], v[132:135], v[196:199], v[88:91]
	v_mfma_f32_16x16x32_bf16 v[84:87], v[158:161], v[196:199], v[84:87]
	v_mfma_f32_16x16x32_bf16 v[78:81], v[132:135], v[204:207], v[80:83]
	v_mfma_f32_16x16x32_bf16 v[74:77], v[158:161], v[204:207], v[74:77]
	v_mfma_f32_16x16x32_bf16 v[70:73], v[132:135], v[212:215], v[70:73]
	v_mfma_f32_16x16x32_bf16 v[66:69], v[158:161], v[212:215], v[66:69]
	v_mfma_f32_16x16x32_bf16 v[96:99], v[136:139], v[192:195], v[96:99]
	v_mfma_f32_16x16x32_bf16 v[92:95], v[162:165], v[192:195], v[92:95]
	v_mfma_f32_16x16x32_bf16 v[88:91], v[136:139], v[200:203], v[88:91]
	v_mfma_f32_16x16x32_bf16 v[84:87], v[162:165], v[200:203], v[84:87]
	v_mfma_f32_16x16x32_bf16 v[80:83], v[136:139], v[208:211], v[78:81]
	v_mfma_f32_16x16x32_bf16 v[76:79], v[162:165], v[208:211], v[74:77]
	v_mfma_f32_16x16x32_bf16 v[70:73], v[136:139], v[216:219], v[70:73]
	v_mfma_f32_16x16x32_bf16 v[66:69], v[162:165], v[216:219], v[66:69]
	s_setprio 0
	s_setprio 3
	v_mfma_f32_16x16x32_bf16 v[30:33], v[172:175], v[188:191], v[30:33]
	v_mfma_f32_16x16x32_bf16 v[26:29], v[180:183], v[188:191], v[26:29]
	v_mfma_f32_16x16x32_bf16 v[22:25], v[172:175], v[196:199], v[22:25]
	v_mfma_f32_16x16x32_bf16 v[18:21], v[180:183], v[196:199], v[18:21]
	v_mfma_f32_16x16x32_bf16 v[14:17], v[172:175], v[204:207], v[14:17]
	v_mfma_f32_16x16x32_bf16 v[10:13], v[180:183], v[204:207], v[10:13]
	v_mfma_f32_16x16x32_bf16 v[6:9], v[172:175], v[212:215], v[6:9]
	v_mfma_f32_16x16x32_bf16 v[2:5], v[180:183], v[212:215], v[2:5]
	v_mfma_f32_16x16x32_bf16 v[30:33], v[176:179], v[192:195], v[30:33]
	v_mfma_f32_16x16x32_bf16 v[26:29], v[184:187], v[192:195], v[26:29]
	v_mfma_f32_16x16x32_bf16 v[22:25], v[176:179], v[200:203], v[22:25]
	v_mfma_f32_16x16x32_bf16 v[18:21], v[184:187], v[200:203], v[18:21]
	v_mfma_f32_16x16x32_bf16 v[14:17], v[176:179], v[208:211], v[14:17]
	v_mfma_f32_16x16x32_bf16 v[10:13], v[184:187], v[208:211], v[10:13]
	v_mfma_f32_16x16x32_bf16 v[6:9], v[176:179], v[216:219], v[6:9]
	s_setprio 0
	s_barrier
	v_mfma_f32_16x16x32_bf16 v[2:5], v[184:187], v[216:219], v[2:5]
	s_add_u32 s6, s6, 0x100
	s_addc_u32 s7, s7, 0
	s_add_u32 s50, s50, 0x100
	s_addc_u32 s51, s51, 0
	s_cmp_ge_u32 s74, s72
	s_mov_b32 s48, s74
	s_cbranch_scc0 .LBB0_677
	s_and_b64 vcc, exec, s[30:31]
	s_cbranch_vccz .LBB0_680
	s_barrier

; #define PG8_STAGE(bufoff, gbase, voff) do { _Pragma("unroll") for (int _i = 0; _i < 2; ++_i) \
;         __builtin_amdgcn_global_load_lds((const unsigned*)((const char*)(gbase) + (voff)[_i]), (PG8_LAS unsigned*)(lds + (bufoff) + ldsw + _i * 8192), 16, 0, 0); } while (0)
; #define PG8_LDA(dst, b, h) do { _Pragma("unroll") for (int m = 0; m < 4; ++m) _Pragma("unroll") for (int k = 0; k < 2; ++k) dst[m][k] = *(const PG8_LAS bf16x8*)(lds + PG8_SA(b, h) + aoff + m * 2048 + k * 1024); } while (0)
; #define PG8_LDB(dst, b, h) do { _Pragma("unroll") for (int n = 0; n < 2; ++n) _Pragma("unroll") for (int k = 0; k < 2; ++k) dst[n][k] = *(const PG8_LAS bf16x8*)(lds + PG8_SB(b, h) + boff + n * 2048 + k * 1024); } while (0)
; #define PG8_MMA(ai, bj, At, Bt) do { __builtin_amdgcn_s_setprio(3); _Pragma("unroll") for (int m = 0; m < 4; ++m) _Pragma("unroll") for (int n = 0; n < 2; ++n) _Pragma("unroll") for (int k = 0; k < 2; ++k) \
;         acc[ai][bj][m][n] = __builtin_amdgcn_mfma_f32_16x16x32_bf16(Bt[n][k], At[m][k], acc[ai][bj][m][n], 0, 0, 0); __builtin_amdgcn_s_setprio(0); } while (0)
; #define PG8_WAIT_V(n) asm volatile("s_waitcnt vmcnt(" #n ")" ::: "memory")
; #define PG8_BAR __builtin_amdgcn_s_barrier()
; template <class Epi, class Sched, bool ALIGN_EPI = false, bool SP2 = false>
; __device__ __forceinline__ void gemm_phase(PG8_LAS unsigned char* lds, const Gemm g, const Sched& S, const Epi& E) {
;     ...
;         for (int t = 0; t < nt; t += 2) {
;             const bool last = (t == nt - 2);
;             const char* a1 = cA + (size_t)(t + 1) * kstep;
;             const char* a2 = last ? nA : cA + (size_t)(t + 2) * kstep; const char* b2 = last ? nB : cB + (size_t)(t + 2) * kstep;
;             const char* a3 = a2 + kstep; const char* b3 = b2 + kstep;
;             if (last && has_next) S.a_ready(nxt);
;             if constexpr (SP2) {
;             PG8_LDB(B0, 0, 0); PG8_LDB(B1, 0, 1); PG8_SCHED; PG8_LDA(At, 0, 0); PG8_STAGE(PG8_SA(1, 1), a1 + hstep, voffA);
;             PG8_WAIT_V(8); PG8_WAIT_L(0); PG8_BAR; PG8_MMA(0, 0, At, B0); PG8_MMA(0, 1, At, B1); PG8_BAR; PG8_SCHED;
;             PG8_LDA(At, 0, 1); PG8_STAGE(PG8_SB(0, 0), b2, voffB); PG8_STAGE(PG8_SB(0, 1), b2 + hstep, voffB); PG8_STAGE(PG8_SA(0, 0), a2, voffA);
;             PG8_WAIT_V(8); PG8_WAIT_L(0); PG8_BAR; PG8_MMA(1, 0, At, B0); PG8_MMA(1, 1, At, B1); PG8_BAR; PG8_SCHED;
.LBB0_1013:
	ds_read_b128 v[148:151], v157
	ds_read_b128 v[152:155], v157 offset:1024
	ds_read_b128 v[160:163], v157 offset:2048
	ds_read_b128 v[168:171], v157 offset:3072
	ds_read_b128 v[172:175], v158
	ds_read_b128 v[176:179], v158 offset:1024
	ds_read_b128 v[180:183], v158 offset:2048
	ds_read_b128 v[184:187], v158 offset:3072
	s_add_i32 s79, s55, 2
	s_add_u32 s10, s56, 0xfff80080
	s_addc_u32 s11, s57, -1
	s_cmp_eq_u32 s9, s55
	s_cselect_b32 s61, s49, s11
	s_cselect_b32 s60, s48, s10
	s_cselect_b32 s59, s53, s51
	s_cselect_b32 s58, s52, s47
	v_lshl_add_u64 v[164:165], s[56:57], 0, v[138:139]
	s_add_i32 m0, s43, 0xc000
	ds_read_b128 v[188:191], v159
	ds_read_b128 v[192:195], v159 offset:1024
	ds_read_b128 v[196:199], v159 offset:2048
	ds_read_b128 v[200:203], v159 offset:3072
	ds_read_b128 v[204:207], v159 offset:4096
	ds_read_b128 v[208:211], v159 offset:5120
	ds_read_b128 v[212:215], v159 offset:6144
	ds_read_b128 v[216:219], v159 offset:7168
	global_load_lds_dwordx4 v[164:165], off
	v_lshl_add_u64 v[164:165], s[56:57], 0, v[142:143]
	s_add_i32 m0, s43, 0xe000
	s_nop 0
	global_load_lds_dwordx4 v[164:165], off
	s_waitcnt vmcnt(8)
	s_waitcnt lgkmcnt(0)
	s_barrier
	s_setprio 3
	s_waitcnt lgkmcnt(0)
	v_mfma_f32_16x16x32_bf16 v[126:129], v[148:151], v[188:191], v[126:129]
	v_mfma_f32_16x16x32_bf16 v[122:125], v[160:163], v[188:191], v[122:125]
	v_mfma_f32_16x16x32_bf16 v[114:117], v[148:151], v[196:199], v[114:117]
	v_mfma_f32_16x16x32_bf16 v[106:109], v[160:163], v[196:199], v[106:109]
	v_mfma_f32_16x16x32_bf16 v[98:101], v[148:151], v[204:207], v[98:101]
	v_mfma_f32_16x16x32_bf16 v[90:93], v[160:163], v[204:207], v[90:93]
	v_mfma_f32_16x16x32_bf16 v[82:85], v[148:151], v[212:215], v[82:85]
	v_mfma_f32_16x16x32_bf16 v[74:77], v[160:163], v[212:215], v[74:77]
	v_mfma_f32_16x16x32_bf16 v[126:129], v[152:155], v[192:195], v[126:129]
	v_mfma_f32_16x16x32_bf16 v[122:125], v[168:171], v[192:195], v[122:125]
	v_mfma_f32_16x16x32_bf16 v[114:117], v[152:155], v[200:203], v[114:117]
	v_mfma_f32_16x16x32_bf16 v[106:109], v[168:171], v[200:203], v[106:109]
	v_mfma_f32_16x16x32_bf16 v[98:101], v[152:155], v[208:211], v[98:101]
	v_mfma_f32_16x16x32_bf16 v[90:93], v[168:171], v[208:211], v[90:93]
	v_mfma_f32_16x16x32_bf16 v[82:85], v[152:155], v[216:219], v[82:85]
	v_mfma_f32_16x16x32_bf16 v[74:77], v[168:171], v[216:219], v[74:77]
	s_setprio 0
	s_setprio 3
	v_mfma_f32_16x16x32_bf16 v[118:121], v[172:175], v[188:191], v[118:121]
	v_mfma_f32_16x16x32_bf16 v[110:113], v[180:183], v[188:191], v[110:113]
	v_mfma_f32_16x16x32_bf16 v[102:105], v[172:175], v[196:199], v[102:105]
	v_mfma_f32_16x16x32_bf16 v[94:97], v[180:183], v[196:199], v[94:97]
	v_mfma_f32_16x16x32_bf16 v[86:89], v[172:175], v[204:207], v[86:89]
	v_mfma_f32_16x16x32_bf16 v[78:81], v[180:183], v[204:207], v[78:81]
	v_mfma_f32_16x16x32_bf16 v[70:73], v[172:175], v[212:215], v[70:73]
	v_mfma_f32_16x16x32_bf16 v[66:69], v[180:183], v[212:215], v[66:69]
	v_mfma_f32_16x16x32_bf16 v[118:121], v[176:179], v[192:195], v[118:121]
	v_mfma_f32_16x16x32_bf16 v[110:113], v[184:187], v[192:195], v[110:113]
	v_mfma_f32_16x16x32_bf16 v[102:105], v[176:179], v[200:203], v[102:105]
	v_mfma_f32_16x16x32_bf16 v[94:97], v[184:187], v[200:203], v[94:97]
	v_mfma_f32_16x16x32_bf16 v[86:89], v[176:179], v[208:211], v[86:89]
	v_mfma_f32_16x16x32_bf16 v[78:81], v[184:187], v[208:211], v[78:81]
	v_mfma_f32_16x16x32_bf16 v[70:73], v[176:179], v[216:219], v[70:73]
	s_setprio 0
	s_barrier
	v_mfma_f32_16x16x32_bf16 v[66:69], v[184:187], v[216:219], v[66:69]
	s_add_i32 s10, s72, s42
	v_lshl_add_u64 v[164:165], s[58:59], 0, v[132:133]
	s_mov_b32 m0, s10
	ds_read_b128 v[188:191], v159 offset:16384
	ds_read_b128 v[192:195], v159 offset:17408
	ds_read_b128 v[196:199], v159 offset:18432
	ds_read_b128 v[200:203], v159 offset:19456
	ds_read_b128 v[204:207], v159 offset:20480
	ds_read_b128 v[208:211], v159 offset:21504
	ds_read_b128 v[212:215], v159 offset:22528
	ds_read_b128 v[216:219], v159 offset:23552
	global_load_lds_dwordx4 v[164:165], off
	s_add_i32 m0, s10, 0x2000
	s_add_u32 s82, s58, 0x80000
	v_lshl_add_u64 v[220:221], s[58:59], 0, v[136:137]
	s_addc_u32 s83, s59, 0
	s_add_i32 s10, s73, s42
	global_load_lds_dwordx4 v[220:221], off
	v_lshl_add_u64 v[222:223], s[82:83], 0, v[132:133]
	s_mov_b32 m0, s10
	v_lshl_add_u64 v[224:225], s[60:61], 0, v[134:135]
	global_load_lds_dwordx4 v[222:223], off
	v_lshl_add_u64 v[222:223], s[82:83], 0, v[136:137]
	s_add_i32 m0, s10, 0x2000
	s_nop 0
	global_load_lds_dwordx4 v[222:223], off
	v_lshl_add_u64 v[222:223], s[60:61], 0, v[130:131]
	s_mov_b32 m0, s43
	s_nop 0
	global_load_lds_dwordx4 v[222:223], off
	s_mov_b32 m0, s62
	s_nop 0
	global_load_lds_dwordx4 v[224:225], off
	s_waitcnt vmcnt(8)
	s_waitcnt lgkmcnt(0)
	s_barrier
; #define PG8_STAGE(bufoff, gbase, voff) do { _Pragma("unroll") for (int _i = 0; _i < 2; ++_i) \
;         __builtin_amdgcn_global_load_lds((const unsigned*)((const char*)(gbase) + (voff)[_i]), (PG8_LAS unsigned*)(lds + (bufoff) + ldsw + _i * 8192), 16, 0, 0); } while (0)
; #define PG8_LDA(dst, b, h) do { _Pragma("unroll") for (int m = 0; m < 4; ++m) _Pragma("unroll") for (int k = 0; k < 2; ++k) dst[m][k] = *(const PG8_LAS bf16x8*)(lds + PG8_SA(b, h) + aoff + m * 2048 + k * 1024); } while (0)
; #define PG8_LDB(dst, b, h) do { _Pragma("unroll") for (int n = 0; n < 2; ++n) _Pragma("unroll") for (int k = 0; k < 2; ++k) dst[n][k] = *(const PG8_LAS bf16x8*)(lds + PG8_SB(b, h) + boff + n * 2048 + k * 1024); } while (0)
; #define PG8_MMA(ai, bj, At, Bt) do { __builtin_amdgcn_s_setprio(3); _Pragma("unroll") for (int m = 0; m < 4; ++m) _Pragma("unroll") for (int n = 0; n < 2; ++n) _Pragma("unroll") for (int k = 0; k < 2; ++k) \
;         acc[ai][bj][m][n] = __builtin_amdgcn_mfma_f32_16x16x32_bf16(Bt[n][k], At[m][k], acc[ai][bj][m][n], 0, 0, 0); __builtin_amdgcn_s_setprio(0); } while (0)
; #define PG8_WAIT_V(n) asm volatile("s_waitcnt vmcnt(" #n ")" ::: "memory")
; #define PG8_WAIT_L(n) asm volatile("s_waitcnt lgkmcnt(" #n ")" ::: "memory")
; #define PG8_BAR __builtin_amdgcn_s_barrier()
; #define PG8_SCHED __builtin_amdgcn_sched_barrier(0)
; template <class Epi, class Sched, bool ALIGN_EPI = false, bool SP2 = false>
; __device__ __forceinline__ void gemm_phase(PG8_LAS unsigned char* lds, const Gemm g, const Sched& S, const Epi& E) {
;     ...
;             PG8_WAIT_V(8); PG8_WAIT_L(0); PG8_BAR; PG8_MMA(1, 0, At, B0); PG8_MMA(1, 1, At, B1); PG8_BAR; PG8_SCHED;
;             PG8_LDB(B0, 1, 0); PG8_LDB(B1, 1, 1); PG8_SCHED; PG8_LDA(At, 1, 0); PG8_STAGE(PG8_SA(0, 1), a2 + hstep, voffA);
;             PG8_WAIT_V(8); PG8_WAIT_L(0); PG8_BAR; PG8_MMA(0, 0, At, B0); PG8_MMA(0, 1, At, B1); PG8_BAR; PG8_SCHED;
	s_setprio 3
	s_waitcnt lgkmcnt(0)
	v_mfma_f32_16x16x32_bf16 v[62:65], v[148:151], v[188:191], v[62:65]
	v_mfma_f32_16x16x32_bf16 v[58:61], v[160:163], v[188:191], v[58:61]
	v_mfma_f32_16x16x32_bf16 v[50:53], v[148:151], v[196:199], v[50:53]
	v_mfma_f32_16x16x32_bf16 v[42:45], v[160:163], v[196:199], v[42:45]
	v_mfma_f32_16x16x32_bf16 v[34:37], v[148:151], v[204:207], v[34:37]
	v_mfma_f32_16x16x32_bf16 v[26:29], v[160:163], v[204:207], v[26:29]
	v_mfma_f32_16x16x32_bf16 v[18:21], v[148:151], v[212:215], v[18:21]
	v_mfma_f32_16x16x32_bf16 v[10:13], v[160:163], v[212:215], v[10:13]
	v_mfma_f32_16x16x32_bf16 v[62:65], v[152:155], v[192:195], v[62:65]
	v_mfma_f32_16x16x32_bf16 v[58:61], v[168:171], v[192:195], v[58:61]
	v_mfma_f32_16x16x32_bf16 v[50:53], v[152:155], v[200:203], v[50:53]
	v_mfma_f32_16x16x32_bf16 v[42:45], v[168:171], v[200:203], v[42:45]
	v_mfma_f32_16x16x32_bf16 v[34:37], v[152:155], v[208:211], v[34:37]
	v_mfma_f32_16x16x32_bf16 v[26:29], v[168:171], v[208:211], v[26:29]
	v_mfma_f32_16x16x32_bf16 v[18:21], v[152:155], v[216:219], v[18:21]
	v_mfma_f32_16x16x32_bf16 v[10:13], v[168:171], v[216:219], v[10:13]
	s_setprio 0
	s_setprio 3
	v_mfma_f32_16x16x32_bf16 v[54:57], v[172:175], v[188:191], v[54:57]
	v_mfma_f32_16x16x32_bf16 v[46:49], v[180:183], v[188:191], v[46:49]
	v_mfma_f32_16x16x32_bf16 v[38:41], v[172:175], v[196:199], v[38:41]
	v_mfma_f32_16x16x32_bf16 v[30:33], v[180:183], v[196:199], v[30:33]
	v_mfma_f32_16x16x32_bf16 v[22:25], v[172:175], v[204:207], v[22:25]
	v_mfma_f32_16x16x32_bf16 v[14:17], v[180:183], v[204:207], v[14:17]
	v_mfma_f32_16x16x32_bf16 v[6:9], v[172:175], v[212:215], v[6:9]
	v_mfma_f32_16x16x32_bf16 v[2:5], v[180:183], v[212:215], v[2:5]
	v_mfma_f32_16x16x32_bf16 v[54:57], v[176:179], v[192:195], v[54:57]
	v_mfma_f32_16x16x32_bf16 v[46:49], v[184:187], v[192:195], v[46:49]
	v_mfma_f32_16x16x32_bf16 v[38:41], v[176:179], v[200:203], v[38:41]
	v_mfma_f32_16x16x32_bf16 v[30:33], v[184:187], v[200:203], v[30:33]
	v_mfma_f32_16x16x32_bf16 v[22:25], v[176:179], v[208:211], v[22:25]
	v_mfma_f32_16x16x32_bf16 v[14:17], v[184:187], v[208:211], v[14:17]
	v_mfma_f32_16x16x32_bf16 v[6:9], v[176:179], v[216:219], v[6:9]
	s_setprio 0
	s_barrier
	v_mfma_f32_16x16x32_bf16 v[2:5], v[184:187], v[216:219], v[2:5]
	s_add_i32 s10, 0, 0x18000
	v_add_u32_e32 v167, s10, v141
	s_add_i32 s11, 0, 0x1c000
	ds_read_b128 v[148:151], v167
	ds_read_b128 v[152:155], v167 offset:1024
	ds_read_b128 v[160:163], v167 offset:2048
	ds_read_b128 v[168:171], v167 offset:3072
	v_add_u32_e32 v167, s11, v141
	ds_read_b128 v[172:175], v167
	ds_read_b128 v[176:179], v167 offset:1024
	ds_read_b128 v[180:183], v167 offset:2048
	ds_read_b128 v[184:187], v167 offset:3072
	s_add_u32 s60, s60, 0x80000
	s_addc_u32 s61, s61, 0
	s_mov_b32 m0, s63
	v_lshl_add_u64 v[226:227], s[60:61], 0, v[130:131]
	ds_read_b128 v[188:191], v159 offset:32768
	ds_read_b128 v[192:195], v159 offset:33792
	ds_read_b128 v[196:199], v159 offset:34816
	ds_read_b128 v[200:203], v159 offset:35840
	ds_read_b128 v[204:207], v159 offset:36864
	ds_read_b128 v[208:211], v159 offset:37888
	ds_read_b128 v[212:215], v159 offset:38912
	ds_read_b128 v[216:219], v159 offset:39936
	global_load_lds_dwordx4 v[226:227], off
	v_lshl_add_u64 v[226:227], s[60:61], 0, v[134:135]
	s_mov_b32 m0, s64
	s_nop 0
	global_load_lds_dwordx4 v[226:227], off
	s_waitcnt vmcnt(8)
	s_waitcnt lgkmcnt(0)
	s_barrier
	s_setprio 3
	s_waitcnt lgkmcnt(0)
	v_mfma_f32_16x16x32_bf16 v[126:129], v[148:151], v[188:191], v[126:129]
	v_mfma_f32_16x16x32_bf16 v[122:125], v[160:163], v[188:191], v[122:125]
	v_mfma_f32_16x16x32_bf16 v[114:117], v[148:151], v[196:199], v[114:117]
	v_mfma_f32_16x16x32_bf16 v[106:109], v[160:163], v[196:199], v[106:109]
	v_mfma_f32_16x16x32_bf16 v[98:101], v[148:151], v[204:207], v[98:101]
	v_mfma_f32_16x16x32_bf16 v[90:93], v[160:163], v[204:207], v[90:93]
	v_mfma_f32_16x16x32_bf16 v[82:85], v[148:151], v[212:215], v[82:85]
	v_mfma_f32_16x16x32_bf16 v[74:77], v[160:163], v[212:215], v[74:77]
	v_mfma_f32_16x16x32_bf16 v[126:129], v[152:155], v[192:195], v[126:129]
	v_mfma_f32_16x16x32_bf16 v[122:125], v[168:171], v[192:195], v[122:125]
	v_mfma_f32_16x16x32_bf16 v[114:117], v[152:155], v[200:203], v[114:117]
	v_mfma_f32_16x16x32_bf16 v[106:109], v[168:171], v[200:203], v[106:109]
	v_mfma_f32_16x16x32_bf16 v[98:101], v[152:155], v[208:211], v[98:101]
	v_mfma_f32_16x16x32_bf16 v[90:93], v[168:171], v[208:211], v[90:93]
	v_mfma_f32_16x16x32_bf16 v[82:85], v[152:155], v[216:219], v[82:85]
	v_mfma_f32_16x16x32_bf16 v[74:77], v[168:171], v[216:219], v[74:77]
	s_setprio 0
	s_setprio 3
	v_mfma_f32_16x16x32_bf16 v[118:121], v[172:175], v[188:191], v[118:121]
	v_mfma_f32_16x16x32_bf16 v[110:113], v[180:183], v[188:191], v[110:113]
	v_mfma_f32_16x16x32_bf16 v[102:105], v[172:175], v[196:199], v[102:105]
	v_mfma_f32_16x16x32_bf16 v[94:97], v[180:183], v[196:199], v[94:97]
	v_mfma_f32_16x16x32_bf16 v[86:89], v[172:175], v[204:207], v[86:89]
	v_mfma_f32_16x16x32_bf16 v[78:81], v[180:183], v[204:207], v[78:81]
	v_mfma_f32_16x16x32_bf16 v[70:73], v[172:175], v[212:215], v[70:73]
	v_mfma_f32_16x16x32_bf16 v[66:69], v[180:183], v[212:215], v[66:69]
	v_mfma_f32_16x16x32_bf16 v[118:121], v[176:179], v[192:195], v[118:121]
	v_mfma_f32_16x16x32_bf16 v[110:113], v[184:187], v[192:195], v[110:113]
	v_mfma_f32_16x16x32_bf16 v[102:105], v[176:179], v[200:203], v[102:105]
	v_mfma_f32_16x16x32_bf16 v[94:97], v[184:187], v[200:203], v[94:97]
	v_mfma_f32_16x16x32_bf16 v[86:89], v[176:179], v[208:211], v[86:89]
	v_mfma_f32_16x16x32_bf16 v[78:81], v[184:187], v[208:211], v[78:81]
	v_mfma_f32_16x16x32_bf16 v[70:73], v[176:179], v[216:219], v[70:73]
	s_setprio 0
	s_barrier
; #define PG8_STAGE(bufoff, gbase, voff) do { _Pragma("unroll") for (int _i = 0; _i < 2; ++_i) \
;         __builtin_amdgcn_global_load_lds((const unsigned*)((const char*)(gbase) + (voff)[_i]), (PG8_LAS unsigned*)(lds + (bufoff) + ldsw + _i * 8192), 16, 0, 0); } while (0)
; #define PG8_LDA(dst, b, h) do { _Pragma("unroll") for (int m = 0; m < 4; ++m) _Pragma("unroll") for (int k = 0; k < 2; ++k) dst[m][k] = *(const PG8_LAS bf16x8*)(lds + PG8_SA(b, h) + aoff + m * 2048 + k * 1024); } while (0)
; #define PG8_MMA(ai, bj, At, Bt) do { __builtin_amdgcn_s_setprio(3); _Pragma("unroll") for (int m = 0; m < 4; ++m) _Pragma("unroll") for (int n = 0; n < 2; ++n) _Pragma("unroll") for (int k = 0; k < 2; ++k) \
;         acc[ai][bj][m][n] = __builtin_amdgcn_mfma_f32_16x16x32_bf16(Bt[n][k], At[m][k], acc[ai][bj][m][n], 0, 0, 0); __builtin_amdgcn_s_setprio(0); } while (0)
; #define PG8_WAIT_V(n) asm volatile("s_waitcnt vmcnt(" #n ")" ::: "memory")
; #define PG8_WAIT_L(n) asm volatile("s_waitcnt lgkmcnt(" #n ")" ::: "memory")
; #define PG8_BAR __builtin_amdgcn_s_barrier()
; #define PG8_SCHED __builtin_amdgcn_sched_barrier(0)
; template <class Epi, class Sched, bool ALIGN_EPI = false, bool SP2 = false>
; __device__ __forceinline__ void gemm_phase(PG8_LAS unsigned char* lds, const Gemm g, const Sched& S, const Epi& E) {
;     ...
;             PG8_WAIT_V(8); PG8_WAIT_L(0); PG8_BAR; PG8_MMA(0, 0, At, B0); PG8_MMA(0, 1, At, B1); PG8_BAR; PG8_SCHED;
;             PG8_LDA(At, 1, 1); PG8_STAGE(PG8_SB(1, 0), b3, voffB); PG8_STAGE(PG8_SB(1, 1), b3 + hstep, voffB); PG8_STAGE(PG8_SA(1, 0), a3, voffA);
;             PG8_WAIT_V(8); PG8_WAIT_L(0); PG8_BAR; PG8_MMA(1, 0, At, B0); PG8_MMA(1, 1, At, B1); PG8_BAR; PG8_SCHED;
;     ...
;         if constexpr (ALIGN_EPI) { if (wr == 0) PG8_BAR; }
	v_mfma_f32_16x16x32_bf16 v[66:69], v[184:187], v[216:219], v[66:69]
	s_add_i32 s10, s10, s42
	v_lshl_add_u64 v[164:165], v[164:165], 0, s[24:25]
	s_mov_b32 m0, s10
	ds_read_b128 v[188:191], v159 offset:49152
	ds_read_b128 v[192:195], v159 offset:50176
	ds_read_b128 v[196:199], v159 offset:51200
	ds_read_b128 v[200:203], v159 offset:52224
	ds_read_b128 v[204:207], v159 offset:53248
	ds_read_b128 v[208:211], v159 offset:54272
	ds_read_b128 v[212:215], v159 offset:55296
	ds_read_b128 v[216:219], v159 offset:56320
	global_load_lds_dwordx4 v[164:165], off
	s_add_i32 m0, s10, 0x2000
	s_add_u32 s58, s58, 0x80080
	v_lshl_add_u64 v[164:165], v[220:221], 0, s[24:25]
	s_addc_u32 s59, s59, 0
	s_add_i32 s10, s11, s42
	global_load_lds_dwordx4 v[164:165], off
	v_lshl_add_u64 v[164:165], s[58:59], 0, v[132:133]
	s_mov_b32 m0, s10
	s_nop 0
	global_load_lds_dwordx4 v[164:165], off
	v_lshl_add_u64 v[164:165], s[58:59], 0, v[136:137]
	s_add_i32 m0, s10, 0x2000
	s_nop 0
	global_load_lds_dwordx4 v[164:165], off
	v_lshl_add_u64 v[164:165], v[222:223], 0, s[24:25]
	s_mov_b32 m0, s69
	s_nop 0
	global_load_lds_dwordx4 v[164:165], off
	v_lshl_add_u64 v[164:165], v[224:225], 0, s[24:25]
	s_mov_b32 m0, s70
	s_nop 0
	global_load_lds_dwordx4 v[164:165], off
	s_waitcnt vmcnt(8)
	s_waitcnt lgkmcnt(0)
	s_barrier
	s_setprio 3
	s_waitcnt lgkmcnt(0)
	v_mfma_f32_16x16x32_bf16 v[62:65], v[148:151], v[188:191], v[62:65]
	v_mfma_f32_16x16x32_bf16 v[58:61], v[160:163], v[188:191], v[58:61]
	v_mfma_f32_16x16x32_bf16 v[50:53], v[148:151], v[196:199], v[50:53]
	v_mfma_f32_16x16x32_bf16 v[42:45], v[160:163], v[196:199], v[42:45]
	v_mfma_f32_16x16x32_bf16 v[34:37], v[148:151], v[204:207], v[34:37]
	v_mfma_f32_16x16x32_bf16 v[26:29], v[160:163], v[204:207], v[26:29]
	v_mfma_f32_16x16x32_bf16 v[18:21], v[148:151], v[212:215], v[18:21]
	v_mfma_f32_16x16x32_bf16 v[10:13], v[160:163], v[212:215], v[10:13]
	v_mfma_f32_16x16x32_bf16 v[62:65], v[152:155], v[192:195], v[62:65]
	v_mfma_f32_16x16x32_bf16 v[58:61], v[168:171], v[192:195], v[58:61]
	v_mfma_f32_16x16x32_bf16 v[50:53], v[152:155], v[200:203], v[50:53]
	v_mfma_f32_16x16x32_bf16 v[42:45], v[168:171], v[200:203], v[42:45]
	v_mfma_f32_16x16x32_bf16 v[34:37], v[152:155], v[208:211], v[34:37]
	v_mfma_f32_16x16x32_bf16 v[26:29], v[168:171], v[208:211], v[26:29]
	v_mfma_f32_16x16x32_bf16 v[18:21], v[152:155], v[216:219], v[18:21]
	v_mfma_f32_16x16x32_bf16 v[10:13], v[168:171], v[216:219], v[10:13]
	s_setprio 0
	s_setprio 3
	v_mfma_f32_16x16x32_bf16 v[54:57], v[172:175], v[188:191], v[54:57]
	v_mfma_f32_16x16x32_bf16 v[46:49], v[180:183], v[188:191], v[46:49]
	v_mfma_f32_16x16x32_bf16 v[38:41], v[172:175], v[196:199], v[38:41]
	v_mfma_f32_16x16x32_bf16 v[30:33], v[180:183], v[196:199], v[30:33]
	v_mfma_f32_16x16x32_bf16 v[22:25], v[172:175], v[204:207], v[22:25]
	v_mfma_f32_16x16x32_bf16 v[14:17], v[180:183], v[204:207], v[14:17]
	v_mfma_f32_16x16x32_bf16 v[6:9], v[172:175], v[212:215], v[6:9]
	v_mfma_f32_16x16x32_bf16 v[2:5], v[180:183], v[212:215], v[2:5]
	v_mfma_f32_16x16x32_bf16 v[54:57], v[176:179], v[192:195], v[54:57]
	v_mfma_f32_16x16x32_bf16 v[46:49], v[184:187], v[192:195], v[46:49]
	v_mfma_f32_16x16x32_bf16 v[38:41], v[176:179], v[200:203], v[38:41]
	v_mfma_f32_16x16x32_bf16 v[30:33], v[184:187], v[200:203], v[30:33]
	v_mfma_f32_16x16x32_bf16 v[22:25], v[176:179], v[208:211], v[22:25]
	v_mfma_f32_16x16x32_bf16 v[14:17], v[184:187], v[208:211], v[14:17]
	v_mfma_f32_16x16x32_bf16 v[6:9], v[176:179], v[216:219], v[6:9]
	s_setprio 0
	s_barrier
	v_mfma_f32_16x16x32_bf16 v[2:5], v[184:187], v[216:219], v[2:5]
	s_add_u32 s56, s56, 0x100
	s_addc_u32 s57, s57, 0
	s_add_u32 s47, s47, 0x100
	s_addc_u32 s51, s51, 0
	s_cmp_ge_u32 s79, s78
	s_mov_b32 s55, s79
	s_cbranch_scc0 .LBB0_1013
	s_and_b64 vcc, exec, s[26:27]
	s_cbranch_vccz .LBB0_1016
	s_barrier

; #define PG8_STAGE(bufoff, gbase, voff) do { _Pragma("unroll") for (int _i = 0; _i < 2; ++_i) \
;         __builtin_amdgcn_global_load_lds((const unsigned*)((const char*)(gbase) + (voff)[_i]), (PG8_LAS unsigned*)(lds + (bufoff) + ldsw + _i * 8192), 16, 0, 0); } while (0)
; #define PG8_LDA(dst, b, h) do { _Pragma("unroll") for (int m = 0; m < 4; ++m) _Pragma("unroll") for (int k = 0; k < 2; ++k) dst[m][k] = *(const PG8_LAS bf16x8*)(lds + PG8_SA(b, h) + aoff + m * 2048 + k * 1024); } while (0)
; #define PG8_LDB(dst, b, h) do { _Pragma("unroll") for (int n = 0; n < 2; ++n) _Pragma("unroll") for (int k = 0; k < 2; ++k) dst[n][k] = *(const PG8_LAS bf16x8*)(lds + PG8_SB(b, h) + boff + n * 2048 + k * 1024); } while (0)
; #define PG8_MMA(ai, bj, At, Bt) do { __builtin_amdgcn_s_setprio(3); _Pragma("unroll") for (int m = 0; m < 4; ++m) _Pragma("unroll") for (int n = 0; n < 2; ++n) _Pragma("unroll") for (int k = 0; k < 2; ++k) \
;         acc[ai][bj][m][n] = __builtin_amdgcn_mfma_f32_16x16x32_bf16(Bt[n][k], At[m][k], acc[ai][bj][m][n], 0, 0, 0); __builtin_amdgcn_s_setprio(0); } while (0)
; #define PG8_WAIT_V(n) asm volatile("s_waitcnt vmcnt(" #n ")" ::: "memory")
; #define PG8_BAR __builtin_amdgcn_s_barrier()
; template <class Epi, class Sched, bool ALIGN_EPI = false, bool SP2 = false>
; __device__ __forceinline__ void gemm_phase(PG8_LAS unsigned char* lds, const Gemm g, const Sched& S, const Epi& E) {
;     ...
;         for (int t = 0; t < nt; t += 2) {
;             const bool last = (t == nt - 2);
;             const char* a1 = cA + (size_t)(t + 1) * kstep;
;             const char* a2 = last ? nA : cA + (size_t)(t + 2) * kstep; const char* b2 = last ? nB : cB + (size_t)(t + 2) * kstep;
;             const char* a3 = a2 + kstep; const char* b3 = b2 + kstep;
;             if (last && has_next) S.a_ready(nxt);
;             if constexpr (SP2) {
;             PG8_LDB(B0, 0, 0); PG8_LDB(B1, 0, 1); PG8_SCHED; PG8_LDA(At, 0, 0); PG8_STAGE(PG8_SA(1, 1), a1 + hstep, voffA);
;             PG8_WAIT_V(8); PG8_WAIT_L(0); PG8_BAR; PG8_MMA(0, 0, At, B0); PG8_MMA(0, 1, At, B1); PG8_BAR; PG8_SCHED;
;             PG8_LDA(At, 0, 1); PG8_STAGE(PG8_SB(0, 0), b2, voffB); PG8_STAGE(PG8_SB(0, 1), b2 + hstep, voffB); PG8_STAGE(PG8_SA(0, 0), a2, voffA);
;             PG8_WAIT_V(8); PG8_WAIT_L(0); PG8_BAR; PG8_MMA(1, 0, At, B0); PG8_MMA(1, 1, At, B1); PG8_BAR; PG8_SCHED;
.LBB0_1218:
	ds_read_b128 v[148:151], v153
	ds_read_b128 v[156:159], v153 offset:1024
	ds_read_b128 v[160:163], v153 offset:2048
	ds_read_b128 v[168:171], v153 offset:3072
	ds_read_b128 v[172:175], v154
	ds_read_b128 v[176:179], v154 offset:1024
	ds_read_b128 v[180:183], v154 offset:2048
	ds_read_b128 v[184:187], v154 offset:3072
	s_add_u32 s10, s46, 0xfff80080
	s_addc_u32 s11, s47, -1
	s_cmp_eq_u32 s66, 28
	s_cselect_b32 s51, s27, s11
	s_cselect_b32 s50, s62, s10
	s_cselect_b32 s49, s25, s65
	s_cselect_b32 s48, s63, s64
	v_lshl_add_u64 v[164:165], s[46:47], 0, v[138:139]
	s_add_i32 m0, s42, 0xc000
	ds_read_b128 v[188:191], v155
	ds_read_b128 v[192:195], v155 offset:1024
	ds_read_b128 v[196:199], v155 offset:2048
	ds_read_b128 v[200:203], v155 offset:3072
	ds_read_b128 v[204:207], v155 offset:4096
	ds_read_b128 v[208:211], v155 offset:5120
	ds_read_b128 v[212:215], v155 offset:6144
	ds_read_b128 v[216:219], v155 offset:7168
	global_load_lds_dwordx4 v[164:165], off
	v_lshl_add_u64 v[164:165], s[46:47], 0, v[142:143]
	s_add_i32 m0, s42, 0xe000
	s_nop 0
	global_load_lds_dwordx4 v[164:165], off
	s_waitcnt vmcnt(8)
	s_waitcnt lgkmcnt(0)
	s_barrier
	s_setprio 3
	s_waitcnt lgkmcnt(0)
	v_mfma_f32_16x16x32_bf16 v[126:129], v[148:151], v[188:191], v[126:129]
	v_mfma_f32_16x16x32_bf16 v[118:121], v[160:163], v[188:191], v[118:121]
	v_mfma_f32_16x16x32_bf16 v[110:113], v[148:151], v[196:199], v[110:113]
	v_mfma_f32_16x16x32_bf16 v[102:105], v[160:163], v[196:199], v[102:105]
	v_mfma_f32_16x16x32_bf16 v[94:97], v[148:151], v[204:207], v[94:97]
	v_mfma_f32_16x16x32_bf16 v[86:89], v[160:163], v[204:207], v[86:89]
	v_mfma_f32_16x16x32_bf16 v[78:81], v[148:151], v[212:215], v[78:81]
	v_mfma_f32_16x16x32_bf16 v[70:73], v[160:163], v[212:215], v[70:73]
	v_mfma_f32_16x16x32_bf16 v[126:129], v[156:159], v[192:195], v[126:129]
	v_mfma_f32_16x16x32_bf16 v[118:121], v[168:171], v[192:195], v[118:121]
	v_mfma_f32_16x16x32_bf16 v[110:113], v[156:159], v[200:203], v[110:113]
	v_mfma_f32_16x16x32_bf16 v[102:105], v[168:171], v[200:203], v[102:105]
	v_mfma_f32_16x16x32_bf16 v[94:97], v[156:159], v[208:211], v[94:97]
	v_mfma_f32_16x16x32_bf16 v[86:89], v[168:171], v[208:211], v[86:89]
	v_mfma_f32_16x16x32_bf16 v[78:81], v[156:159], v[216:219], v[78:81]
	v_mfma_f32_16x16x32_bf16 v[70:73], v[168:171], v[216:219], v[70:73]
	s_setprio 0
	s_setprio 3
	v_mfma_f32_16x16x32_bf16 v[122:125], v[172:175], v[188:191], v[122:125]
	v_mfma_f32_16x16x32_bf16 v[114:117], v[180:183], v[188:191], v[114:117]
	v_mfma_f32_16x16x32_bf16 v[106:109], v[172:175], v[196:199], v[106:109]
	v_mfma_f32_16x16x32_bf16 v[98:101], v[180:183], v[196:199], v[98:101]
	v_mfma_f32_16x16x32_bf16 v[90:93], v[172:175], v[204:207], v[90:93]
	v_mfma_f32_16x16x32_bf16 v[82:85], v[180:183], v[204:207], v[82:85]
	v_mfma_f32_16x16x32_bf16 v[74:77], v[172:175], v[212:215], v[74:77]
	v_mfma_f32_16x16x32_bf16 v[66:69], v[180:183], v[212:215], v[66:69]
	v_mfma_f32_16x16x32_bf16 v[122:125], v[176:179], v[192:195], v[122:125]
	v_mfma_f32_16x16x32_bf16 v[114:117], v[184:187], v[192:195], v[114:117]
	v_mfma_f32_16x16x32_bf16 v[106:109], v[176:179], v[200:203], v[106:109]
	v_mfma_f32_16x16x32_bf16 v[98:101], v[184:187], v[200:203], v[98:101]
	v_mfma_f32_16x16x32_bf16 v[90:93], v[176:179], v[208:211], v[90:93]
	v_mfma_f32_16x16x32_bf16 v[82:85], v[184:187], v[208:211], v[82:85]
	v_mfma_f32_16x16x32_bf16 v[74:77], v[176:179], v[216:219], v[74:77]
	s_setprio 0
	s_barrier
	v_mfma_f32_16x16x32_bf16 v[66:69], v[184:187], v[216:219], v[66:69]
	s_add_i32 s10, s58, s35
	v_lshl_add_u64 v[164:165], s[48:49], 0, v[132:133]
	s_mov_b32 m0, s10
	ds_read_b128 v[188:191], v155 offset:16384
	ds_read_b128 v[192:195], v155 offset:17408
	ds_read_b128 v[196:199], v155 offset:18432
	ds_read_b128 v[200:203], v155 offset:19456
	ds_read_b128 v[204:207], v155 offset:20480
	ds_read_b128 v[208:211], v155 offset:21504
	ds_read_b128 v[212:215], v155 offset:22528
	ds_read_b128 v[216:219], v155 offset:23552
	global_load_lds_dwordx4 v[164:165], off
	s_add_i32 m0, s10, 0x2000
	s_add_u32 s68, s48, 0x80000
	v_lshl_add_u64 v[220:221], s[48:49], 0, v[136:137]
	s_addc_u32 s69, s49, 0
	s_add_i32 s10, s59, s35
	global_load_lds_dwordx4 v[220:221], off
	v_lshl_add_u64 v[222:223], s[68:69], 0, v[132:133]
	s_mov_b32 m0, s10
	v_lshl_add_u64 v[224:225], s[50:51], 0, v[134:135]
	global_load_lds_dwordx4 v[222:223], off
	v_lshl_add_u64 v[222:223], s[68:69], 0, v[136:137]
	s_add_i32 m0, s10, 0x2000
	s_nop 0
	global_load_lds_dwordx4 v[222:223], off
	v_lshl_add_u64 v[222:223], s[50:51], 0, v[130:131]
	s_mov_b32 m0, s42
	s_nop 0
	global_load_lds_dwordx4 v[222:223], off
	s_mov_b32 m0, s43
	s_nop 0
	global_load_lds_dwordx4 v[224:225], off
	s_waitcnt vmcnt(8)
	s_waitcnt lgkmcnt(0)
	s_barrier
; #define PG8_STAGE(bufoff, gbase, voff) do { _Pragma("unroll") for (int _i = 0; _i < 2; ++_i) \
;         __builtin_amdgcn_global_load_lds((const unsigned*)((const char*)(gbase) + (voff)[_i]), (PG8_LAS unsigned*)(lds + (bufoff) + ldsw + _i * 8192), 16, 0, 0); } while (0)
; #define PG8_LDA(dst, b, h) do { _Pragma("unroll") for (int m = 0; m < 4; ++m) _Pragma("unroll") for (int k = 0; k < 2; ++k) dst[m][k] = *(const PG8_LAS bf16x8*)(lds + PG8_SA(b, h) + aoff + m * 2048 + k * 1024); } while (0)
; #define PG8_LDB(dst, b, h) do { _Pragma("unroll") for (int n = 0; n < 2; ++n) _Pragma("unroll") for (int k = 0; k < 2; ++k) dst[n][k] = *(const PG8_LAS bf16x8*)(lds + PG8_SB(b, h) + boff + n * 2048 + k * 1024); } while (0)
; #define PG8_MMA(ai, bj, At, Bt) do { __builtin_amdgcn_s_setprio(3); _Pragma("unroll") for (int m = 0; m < 4; ++m) _Pragma("unroll") for (int n = 0; n < 2; ++n) _Pragma("unroll") for (int k = 0; k < 2; ++k) \
;         acc[ai][bj][m][n] = __builtin_amdgcn_mfma_f32_16x16x32_bf16(Bt[n][k], At[m][k], acc[ai][bj][m][n], 0, 0, 0); __builtin_amdgcn_s_setprio(0); } while (0)
; #define PG8_WAIT_V(n) asm volatile("s_waitcnt vmcnt(" #n ")" ::: "memory")
; #define PG8_WAIT_L(n) asm volatile("s_waitcnt lgkmcnt(" #n ")" ::: "memory")
; #define PG8_BAR __builtin_amdgcn_s_barrier()
; #define PG8_SCHED __builtin_amdgcn_sched_barrier(0)
; template <class Epi, class Sched, bool ALIGN_EPI = false, bool SP2 = false>
; __device__ __forceinline__ void gemm_phase(PG8_LAS unsigned char* lds, const Gemm g, const Sched& S, const Epi& E) {
;     ...
;             PG8_WAIT_V(8); PG8_WAIT_L(0); PG8_BAR; PG8_MMA(1, 0, At, B0); PG8_MMA(1, 1, At, B1); PG8_BAR; PG8_SCHED;
;             PG8_LDB(B0, 1, 0); PG8_LDB(B1, 1, 1); PG8_SCHED; PG8_LDA(At, 1, 0); PG8_STAGE(PG8_SA(0, 1), a2 + hstep, voffA);
;             PG8_WAIT_V(8); PG8_WAIT_L(0); PG8_BAR; PG8_MMA(0, 0, At, B0); PG8_MMA(0, 1, At, B1); PG8_BAR; PG8_SCHED;
	s_setprio 3
	s_waitcnt lgkmcnt(0)
	v_mfma_f32_16x16x32_bf16 v[62:65], v[148:151], v[188:191], v[62:65]
	v_mfma_f32_16x16x32_bf16 v[54:57], v[160:163], v[188:191], v[54:57]
	v_mfma_f32_16x16x32_bf16 v[46:49], v[148:151], v[196:199], v[46:49]
	v_mfma_f32_16x16x32_bf16 v[38:41], v[160:163], v[196:199], v[38:41]
	v_mfma_f32_16x16x32_bf16 v[30:33], v[148:151], v[204:207], v[30:33]
	v_mfma_f32_16x16x32_bf16 v[22:25], v[160:163], v[204:207], v[22:25]
	v_mfma_f32_16x16x32_bf16 v[14:17], v[148:151], v[212:215], v[14:17]
	v_mfma_f32_16x16x32_bf16 v[6:9], v[160:163], v[212:215], v[6:9]
	v_mfma_f32_16x16x32_bf16 v[62:65], v[156:159], v[192:195], v[62:65]
	v_mfma_f32_16x16x32_bf16 v[54:57], v[168:171], v[192:195], v[54:57]
	v_mfma_f32_16x16x32_bf16 v[46:49], v[156:159], v[200:203], v[46:49]
	v_mfma_f32_16x16x32_bf16 v[38:41], v[168:171], v[200:203], v[38:41]
	v_mfma_f32_16x16x32_bf16 v[30:33], v[156:159], v[208:211], v[30:33]
	v_mfma_f32_16x16x32_bf16 v[22:25], v[168:171], v[208:211], v[22:25]
	v_mfma_f32_16x16x32_bf16 v[14:17], v[156:159], v[216:219], v[14:17]
	v_mfma_f32_16x16x32_bf16 v[6:9], v[168:171], v[216:219], v[6:9]
	s_setprio 0
	s_setprio 3
	v_mfma_f32_16x16x32_bf16 v[58:61], v[172:175], v[188:191], v[58:61]
	v_mfma_f32_16x16x32_bf16 v[50:53], v[180:183], v[188:191], v[50:53]
	v_mfma_f32_16x16x32_bf16 v[42:45], v[172:175], v[196:199], v[42:45]
	v_mfma_f32_16x16x32_bf16 v[34:37], v[180:183], v[196:199], v[34:37]
	v_mfma_f32_16x16x32_bf16 v[26:29], v[172:175], v[204:207], v[26:29]
	v_mfma_f32_16x16x32_bf16 v[18:21], v[180:183], v[204:207], v[18:21]
	v_mfma_f32_16x16x32_bf16 v[10:13], v[172:175], v[212:215], v[10:13]
	v_mfma_f32_16x16x32_bf16 v[2:5], v[180:183], v[212:215], v[2:5]
	v_mfma_f32_16x16x32_bf16 v[58:61], v[176:179], v[192:195], v[58:61]
	v_mfma_f32_16x16x32_bf16 v[50:53], v[184:187], v[192:195], v[50:53]
	v_mfma_f32_16x16x32_bf16 v[42:45], v[176:179], v[200:203], v[42:45]
	v_mfma_f32_16x16x32_bf16 v[34:37], v[184:187], v[200:203], v[34:37]
	v_mfma_f32_16x16x32_bf16 v[26:29], v[176:179], v[208:211], v[26:29]
	v_mfma_f32_16x16x32_bf16 v[18:21], v[184:187], v[208:211], v[18:21]
	v_mfma_f32_16x16x32_bf16 v[10:13], v[176:179], v[216:219], v[10:13]
	s_setprio 0
	s_barrier
	v_mfma_f32_16x16x32_bf16 v[2:5], v[184:187], v[216:219], v[2:5]
	s_add_i32 s10, 0, 0x18000
	v_add_u32_e32 v167, s10, v141
	s_add_i32 s11, 0, 0x1c000
	ds_read_b128 v[148:151], v167
	ds_read_b128 v[156:159], v167 offset:1024
	ds_read_b128 v[160:163], v167 offset:2048
	ds_read_b128 v[168:171], v167 offset:3072
	v_add_u32_e32 v167, s11, v141
	ds_read_b128 v[172:175], v167
	ds_read_b128 v[176:179], v167 offset:1024
	ds_read_b128 v[180:183], v167 offset:2048
	ds_read_b128 v[184:187], v167 offset:3072
	s_add_u32 s50, s50, 0x80000
	s_addc_u32 s51, s51, 0
	s_mov_b32 m0, s45
	v_lshl_add_u64 v[226:227], s[50:51], 0, v[130:131]
	ds_read_b128 v[188:191], v155 offset:32768
	ds_read_b128 v[192:195], v155 offset:33792
	ds_read_b128 v[196:199], v155 offset:34816
	ds_read_b128 v[200:203], v155 offset:35840
	ds_read_b128 v[204:207], v155 offset:36864
	ds_read_b128 v[208:211], v155 offset:37888
	ds_read_b128 v[212:215], v155 offset:38912
	ds_read_b128 v[216:219], v155 offset:39936
	global_load_lds_dwordx4 v[226:227], off
	v_lshl_add_u64 v[226:227], s[50:51], 0, v[134:135]
	s_mov_b32 m0, s52
	s_nop 0
	global_load_lds_dwordx4 v[226:227], off
	s_waitcnt vmcnt(8)
	s_waitcnt lgkmcnt(0)
	s_barrier
	s_setprio 3
	s_waitcnt lgkmcnt(0)
	v_mfma_f32_16x16x32_bf16 v[126:129], v[148:151], v[188:191], v[126:129]
	v_mfma_f32_16x16x32_bf16 v[118:121], v[160:163], v[188:191], v[118:121]
	v_mfma_f32_16x16x32_bf16 v[110:113], v[148:151], v[196:199], v[110:113]
	v_mfma_f32_16x16x32_bf16 v[102:105], v[160:163], v[196:199], v[102:105]
	v_mfma_f32_16x16x32_bf16 v[94:97], v[148:151], v[204:207], v[94:97]
	v_mfma_f32_16x16x32_bf16 v[86:89], v[160:163], v[204:207], v[86:89]
	v_mfma_f32_16x16x32_bf16 v[78:81], v[148:151], v[212:215], v[78:81]
	v_mfma_f32_16x16x32_bf16 v[70:73], v[160:163], v[212:215], v[70:73]
	v_mfma_f32_16x16x32_bf16 v[126:129], v[156:159], v[192:195], v[126:129]
	v_mfma_f32_16x16x32_bf16 v[118:121], v[168:171], v[192:195], v[118:121]
	v_mfma_f32_16x16x32_bf16 v[110:113], v[156:159], v[200:203], v[110:113]
	v_mfma_f32_16x16x32_bf16 v[102:105], v[168:171], v[200:203], v[102:105]
	v_mfma_f32_16x16x32_bf16 v[94:97], v[156:159], v[208:211], v[94:97]
	v_mfma_f32_16x16x32_bf16 v[86:89], v[168:171], v[208:211], v[86:89]
	v_mfma_f32_16x16x32_bf16 v[78:81], v[156:159], v[216:219], v[78:81]
	v_mfma_f32_16x16x32_bf16 v[70:73], v[168:171], v[216:219], v[70:73]
	s_setprio 0
	s_setprio 3
	v_mfma_f32_16x16x32_bf16 v[122:125], v[172:175], v[188:191], v[122:125]
	v_mfma_f32_16x16x32_bf16 v[114:117], v[180:183], v[188:191], v[114:117]
	v_mfma_f32_16x16x32_bf16 v[106:109], v[172:175], v[196:199], v[106:109]
	v_mfma_f32_16x16x32_bf16 v[98:101], v[180:183], v[196:199], v[98:101]
	v_mfma_f32_16x16x32_bf16 v[90:93], v[172:175], v[204:207], v[90:93]
	v_mfma_f32_16x16x32_bf16 v[82:85], v[180:183], v[204:207], v[82:85]
	v_mfma_f32_16x16x32_bf16 v[74:77], v[172:175], v[212:215], v[74:77]
	v_mfma_f32_16x16x32_bf16 v[66:69], v[180:183], v[212:215], v[66:69]
	v_mfma_f32_16x16x32_bf16 v[122:125], v[176:179], v[192:195], v[122:125]
	v_mfma_f32_16x16x32_bf16 v[114:117], v[184:187], v[192:195], v[114:117]
	v_mfma_f32_16x16x32_bf16 v[106:109], v[176:179], v[200:203], v[106:109]
	v_mfma_f32_16x16x32_bf16 v[98:101], v[184:187], v[200:203], v[98:101]
	v_mfma_f32_16x16x32_bf16 v[90:93], v[176:179], v[208:211], v[90:93]
	v_mfma_f32_16x16x32_bf16 v[82:85], v[184:187], v[208:211], v[82:85]
	v_mfma_f32_16x16x32_bf16 v[74:77], v[176:179], v[216:219], v[74:77]
	s_setprio 0
	s_barrier
; #define PG8_STAGE(bufoff, gbase, voff) do { _Pragma("unroll") for (int _i = 0; _i < 2; ++_i) \
;         __builtin_amdgcn_global_load_lds((const unsigned*)((const char*)(gbase) + (voff)[_i]), (PG8_LAS unsigned*)(lds + (bufoff) + ldsw + _i * 8192), 16, 0, 0); } while (0)
; #define PG8_LDA(dst, b, h) do { _Pragma("unroll") for (int m = 0; m < 4; ++m) _Pragma("unroll") for (int k = 0; k < 2; ++k) dst[m][k] = *(const PG8_LAS bf16x8*)(lds + PG8_SA(b, h) + aoff + m * 2048 + k * 1024); } while (0)
; #define PG8_MMA(ai, bj, At, Bt) do { __builtin_amdgcn_s_setprio(3); _Pragma("unroll") for (int m = 0; m < 4; ++m) _Pragma("unroll") for (int n = 0; n < 2; ++n) _Pragma("unroll") for (int k = 0; k < 2; ++k) \
;         acc[ai][bj][m][n] = __builtin_amdgcn_mfma_f32_16x16x32_bf16(Bt[n][k], At[m][k], acc[ai][bj][m][n], 0, 0, 0); __builtin_amdgcn_s_setprio(0); } while (0)
; #define PG8_WAIT_V(n) asm volatile("s_waitcnt vmcnt(" #n ")" ::: "memory")
; #define PG8_WAIT_L(n) asm volatile("s_waitcnt lgkmcnt(" #n ")" ::: "memory")
; #define PG8_BAR __builtin_amdgcn_s_barrier()
; #define PG8_SCHED __builtin_amdgcn_sched_barrier(0)
; template <class Epi, class Sched, bool ALIGN_EPI = false, bool SP2 = false>
; __device__ __forceinline__ void gemm_phase(PG8_LAS unsigned char* lds, const Gemm g, const Sched& S, const Epi& E) {
;     ...
;             PG8_WAIT_V(8); PG8_WAIT_L(0); PG8_BAR; PG8_MMA(0, 0, At, B0); PG8_MMA(0, 1, At, B1); PG8_BAR; PG8_SCHED;
;             PG8_LDA(At, 1, 1); PG8_STAGE(PG8_SB(1, 0), b3, voffB); PG8_STAGE(PG8_SB(1, 1), b3 + hstep, voffB); PG8_STAGE(PG8_SA(1, 0), a3, voffA);
;             PG8_WAIT_V(8); PG8_WAIT_L(0); PG8_BAR; PG8_MMA(1, 0, At, B0); PG8_MMA(1, 1, At, B1); PG8_BAR; PG8_SCHED;
;     ...
;         if constexpr (ALIGN_EPI) { if (wr == 0) PG8_BAR; }
	v_mfma_f32_16x16x32_bf16 v[66:69], v[184:187], v[216:219], v[66:69]
	s_add_i32 s10, s10, s35
	v_lshl_add_u64 v[164:165], v[164:165], 0, s[16:17]
	s_mov_b32 m0, s10
	ds_read_b128 v[188:191], v155 offset:49152
	ds_read_b128 v[192:195], v155 offset:50176
	ds_read_b128 v[196:199], v155 offset:51200
	ds_read_b128 v[200:203], v155 offset:52224
	ds_read_b128 v[204:207], v155 offset:53248
	ds_read_b128 v[208:211], v155 offset:54272
	ds_read_b128 v[212:215], v155 offset:55296
	ds_read_b128 v[216:219], v155 offset:56320
	global_load_lds_dwordx4 v[164:165], off
	s_add_i32 m0, s10, 0x2000
	s_add_u32 s48, s48, 0x80080
	v_lshl_add_u64 v[164:165], v[220:221], 0, s[16:17]
	s_addc_u32 s49, s49, 0
	s_add_i32 s10, s11, s35
	global_load_lds_dwordx4 v[164:165], off
	v_lshl_add_u64 v[164:165], s[48:49], 0, v[132:133]
	s_mov_b32 m0, s10
	s_nop 0
	global_load_lds_dwordx4 v[164:165], off
	v_lshl_add_u64 v[164:165], s[48:49], 0, v[136:137]
	s_add_i32 m0, s10, 0x2000
	s_nop 0
	global_load_lds_dwordx4 v[164:165], off
	v_lshl_add_u64 v[164:165], v[222:223], 0, s[16:17]
	s_mov_b32 m0, s55
	s_nop 0
	global_load_lds_dwordx4 v[164:165], off
	v_lshl_add_u64 v[164:165], v[224:225], 0, s[16:17]
	s_mov_b32 m0, s56
	s_nop 0
	global_load_lds_dwordx4 v[164:165], off
	s_waitcnt vmcnt(8)
	s_waitcnt lgkmcnt(0)
	s_barrier
	s_setprio 3
	s_waitcnt lgkmcnt(0)
	v_mfma_f32_16x16x32_bf16 v[62:65], v[148:151], v[188:191], v[62:65]
	v_mfma_f32_16x16x32_bf16 v[54:57], v[160:163], v[188:191], v[54:57]
	v_mfma_f32_16x16x32_bf16 v[46:49], v[148:151], v[196:199], v[46:49]
	v_mfma_f32_16x16x32_bf16 v[38:41], v[160:163], v[196:199], v[38:41]
	v_mfma_f32_16x16x32_bf16 v[30:33], v[148:151], v[204:207], v[30:33]
	v_mfma_f32_16x16x32_bf16 v[22:25], v[160:163], v[204:207], v[22:25]
	v_mfma_f32_16x16x32_bf16 v[14:17], v[148:151], v[212:215], v[14:17]
	v_mfma_f32_16x16x32_bf16 v[6:9], v[160:163], v[212:215], v[6:9]
	v_mfma_f32_16x16x32_bf16 v[62:65], v[156:159], v[192:195], v[62:65]
	v_mfma_f32_16x16x32_bf16 v[54:57], v[168:171], v[192:195], v[54:57]
	v_mfma_f32_16x16x32_bf16 v[46:49], v[156:159], v[200:203], v[46:49]
	v_mfma_f32_16x16x32_bf16 v[38:41], v[168:171], v[200:203], v[38:41]
	v_mfma_f32_16x16x32_bf16 v[30:33], v[156:159], v[208:211], v[30:33]
	v_mfma_f32_16x16x32_bf16 v[22:25], v[168:171], v[208:211], v[22:25]
	v_mfma_f32_16x16x32_bf16 v[14:17], v[156:159], v[216:219], v[14:17]
	v_mfma_f32_16x16x32_bf16 v[6:9], v[168:171], v[216:219], v[6:9]
	s_setprio 0
	s_setprio 3
	v_mfma_f32_16x16x32_bf16 v[58:61], v[172:175], v[188:191], v[58:61]
	v_mfma_f32_16x16x32_bf16 v[50:53], v[180:183], v[188:191], v[50:53]
	v_mfma_f32_16x16x32_bf16 v[42:45], v[172:175], v[196:199], v[42:45]
	v_mfma_f32_16x16x32_bf16 v[34:37], v[180:183], v[196:199], v[34:37]
	v_mfma_f32_16x16x32_bf16 v[26:29], v[172:175], v[204:207], v[26:29]
	v_mfma_f32_16x16x32_bf16 v[18:21], v[180:183], v[204:207], v[18:21]
	v_mfma_f32_16x16x32_bf16 v[10:13], v[172:175], v[212:215], v[10:13]
	v_mfma_f32_16x16x32_bf16 v[2:5], v[180:183], v[212:215], v[2:5]
	v_mfma_f32_16x16x32_bf16 v[58:61], v[176:179], v[192:195], v[58:61]
	v_mfma_f32_16x16x32_bf16 v[50:53], v[184:187], v[192:195], v[50:53]
	v_mfma_f32_16x16x32_bf16 v[42:45], v[176:179], v[200:203], v[42:45]
	v_mfma_f32_16x16x32_bf16 v[34:37], v[184:187], v[200:203], v[34:37]
	v_mfma_f32_16x16x32_bf16 v[26:29], v[176:179], v[208:211], v[26:29]
	v_mfma_f32_16x16x32_bf16 v[18:21], v[184:187], v[208:211], v[18:21]
	v_mfma_f32_16x16x32_bf16 v[10:13], v[176:179], v[216:219], v[10:13]
	s_setprio 0
	s_barrier
	v_mfma_f32_16x16x32_bf16 v[2:5], v[184:187], v[216:219], v[2:5]
	s_add_i32 s66, s66, 2
	s_add_u32 s46, s46, 0x100
	s_addc_u32 s47, s47, 0
	s_add_u32 s64, s64, 0x100
	s_addc_u32 s65, s65, 0
	s_cmp_gt_u32 s66, 29
	s_cbranch_scc0 .LBB0_1218
	s_and_b64 vcc, exec, s[18:19]
	s_cbranch_vccz .LBB0_1221
	s_barrier

; #define PG8_STAGE(bufoff, gbase, voff) do { _Pragma("unroll") for (int _i = 0; _i < 2; ++_i) \
;         __builtin_amdgcn_global_load_lds((const unsigned*)((const char*)(gbase) + (voff)[_i]), (PG8_LAS unsigned*)(lds + (bufoff) + ldsw + _i * 8192), 16, 0, 0); } while (0)
; #define PG8_LDA(dst, b, h) do { _Pragma("unroll") for (int m = 0; m < 4; ++m) _Pragma("unroll") for (int k = 0; k < 2; ++k) dst[m][k] = *(const PG8_LAS bf16x8*)(lds + PG8_SA(b, h) + aoff + m * 2048 + k * 1024); } while (0)
; #define PG8_LDB(dst, b, h) do { _Pragma("unroll") for (int n = 0; n < 2; ++n) _Pragma("unroll") for (int k = 0; k < 2; ++k) dst[n][k] = *(const PG8_LAS bf16x8*)(lds + PG8_SB(b, h) + boff + n * 2048 + k * 1024); } while (0)
; #define PG8_MMA(ai, bj, At, Bt) do { __builtin_amdgcn_s_setprio(3); _Pragma("unroll") for (int m = 0; m < 4; ++m) _Pragma("unroll") for (int n = 0; n < 2; ++n) _Pragma("unroll") for (int k = 0; k < 2; ++k) \
;         acc[ai][bj][m][n] = __builtin_amdgcn_mfma_f32_16x16x32_bf16(Bt[n][k], At[m][k], acc[ai][bj][m][n], 0, 0, 0); __builtin_amdgcn_s_setprio(0); } while (0)
; #define PG8_WAIT_V(n) asm volatile("s_waitcnt vmcnt(" #n ")" ::: "memory")
; #define PG8_BAR __builtin_amdgcn_s_barrier()
; template <class Epi, class Sched, bool ALIGN_EPI = false, bool SP2 = false>
; __device__ __forceinline__ void gemm_phase(PG8_LAS unsigned char* lds, const Gemm g, const Sched& S, const Epi& E) {
;     ...
;         for (int t = 0; t < nt; t += 2) {
;             const bool last = (t == nt - 2);
;             const char* a1 = cA + (size_t)(t + 1) * kstep;
;             const char* a2 = last ? nA : cA + (size_t)(t + 2) * kstep; const char* b2 = last ? nB : cB + (size_t)(t + 2) * kstep;
;             const char* a3 = a2 + kstep; const char* b3 = b2 + kstep;
;             if (last && has_next) S.a_ready(nxt);
;             if constexpr (SP2) {
;             PG8_LDB(B0, 0, 0); PG8_LDB(B1, 0, 1); PG8_SCHED; PG8_LDA(At, 0, 0); PG8_STAGE(PG8_SA(1, 1), a1 + hstep, voffA);
;             PG8_WAIT_V(8); PG8_WAIT_L(0); PG8_BAR; PG8_MMA(0, 0, At, B0); PG8_MMA(0, 1, At, B1); PG8_BAR; PG8_SCHED;
;             PG8_LDA(At, 0, 1); PG8_STAGE(PG8_SB(0, 0), b2, voffB); PG8_STAGE(PG8_SB(0, 1), b2 + hstep, voffB); PG8_STAGE(PG8_SA(0, 0), a2, voffA);
;             PG8_WAIT_V(8); PG8_WAIT_L(0); PG8_BAR; PG8_MMA(1, 0, At, B0); PG8_MMA(1, 1, At, B1); PG8_BAR; PG8_SCHED;
.LBB0_1309:
	ds_read_b128 v[148:151], v157
	ds_read_b128 v[152:155], v157 offset:1024
	ds_read_b128 v[160:163], v157 offset:2048
	ds_read_b128 v[168:171], v157 offset:3072
	ds_read_b128 v[172:175], v158
	ds_read_b128 v[176:179], v158 offset:1024
	ds_read_b128 v[180:183], v158 offset:2048
	ds_read_b128 v[184:187], v158 offset:3072
	s_add_i32 s79, s50, 2
	s_add_u32 s10, s8, 0xffea8080
	s_addc_u32 s11, s9, -1
	s_cmp_eq_u32 s76, s50
	s_cselect_b32 s50, s48, s77
	s_cselect_b32 s53, s47, s11
	s_cselect_b32 s52, s46, s10
	s_cselect_b32 s51, s49, s78
	v_lshl_add_u64 v[164:165], s[8:9], 0, v[138:139]
	s_add_i32 m0, s43, 0xc000
	ds_read_b128 v[188:191], v159
	ds_read_b128 v[192:195], v159 offset:1024
	ds_read_b128 v[196:199], v159 offset:2048
	ds_read_b128 v[200:203], v159 offset:3072
	ds_read_b128 v[204:207], v159 offset:4096
	ds_read_b128 v[208:211], v159 offset:5120
	ds_read_b128 v[212:215], v159 offset:6144
	ds_read_b128 v[216:219], v159 offset:7168
	global_load_lds_dwordx4 v[164:165], off
	v_lshl_add_u64 v[164:165], s[8:9], 0, v[142:143]
	s_add_i32 m0, s43, 0xe000
	s_nop 0
	global_load_lds_dwordx4 v[164:165], off
	s_waitcnt vmcnt(8)
	s_waitcnt lgkmcnt(0)
	s_barrier
	s_setprio 3
	s_waitcnt lgkmcnt(0)
	v_mfma_f32_16x16x32_bf16 v[126:129], v[148:151], v[188:191], v[126:129]
	v_mfma_f32_16x16x32_bf16 v[122:125], v[160:163], v[188:191], v[122:125]
	v_mfma_f32_16x16x32_bf16 v[114:117], v[148:151], v[196:199], v[114:117]
	v_mfma_f32_16x16x32_bf16 v[106:109], v[160:163], v[196:199], v[106:109]
	v_mfma_f32_16x16x32_bf16 v[98:101], v[148:151], v[204:207], v[98:101]
	v_mfma_f32_16x16x32_bf16 v[90:93], v[160:163], v[204:207], v[90:93]
	v_mfma_f32_16x16x32_bf16 v[82:85], v[148:151], v[212:215], v[82:85]
	v_mfma_f32_16x16x32_bf16 v[74:77], v[160:163], v[212:215], v[74:77]
	v_mfma_f32_16x16x32_bf16 v[126:129], v[152:155], v[192:195], v[126:129]
	v_mfma_f32_16x16x32_bf16 v[122:125], v[168:171], v[192:195], v[122:125]
	v_mfma_f32_16x16x32_bf16 v[114:117], v[152:155], v[200:203], v[114:117]
	v_mfma_f32_16x16x32_bf16 v[106:109], v[168:171], v[200:203], v[106:109]
	v_mfma_f32_16x16x32_bf16 v[98:101], v[152:155], v[208:211], v[98:101]
	v_mfma_f32_16x16x32_bf16 v[90:93], v[168:171], v[208:211], v[90:93]
	v_mfma_f32_16x16x32_bf16 v[82:85], v[152:155], v[216:219], v[82:85]
	v_mfma_f32_16x16x32_bf16 v[74:77], v[168:171], v[216:219], v[74:77]
	s_setprio 0
	s_setprio 3
	v_mfma_f32_16x16x32_bf16 v[118:121], v[172:175], v[188:191], v[118:121]
	v_mfma_f32_16x16x32_bf16 v[110:113], v[180:183], v[188:191], v[110:113]
	v_mfma_f32_16x16x32_bf16 v[102:105], v[172:175], v[196:199], v[102:105]
	v_mfma_f32_16x16x32_bf16 v[94:97], v[180:183], v[196:199], v[94:97]
	v_mfma_f32_16x16x32_bf16 v[86:89], v[172:175], v[204:207], v[86:89]
	v_mfma_f32_16x16x32_bf16 v[78:81], v[180:183], v[204:207], v[78:81]
	v_mfma_f32_16x16x32_bf16 v[70:73], v[172:175], v[212:215], v[70:73]
	v_mfma_f32_16x16x32_bf16 v[66:69], v[180:183], v[212:215], v[66:69]
	v_mfma_f32_16x16x32_bf16 v[118:121], v[176:179], v[192:195], v[118:121]
	v_mfma_f32_16x16x32_bf16 v[110:113], v[184:187], v[192:195], v[110:113]
	v_mfma_f32_16x16x32_bf16 v[102:105], v[176:179], v[200:203], v[102:105]
	v_mfma_f32_16x16x32_bf16 v[94:97], v[184:187], v[200:203], v[94:97]
	v_mfma_f32_16x16x32_bf16 v[86:89], v[176:179], v[208:211], v[86:89]
	v_mfma_f32_16x16x32_bf16 v[78:81], v[184:187], v[208:211], v[78:81]
	v_mfma_f32_16x16x32_bf16 v[70:73], v[176:179], v[216:219], v[70:73]
	s_setprio 0
	s_barrier
	v_mfma_f32_16x16x32_bf16 v[66:69], v[184:187], v[216:219], v[66:69]
	s_add_i32 s10, s66, s42
	v_lshl_add_u64 v[164:165], s[50:51], 0, v[132:133]
	s_mov_b32 m0, s10
	ds_read_b128 v[188:191], v159 offset:16384
	ds_read_b128 v[192:195], v159 offset:17408
	ds_read_b128 v[196:199], v159 offset:18432
	ds_read_b128 v[200:203], v159 offset:19456
	ds_read_b128 v[204:207], v159 offset:20480
	ds_read_b128 v[208:211], v159 offset:21504
	ds_read_b128 v[212:215], v159 offset:22528
	ds_read_b128 v[216:219], v159 offset:23552
	global_load_lds_dwordx4 v[164:165], off
	s_add_i32 m0, s10, 0x2000
	s_add_u32 s82, s50, 0x158000
	v_lshl_add_u64 v[220:221], s[50:51], 0, v[136:137]
	s_addc_u32 s83, s51, 0
	s_add_i32 s10, s67, s42
	global_load_lds_dwordx4 v[220:221], off
	v_lshl_add_u64 v[222:223], s[82:83], 0, v[132:133]
	s_mov_b32 m0, s10
	v_lshl_add_u64 v[224:225], s[52:53], 0, v[134:135]
	global_load_lds_dwordx4 v[222:223], off
	v_lshl_add_u64 v[222:223], s[82:83], 0, v[136:137]
	s_add_i32 m0, s10, 0x2000
	s_nop 0
	global_load_lds_dwordx4 v[222:223], off
	v_lshl_add_u64 v[222:223], s[52:53], 0, v[130:131]
	s_mov_b32 m0, s43
	s_nop 0
	global_load_lds_dwordx4 v[222:223], off
	s_mov_b32 m0, s54
	s_nop 0
	global_load_lds_dwordx4 v[224:225], off
	s_waitcnt vmcnt(8)
	s_waitcnt lgkmcnt(0)
	s_barrier
; #define PG8_STAGE(bufoff, gbase, voff) do { _Pragma("unroll") for (int _i = 0; _i < 2; ++_i) \
;         __builtin_amdgcn_global_load_lds((const unsigned*)((const char*)(gbase) + (voff)[_i]), (PG8_LAS unsigned*)(lds + (bufoff) + ldsw + _i * 8192), 16, 0, 0); } while (0)
; #define PG8_LDA(dst, b, h) do { _Pragma("unroll") for (int m = 0; m < 4; ++m) _Pragma("unroll") for (int k = 0; k < 2; ++k) dst[m][k] = *(const PG8_LAS bf16x8*)(lds + PG8_SA(b, h) + aoff + m * 2048 + k * 1024); } while (0)
; #define PG8_LDB(dst, b, h) do { _Pragma("unroll") for (int n = 0; n < 2; ++n) _Pragma("unroll") for (int k = 0; k < 2; ++k) dst[n][k] = *(const PG8_LAS bf16x8*)(lds + PG8_SB(b, h) + boff + n * 2048 + k * 1024); } while (0)
; #define PG8_MMA(ai, bj, At, Bt) do { __builtin_amdgcn_s_setprio(3); _Pragma("unroll") for (int m = 0; m < 4; ++m) _Pragma("unroll") for (int n = 0; n < 2; ++n) _Pragma("unroll") for (int k = 0; k < 2; ++k) \
;         acc[ai][bj][m][n] = __builtin_amdgcn_mfma_f32_16x16x32_bf16(Bt[n][k], At[m][k], acc[ai][bj][m][n], 0, 0, 0); __builtin_amdgcn_s_setprio(0); } while (0)
; #define PG8_WAIT_V(n) asm volatile("s_waitcnt vmcnt(" #n ")" ::: "memory")
; #define PG8_WAIT_L(n) asm volatile("s_waitcnt lgkmcnt(" #n ")" ::: "memory")
; #define PG8_BAR __builtin_amdgcn_s_barrier()
; #define PG8_SCHED __builtin_amdgcn_sched_barrier(0)
; template <class Epi, class Sched, bool ALIGN_EPI = false, bool SP2 = false>
; __device__ __forceinline__ void gemm_phase(PG8_LAS unsigned char* lds, const Gemm g, const Sched& S, const Epi& E) {
;     ...
;             PG8_WAIT_V(8); PG8_WAIT_L(0); PG8_BAR; PG8_MMA(1, 0, At, B0); PG8_MMA(1, 1, At, B1); PG8_BAR; PG8_SCHED;
;             PG8_LDB(B0, 1, 0); PG8_LDB(B1, 1, 1); PG8_SCHED; PG8_LDA(At, 1, 0); PG8_STAGE(PG8_SA(0, 1), a2 + hstep, voffA);
;             PG8_WAIT_V(8); PG8_WAIT_L(0); PG8_BAR; PG8_MMA(0, 0, At, B0); PG8_MMA(0, 1, At, B1); PG8_BAR; PG8_SCHED;
	s_setprio 3
	s_waitcnt lgkmcnt(0)
	v_mfma_f32_16x16x32_bf16 v[62:65], v[148:151], v[188:191], v[62:65]
	v_mfma_f32_16x16x32_bf16 v[58:61], v[160:163], v[188:191], v[58:61]
	v_mfma_f32_16x16x32_bf16 v[50:53], v[148:151], v[196:199], v[50:53]
	v_mfma_f32_16x16x32_bf16 v[42:45], v[160:163], v[196:199], v[42:45]
	v_mfma_f32_16x16x32_bf16 v[34:37], v[148:151], v[204:207], v[34:37]
	v_mfma_f32_16x16x32_bf16 v[26:29], v[160:163], v[204:207], v[26:29]
	v_mfma_f32_16x16x32_bf16 v[18:21], v[148:151], v[212:215], v[18:21]
	v_mfma_f32_16x16x32_bf16 v[10:13], v[160:163], v[212:215], v[10:13]
	v_mfma_f32_16x16x32_bf16 v[62:65], v[152:155], v[192:195], v[62:65]
	v_mfma_f32_16x16x32_bf16 v[58:61], v[168:171], v[192:195], v[58:61]
	v_mfma_f32_16x16x32_bf16 v[50:53], v[152:155], v[200:203], v[50:53]
	v_mfma_f32_16x16x32_bf16 v[42:45], v[168:171], v[200:203], v[42:45]
	v_mfma_f32_16x16x32_bf16 v[34:37], v[152:155], v[208:211], v[34:37]
	v_mfma_f32_16x16x32_bf16 v[26:29], v[168:171], v[208:211], v[26:29]
	v_mfma_f32_16x16x32_bf16 v[18:21], v[152:155], v[216:219], v[18:21]
	v_mfma_f32_16x16x32_bf16 v[10:13], v[168:171], v[216:219], v[10:13]
	s_setprio 0
	s_setprio 3
	v_mfma_f32_16x16x32_bf16 v[54:57], v[172:175], v[188:191], v[54:57]
	v_mfma_f32_16x16x32_bf16 v[46:49], v[180:183], v[188:191], v[46:49]
	v_mfma_f32_16x16x32_bf16 v[38:41], v[172:175], v[196:199], v[38:41]
	v_mfma_f32_16x16x32_bf16 v[30:33], v[180:183], v[196:199], v[30:33]
	v_mfma_f32_16x16x32_bf16 v[22:25], v[172:175], v[204:207], v[22:25]
	v_mfma_f32_16x16x32_bf16 v[14:17], v[180:183], v[204:207], v[14:17]
	v_mfma_f32_16x16x32_bf16 v[6:9], v[172:175], v[212:215], v[6:9]
	v_mfma_f32_16x16x32_bf16 v[2:5], v[180:183], v[212:215], v[2:5]
	v_mfma_f32_16x16x32_bf16 v[54:57], v[176:179], v[192:195], v[54:57]
	v_mfma_f32_16x16x32_bf16 v[46:49], v[184:187], v[192:195], v[46:49]
	v_mfma_f32_16x16x32_bf16 v[38:41], v[176:179], v[200:203], v[38:41]
	v_mfma_f32_16x16x32_bf16 v[30:33], v[184:187], v[200:203], v[30:33]
	v_mfma_f32_16x16x32_bf16 v[22:25], v[176:179], v[208:211], v[22:25]
	v_mfma_f32_16x16x32_bf16 v[14:17], v[184:187], v[208:211], v[14:17]
	v_mfma_f32_16x16x32_bf16 v[6:9], v[176:179], v[216:219], v[6:9]
	s_setprio 0
	s_barrier
	v_mfma_f32_16x16x32_bf16 v[2:5], v[184:187], v[216:219], v[2:5]
	s_add_i32 s10, 0, 0x18000
	v_add_u32_e32 v167, s10, v141
	s_add_i32 s11, 0, 0x1c000
	ds_read_b128 v[148:151], v167
	ds_read_b128 v[152:155], v167 offset:1024
	ds_read_b128 v[160:163], v167 offset:2048
	ds_read_b128 v[168:171], v167 offset:3072
	v_add_u32_e32 v167, s11, v141
	ds_read_b128 v[172:175], v167
	ds_read_b128 v[176:179], v167 offset:1024
	ds_read_b128 v[180:183], v167 offset:2048
	ds_read_b128 v[184:187], v167 offset:3072
	s_add_u32 s52, s52, 0x158000
	s_addc_u32 s53, s53, 0
	s_mov_b32 m0, s55
	v_lshl_add_u64 v[226:227], s[52:53], 0, v[130:131]
	ds_read_b128 v[188:191], v159 offset:32768
	ds_read_b128 v[192:195], v159 offset:33792
	ds_read_b128 v[196:199], v159 offset:34816
	ds_read_b128 v[200:203], v159 offset:35840
	ds_read_b128 v[204:207], v159 offset:36864
	ds_read_b128 v[208:211], v159 offset:37888
	ds_read_b128 v[212:215], v159 offset:38912
	ds_read_b128 v[216:219], v159 offset:39936
	global_load_lds_dwordx4 v[226:227], off
	v_lshl_add_u64 v[226:227], s[52:53], 0, v[134:135]
	s_mov_b32 m0, s56
	s_nop 0
	global_load_lds_dwordx4 v[226:227], off
	s_waitcnt vmcnt(8)
	s_waitcnt lgkmcnt(0)
	s_barrier
	s_setprio 3
	s_waitcnt lgkmcnt(0)
	v_mfma_f32_16x16x32_bf16 v[126:129], v[148:151], v[188:191], v[126:129]
	v_mfma_f32_16x16x32_bf16 v[122:125], v[160:163], v[188:191], v[122:125]
	v_mfma_f32_16x16x32_bf16 v[114:117], v[148:151], v[196:199], v[114:117]
	v_mfma_f32_16x16x32_bf16 v[106:109], v[160:163], v[196:199], v[106:109]
	v_mfma_f32_16x16x32_bf16 v[98:101], v[148:151], v[204:207], v[98:101]
	v_mfma_f32_16x16x32_bf16 v[90:93], v[160:163], v[204:207], v[90:93]
	v_mfma_f32_16x16x32_bf16 v[82:85], v[148:151], v[212:215], v[82:85]
	v_mfma_f32_16x16x32_bf16 v[74:77], v[160:163], v[212:215], v[74:77]
	v_mfma_f32_16x16x32_bf16 v[126:129], v[152:155], v[192:195], v[126:129]
	v_mfma_f32_16x16x32_bf16 v[122:125], v[168:171], v[192:195], v[122:125]
	v_mfma_f32_16x16x32_bf16 v[114:117], v[152:155], v[200:203], v[114:117]
	v_mfma_f32_16x16x32_bf16 v[106:109], v[168:171], v[200:203], v[106:109]
	v_mfma_f32_16x16x32_bf16 v[98:101], v[152:155], v[208:211], v[98:101]
	v_mfma_f32_16x16x32_bf16 v[90:93], v[168:171], v[208:211], v[90:93]
	v_mfma_f32_16x16x32_bf16 v[82:85], v[152:155], v[216:219], v[82:85]
	v_mfma_f32_16x16x32_bf16 v[74:77], v[168:171], v[216:219], v[74:77]
	s_setprio 0
	s_setprio 3
	v_mfma_f32_16x16x32_bf16 v[118:121], v[172:175], v[188:191], v[118:121]
	v_mfma_f32_16x16x32_bf16 v[110:113], v[180:183], v[188:191], v[110:113]
	v_mfma_f32_16x16x32_bf16 v[102:105], v[172:175], v[196:199], v[102:105]
	v_mfma_f32_16x16x32_bf16 v[94:97], v[180:183], v[196:199], v[94:97]
	v_mfma_f32_16x16x32_bf16 v[86:89], v[172:175], v[204:207], v[86:89]
	v_mfma_f32_16x16x32_bf16 v[78:81], v[180:183], v[204:207], v[78:81]
	v_mfma_f32_16x16x32_bf16 v[70:73], v[172:175], v[212:215], v[70:73]
	v_mfma_f32_16x16x32_bf16 v[66:69], v[180:183], v[212:215], v[66:69]
	v_mfma_f32_16x16x32_bf16 v[118:121], v[176:179], v[192:195], v[118:121]
	v_mfma_f32_16x16x32_bf16 v[110:113], v[184:187], v[192:195], v[110:113]
	v_mfma_f32_16x16x32_bf16 v[102:105], v[176:179], v[200:203], v[102:105]
	v_mfma_f32_16x16x32_bf16 v[94:97], v[184:187], v[200:203], v[94:97]
	v_mfma_f32_16x16x32_bf16 v[86:89], v[176:179], v[208:211], v[86:89]
	v_mfma_f32_16x16x32_bf16 v[78:81], v[184:187], v[208:211], v[78:81]
	v_mfma_f32_16x16x32_bf16 v[70:73], v[176:179], v[216:219], v[70:73]
	s_setprio 0
	s_barrier
; #define PG8_STAGE(bufoff, gbase, voff) do { _Pragma("unroll") for (int _i = 0; _i < 2; ++_i) \
;         __builtin_amdgcn_global_load_lds((const unsigned*)((const char*)(gbase) + (voff)[_i]), (PG8_LAS unsigned*)(lds + (bufoff) + ldsw + _i * 8192), 16, 0, 0); } while (0)
; #define PG8_LDA(dst, b, h) do { _Pragma("unroll") for (int m = 0; m < 4; ++m) _Pragma("unroll") for (int k = 0; k < 2; ++k) dst[m][k] = *(const PG8_LAS bf16x8*)(lds + PG8_SA(b, h) + aoff + m * 2048 + k * 1024); } while (0)
; #define PG8_MMA(ai, bj, At, Bt) do { __builtin_amdgcn_s_setprio(3); _Pragma("unroll") for (int m = 0; m < 4; ++m) _Pragma("unroll") for (int n = 0; n < 2; ++n) _Pragma("unroll") for (int k = 0; k < 2; ++k) \
;         acc[ai][bj][m][n] = __builtin_amdgcn_mfma_f32_16x16x32_bf16(Bt[n][k], At[m][k], acc[ai][bj][m][n], 0, 0, 0); __builtin_amdgcn_s_setprio(0); } while (0)
; #define PG8_WAIT_V(n) asm volatile("s_waitcnt vmcnt(" #n ")" ::: "memory")
; #define PG8_WAIT_L(n) asm volatile("s_waitcnt lgkmcnt(" #n ")" ::: "memory")
; #define PG8_BAR __builtin_amdgcn_s_barrier()
; #define PG8_SCHED __builtin_amdgcn_sched_barrier(0)
; template <class Epi, class Sched, bool ALIGN_EPI = false, bool SP2 = false>
; __device__ __forceinline__ void gemm_phase(PG8_LAS unsigned char* lds, const Gemm g, const Sched& S, const Epi& E) {
;     ...
;             PG8_LDA(At, 1, 1); PG8_STAGE(PG8_SB(1, 0), b3, voffB); PG8_STAGE(PG8_SB(1, 1), b3 + hstep, voffB); PG8_STAGE(PG8_SA(1, 0), a3, voffA);
;             PG8_WAIT_V(8); PG8_WAIT_L(0); PG8_BAR; PG8_MMA(1, 0, At, B0); PG8_MMA(1, 1, At, B1); PG8_BAR; PG8_SCHED;
;     ...
;         }
;         if constexpr (ALIGN_EPI) { if (wr == 0) PG8_BAR; }
	v_mfma_f32_16x16x32_bf16 v[66:69], v[184:187], v[216:219], v[66:69]
	s_add_i32 s10, s10, s42
	v_lshl_add_u64 v[164:165], v[164:165], 0, s[18:19]
	s_mov_b32 m0, s10
	ds_read_b128 v[188:191], v159 offset:49152
	ds_read_b128 v[192:195], v159 offset:50176
	ds_read_b128 v[196:199], v159 offset:51200
	ds_read_b128 v[200:203], v159 offset:52224
	ds_read_b128 v[204:207], v159 offset:53248
	ds_read_b128 v[208:211], v159 offset:54272
	ds_read_b128 v[212:215], v159 offset:55296
	ds_read_b128 v[216:219], v159 offset:56320
	global_load_lds_dwordx4 v[164:165], off
	s_add_i32 m0, s10, 0x2000
	s_add_u32 s50, s50, 0x158080
	v_lshl_add_u64 v[164:165], v[220:221], 0, s[18:19]
	s_addc_u32 s51, s51, 0
	s_add_i32 s10, s11, s42
	global_load_lds_dwordx4 v[164:165], off
	v_lshl_add_u64 v[164:165], s[50:51], 0, v[132:133]
	s_mov_b32 m0, s10
	s_nop 0
	global_load_lds_dwordx4 v[164:165], off
	v_lshl_add_u64 v[164:165], s[50:51], 0, v[136:137]
	s_add_i32 m0, s10, 0x2000
	s_nop 0
	global_load_lds_dwordx4 v[164:165], off
	v_lshl_add_u64 v[164:165], v[222:223], 0, s[18:19]
	s_mov_b32 m0, s61
	s_nop 0
	global_load_lds_dwordx4 v[164:165], off
	v_lshl_add_u64 v[164:165], v[224:225], 0, s[18:19]
	s_mov_b32 m0, s62
	s_nop 0
	global_load_lds_dwordx4 v[164:165], off
	s_waitcnt vmcnt(8)
	s_waitcnt lgkmcnt(0)
	s_barrier
	s_setprio 3
	s_waitcnt lgkmcnt(0)
	v_mfma_f32_16x16x32_bf16 v[62:65], v[148:151], v[188:191], v[62:65]
	v_mfma_f32_16x16x32_bf16 v[58:61], v[160:163], v[188:191], v[58:61]
	v_mfma_f32_16x16x32_bf16 v[50:53], v[148:151], v[196:199], v[50:53]
	v_mfma_f32_16x16x32_bf16 v[42:45], v[160:163], v[196:199], v[42:45]
	v_mfma_f32_16x16x32_bf16 v[34:37], v[148:151], v[204:207], v[34:37]
	v_mfma_f32_16x16x32_bf16 v[26:29], v[160:163], v[204:207], v[26:29]
	v_mfma_f32_16x16x32_bf16 v[18:21], v[148:151], v[212:215], v[18:21]
	v_mfma_f32_16x16x32_bf16 v[10:13], v[160:163], v[212:215], v[10:13]
	v_mfma_f32_16x16x32_bf16 v[62:65], v[152:155], v[192:195], v[62:65]
	v_mfma_f32_16x16x32_bf16 v[58:61], v[168:171], v[192:195], v[58:61]
	v_mfma_f32_16x16x32_bf16 v[50:53], v[152:155], v[200:203], v[50:53]
	v_mfma_f32_16x16x32_bf16 v[42:45], v[168:171], v[200:203], v[42:45]
	v_mfma_f32_16x16x32_bf16 v[34:37], v[152:155], v[208:211], v[34:37]
	v_mfma_f32_16x16x32_bf16 v[26:29], v[168:171], v[208:211], v[26:29]
	v_mfma_f32_16x16x32_bf16 v[18:21], v[152:155], v[216:219], v[18:21]
	v_mfma_f32_16x16x32_bf16 v[10:13], v[168:171], v[216:219], v[10:13]
	s_setprio 0
	s_setprio 3
	v_mfma_f32_16x16x32_bf16 v[54:57], v[172:175], v[188:191], v[54:57]
	v_mfma_f32_16x16x32_bf16 v[46:49], v[180:183], v[188:191], v[46:49]
	v_mfma_f32_16x16x32_bf16 v[38:41], v[172:175], v[196:199], v[38:41]
	v_mfma_f32_16x16x32_bf16 v[30:33], v[180:183], v[196:199], v[30:33]
	v_mfma_f32_16x16x32_bf16 v[22:25], v[172:175], v[204:207], v[22:25]
	v_mfma_f32_16x16x32_bf16 v[14:17], v[180:183], v[204:207], v[14:17]
	v_mfma_f32_16x16x32_bf16 v[6:9], v[172:175], v[212:215], v[6:9]
	v_mfma_f32_16x16x32_bf16 v[2:5], v[180:183], v[212:215], v[2:5]
	v_mfma_f32_16x16x32_bf16 v[54:57], v[176:179], v[192:195], v[54:57]
	v_mfma_f32_16x16x32_bf16 v[46:49], v[184:187], v[192:195], v[46:49]
	v_mfma_f32_16x16x32_bf16 v[38:41], v[176:179], v[200:203], v[38:41]
	v_mfma_f32_16x16x32_bf16 v[30:33], v[184:187], v[200:203], v[30:33]
	v_mfma_f32_16x16x32_bf16 v[22:25], v[176:179], v[208:211], v[22:25]
	v_mfma_f32_16x16x32_bf16 v[14:17], v[184:187], v[208:211], v[14:17]
	v_mfma_f32_16x16x32_bf16 v[6:9], v[176:179], v[216:219], v[6:9]
	s_setprio 0
	s_barrier
	v_mfma_f32_16x16x32_bf16 v[2:5], v[184:187], v[216:219], v[2:5]
	s_add_u32 s8, s8, 0x100
	s_addc_u32 s9, s9, 0
	s_add_u32 s77, s77, 0x100
	s_addc_u32 s78, s78, 0
	s_cmp_ge_u32 s79, s75
	s_mov_b32 s50, s79
	s_cbranch_scc0 .LBB0_1309
	s_and_b64 vcc, exec, s[24:25]
	s_cbranch_vccz .LBB0_1312
	s_barrier
